# baseline (speedup 1.0000x reference)
.Lh2_loop:
	ds_read_b128 v[140:143], v138
	ds_read_b128 v[144:147], v138 offset:1024
	ds_read_b128 v[148:151], v138 offset:2048
	ds_read_b128 v[152:155], v138 offset:3072
	s_add_u32 s8, s6, s65
	s_addc_u32 s9, s7, s66
	ds_read_b128 v[156:159], v134
	ds_read_b128 v[160:163], v134 offset:1024
	ds_read_b128 v[164:167], v133
	ds_read_b128 v[168:171], v133 offset:1024
	ds_read_b128 v[172:175], v132
	ds_read_b128 v[176:179], v132 offset:1024
	ds_read_b128 v[180:183], v131
	ds_read_b128 v[184:187], v131 offset:1024
	s_mov_b32 m0, s76
	s_mov_b32 m0, s75
	s_nop 0
	s_waitcnt lgkmcnt(8)
	s_barrier
	s_waitcnt lgkmcnt(0)
	v_mfma_f32_16x16x32_bf16 v[124:127], v[140:143], v[156:159], v[124:127]
	v_mfma_f32_16x16x32_bf16 v[120:123], v[148:151], v[156:159], v[120:123]
	v_mfma_f32_16x16x32_bf16 v[116:119], v[140:143], v[164:167], v[116:119]
	v_mfma_f32_16x16x32_bf16 v[112:115], v[148:151], v[164:167], v[112:115]
	v_mfma_f32_16x16x32_bf16 v[108:111], v[140:143], v[172:175], v[108:111]
	v_mfma_f32_16x16x32_bf16 v[104:107], v[148:151], v[172:175], v[104:107]
	v_mfma_f32_16x16x32_bf16 v[100:103], v[140:143], v[180:183], v[100:103]
	v_mfma_f32_16x16x32_bf16 v[96:99], v[148:151], v[180:183], v[96:99]
	v_mfma_f32_16x16x32_bf16 v[124:127], v[144:147], v[160:163], v[124:127]
	v_mfma_f32_16x16x32_bf16 v[120:123], v[152:155], v[160:163], v[120:123]
	v_mfma_f32_16x16x32_bf16 v[116:119], v[144:147], v[168:171], v[116:119]
	v_mfma_f32_16x16x32_bf16 v[112:115], v[152:155], v[168:171], v[112:115]
	v_mfma_f32_16x16x32_bf16 v[108:111], v[144:147], v[176:179], v[108:111]
	v_mfma_f32_16x16x32_bf16 v[104:107], v[152:155], v[176:179], v[104:107]
	v_mfma_f32_16x16x32_bf16 v[100:103], v[144:147], v[184:187], v[100:103]
	v_mfma_f32_16x16x32_bf16 v[96:99], v[152:155], v[184:187], v[96:99]
	s_barrier
	s_add_u32 s10, s6, s36
	s_addc_u32 s11, s7, s37
	ds_read_b128 v[188:191], v137
	ds_read_b128 v[192:195], v137 offset:1024
	ds_read_b128 v[202:205], v137 offset:2048
	ds_read_b128 v[206:209], v137 offset:3072
	s_mov_b32 m0, s63
	s_add_u32 s98, s10, s46
	s_addc_u32 s99, s11, s47
	global_load_lds_dwordx4 v129, s[98:99]
	s_mov_b32 m0, s64
	s_nop 0
	global_load_lds_dwordx4 v130, s[98:99]
	s_barrier
	s_waitcnt lgkmcnt(0)
	v_mfma_f32_16x16x32_bf16 v[92:95], v[188:191], v[156:159], v[92:95]
	v_mfma_f32_16x16x32_bf16 v[88:91], v[202:205], v[156:159], v[88:91]
	v_mfma_f32_16x16x32_bf16 v[84:87], v[188:191], v[164:167], v[84:87]
	v_mfma_f32_16x16x32_bf16 v[80:83], v[202:205], v[164:167], v[80:83]
	v_mfma_f32_16x16x32_bf16 v[76:79], v[188:191], v[172:175], v[76:79]
	v_mfma_f32_16x16x32_bf16 v[72:75], v[202:205], v[172:175], v[72:75]
	v_mfma_f32_16x16x32_bf16 v[68:71], v[188:191], v[180:183], v[68:71]
	v_mfma_f32_16x16x32_bf16 v[64:67], v[202:205], v[180:183], v[64:67]
	v_mfma_f32_16x16x32_bf16 v[92:95], v[192:195], v[160:163], v[92:95]
	v_mfma_f32_16x16x32_bf16 v[88:91], v[206:209], v[160:163], v[88:91]
	v_mfma_f32_16x16x32_bf16 v[84:87], v[192:195], v[168:171], v[84:87]
	v_mfma_f32_16x16x32_bf16 v[80:83], v[206:209], v[168:171], v[80:83]
	v_mfma_f32_16x16x32_bf16 v[76:79], v[192:195], v[176:179], v[76:79]
	v_mfma_f32_16x16x32_bf16 v[72:75], v[206:209], v[176:179], v[72:75]
	v_mfma_f32_16x16x32_bf16 v[68:71], v[192:195], v[184:187], v[68:71]
	v_mfma_f32_16x16x32_bf16 v[64:67], v[206:209], v[184:187], v[64:67]
	s_barrier
	s_mov_b32 m0, s62
	s_add_u32 s98, s8, s48
	s_addc_u32 s99, s9, s49
	global_load_lds_dwordx4 v129, s[98:99]
	s_mov_b32 m0, s67
	s_nop 0
	global_load_lds_dwordx4 v130, s[98:99]
	s_waitcnt vmcnt(4)
	s_barrier
	s_mov_b32 m0, s68
	s_add_u32 s98, s10, s50
	s_addc_u32 s99, s11, s51
	global_load_lds_dwordx4 v129, s[98:99]
	s_mov_b32 m0, s69
	s_nop 0
	global_load_lds_dwordx4 v130, s[98:99]
	s_barrier
	ds_read_b128 v[140:143], v136
	ds_read_b128 v[144:147], v136 offset:1024
	ds_read_b128 v[148:151], v136 offset:2048
	ds_read_b128 v[152:155], v136 offset:3072
	ds_read_b128 v[156:159], v134 offset:32768
	ds_read_b128 v[160:163], v134 offset:33792
	ds_read_b128 v[164:167], v133 offset:32768
	ds_read_b128 v[168:171], v133 offset:33792
	ds_read_b128 v[172:175], v132 offset:32768
	ds_read_b128 v[176:179], v132 offset:33792
	ds_read_b128 v[180:183], v131 offset:32768
	ds_read_b128 v[184:187], v131 offset:33792
	s_mov_b32 m0, s70
	s_mov_b32 m0, s71
	s_nop 0
	s_waitcnt lgkmcnt(8)
	s_barrier
	s_waitcnt lgkmcnt(0)
	v_mfma_f32_16x16x32_bf16 v[124:127], v[140:143], v[156:159], v[124:127]
	v_mfma_f32_16x16x32_bf16 v[120:123], v[148:151], v[156:159], v[120:123]
	v_mfma_f32_16x16x32_bf16 v[116:119], v[140:143], v[164:167], v[116:119]
	v_mfma_f32_16x16x32_bf16 v[112:115], v[148:151], v[164:167], v[112:115]
	v_mfma_f32_16x16x32_bf16 v[108:111], v[140:143], v[172:175], v[108:111]
	v_mfma_f32_16x16x32_bf16 v[104:107], v[148:151], v[172:175], v[104:107]
	v_mfma_f32_16x16x32_bf16 v[100:103], v[140:143], v[180:183], v[100:103]
	v_mfma_f32_16x16x32_bf16 v[96:99], v[148:151], v[180:183], v[96:99]
	v_mfma_f32_16x16x32_bf16 v[124:127], v[144:147], v[160:163], v[124:127]
	v_mfma_f32_16x16x32_bf16 v[120:123], v[152:155], v[160:163], v[120:123]
	v_mfma_f32_16x16x32_bf16 v[116:119], v[144:147], v[168:171], v[116:119]
	v_mfma_f32_16x16x32_bf16 v[112:115], v[152:155], v[168:171], v[112:115]
	v_mfma_f32_16x16x32_bf16 v[108:111], v[144:147], v[176:179], v[108:111]
	v_mfma_f32_16x16x32_bf16 v[104:107], v[152:155], v[176:179], v[104:107]
	v_mfma_f32_16x16x32_bf16 v[100:103], v[144:147], v[184:187], v[100:103]
	v_mfma_f32_16x16x32_bf16 v[96:99], v[152:155], v[184:187], v[96:99]
	s_barrier
	ds_read_b128 v[188:191], v135
	ds_read_b128 v[192:195], v135 offset:1024
	ds_read_b128 v[202:205], v135 offset:2048
	ds_read_b128 v[206:209], v135 offset:3072
	s_mov_b32 m0, s28
	s_add_u32 s98, s10, s92
	s_addc_u32 s99, s11, s93
	global_load_lds_dwordx4 v129, s[98:99]
	s_mov_b32 m0, s29
	s_nop 0
	global_load_lds_dwordx4 v130, s[98:99]
	s_barrier
	s_waitcnt lgkmcnt(0)
	v_mfma_f32_16x16x32_bf16 v[92:95], v[188:191], v[156:159], v[92:95]
	v_mfma_f32_16x16x32_bf16 v[88:91], v[202:205], v[156:159], v[88:91]
	v_mfma_f32_16x16x32_bf16 v[84:87], v[188:191], v[164:167], v[84:87]
	v_mfma_f32_16x16x32_bf16 v[80:83], v[202:205], v[164:167], v[80:83]
	v_mfma_f32_16x16x32_bf16 v[76:79], v[188:191], v[172:175], v[76:79]
	v_mfma_f32_16x16x32_bf16 v[72:75], v[202:205], v[172:175], v[72:75]
	v_mfma_f32_16x16x32_bf16 v[68:71], v[188:191], v[180:183], v[68:71]
	v_mfma_f32_16x16x32_bf16 v[64:67], v[202:205], v[180:183], v[64:67]
	v_mfma_f32_16x16x32_bf16 v[92:95], v[192:195], v[160:163], v[92:95]
	v_mfma_f32_16x16x32_bf16 v[88:91], v[206:209], v[160:163], v[88:91]
	v_mfma_f32_16x16x32_bf16 v[84:87], v[192:195], v[168:171], v[84:87]
	v_mfma_f32_16x16x32_bf16 v[80:83], v[206:209], v[168:171], v[80:83]
	v_mfma_f32_16x16x32_bf16 v[76:79], v[192:195], v[176:179], v[76:79]
	v_mfma_f32_16x16x32_bf16 v[72:75], v[206:209], v[176:179], v[72:75]
	v_mfma_f32_16x16x32_bf16 v[68:71], v[192:195], v[184:187], v[68:71]
	v_mfma_f32_16x16x32_bf16 v[64:67], v[206:209], v[184:187], v[64:67]
	v_mov_b32_e32 v210, v130
	s_barrier
	v_mov_b32_e32 v211, v197
	s_mov_b32 m0, s72
	s_add_u32 s98, s8, s96
	s_addc_u32 s99, s9, s97
	global_load_lds_dwordx4 v129, s[98:99]
	s_mov_b32 m0, s73
	s_nop 0
	global_load_lds_dwordx4 v130, s[98:99]
	s_waitcnt vmcnt(4)
	s_barrier
	v_mov_b32_e32 v196, v129
	s_mov_b32 m0, s33
	s_add_u32 s98, s10, vcc_lo
	s_addc_u32 s99, s11, vcc_hi
	global_load_lds_dwordx4 v129, s[98:99]
	s_mov_b32 m0, s74
	s_nop 0
	global_load_lds_dwordx4 v130, s[98:99]
	s_barrier
	s_add_i32 s38, s38, 2
	s_add_u32 s6, s6, 0x100
	s_addc_u32 s7, s7, 0
	s_cmpk_lt_u32 s38, 0x54
	s_cbranch_scc1 .Lh2_loop
	s_add_u32 s4, s4, 0x2b80
	s_addc_u32 s5, s5, 0
	s_mov_b32 m0, s76
	ds_read_b128 v[140:143], v138
	ds_read_b128 v[144:147], v138 offset:1024
	ds_read_b128 v[148:151], v138 offset:2048
	ds_read_b128 v[152:155], v138 offset:3072
	ds_read_b128 v[156:159], v134
	ds_read_b128 v[160:163], v134 offset:1024
	ds_read_b128 v[164:167], v133
	ds_read_b128 v[168:171], v133 offset:1024
	ds_read_b128 v[172:175], v132
	ds_read_b128 v[176:179], v132 offset:1024
	ds_read_b128 v[180:183], v131
	ds_read_b128 v[184:187], v131 offset:1024
	s_nop 0
	s_mov_b32 m0, s75
	s_nop 0
	s_barrier
	s_waitcnt lgkmcnt(0)
	v_mfma_f32_16x16x32_bf16 v[124:127], v[140:143], v[156:159], v[124:127]
	v_mfma_f32_16x16x32_bf16 v[120:123], v[148:151], v[156:159], v[120:123]
	v_mfma_f32_16x16x32_bf16 v[116:119], v[140:143], v[164:167], v[116:119]
	v_mfma_f32_16x16x32_bf16 v[112:115], v[148:151], v[164:167], v[112:115]
	v_mfma_f32_16x16x32_bf16 v[108:111], v[140:143], v[172:175], v[108:111]
	v_mfma_f32_16x16x32_bf16 v[100:103], v[140:143], v[180:183], v[100:103]
	v_mfma_f32_16x16x32_bf16 v[96:99], v[148:151], v[180:183], v[96:99]
	v_mfma_f32_16x16x32_bf16 v[124:127], v[144:147], v[160:163], v[124:127]
	v_mfma_f32_16x16x32_bf16 v[120:123], v[152:155], v[160:163], v[120:123]
	v_mfma_f32_16x16x32_bf16 v[116:119], v[144:147], v[168:171], v[116:119]
	v_mfma_f32_16x16x32_bf16 v[112:115], v[152:155], v[168:171], v[112:115]
	v_mfma_f32_16x16x32_bf16 v[108:111], v[144:147], v[176:179], v[108:111]
	v_mfma_f32_16x16x32_bf16 v[104:107], v[148:151], v[172:175], v[104:107]
	v_mfma_f32_16x16x32_bf16 v[100:103], v[144:147], v[184:187], v[100:103]
	v_mfma_f32_16x16x32_bf16 v[96:99], v[152:155], v[184:187], v[96:99]
	v_mfma_f32_16x16x32_bf16 v[188:191], v[152:155], v[176:179], v[104:107]
	s_barrier
	s_nop 2
	ds_read_b128 v[104:107], v137
	ds_read_b128 v[192:195], v137 offset:1024
	ds_read_b128 v[202:205], v137 offset:2048
	ds_read_b128 v[206:209], v137 offset:3072
	s_barrier
	s_waitcnt lgkmcnt(0)
	v_mfma_f32_16x16x32_bf16 v[92:95], v[104:107], v[156:159], v[92:95]
	v_mfma_f32_16x16x32_bf16 v[88:91], v[202:205], v[156:159], v[88:91]
	v_mfma_f32_16x16x32_bf16 v[80:83], v[202:205], v[164:167], v[80:83]
	v_mfma_f32_16x16x32_bf16 v[72:75], v[202:205], v[172:175], v[72:75]
	v_mfma_f32_16x16x32_bf16 v[64:67], v[202:205], v[180:183], v[64:67]
	v_mfma_f32_16x16x32_bf16 v[92:95], v[192:195], v[160:163], v[92:95]
	v_mfma_f32_16x16x32_bf16 v[88:91], v[206:209], v[160:163], v[88:91]
	v_mfma_f32_16x16x32_bf16 v[84:87], v[104:107], v[164:167], v[84:87]
	v_mfma_f32_16x16x32_bf16 v[80:83], v[206:209], v[168:171], v[80:83]
	v_mfma_f32_16x16x32_bf16 v[76:79], v[104:107], v[172:175], v[76:79]
	v_mfma_f32_16x16x32_bf16 v[72:75], v[206:209], v[176:179], v[72:75]
	v_mfma_f32_16x16x32_bf16 v[68:71], v[104:107], v[180:183], v[68:71]
	v_mfma_f32_16x16x32_bf16 v[64:67], v[206:209], v[184:187], v[64:67]
	v_mfma_f32_16x16x32_bf16 v[156:159], v[192:195], v[168:171], v[84:87]
	v_mfma_f32_16x16x32_bf16 v[160:163], v[192:195], v[176:179], v[76:79]
	v_mfma_f32_16x16x32_bf16 v[164:167], v[192:195], v[184:187], v[68:71]
	s_barrier
	s_nop 1
	s_waitcnt vmcnt(2)
	s_barrier
	s_waitcnt lgkmcnt(0)
	s_barrier
	ds_read_b128 v[16:19], v136
	ds_read_b128 v[180:183], v136 offset:1024
	ds_read_b128 v[184:187], v136 offset:2048
	ds_read_b128 v[192:195], v136 offset:3072
	ds_read_b128 v[0:3], v134 offset:32768
	ds_read_b128 v[4:7], v134 offset:33792
	ds_read_b128 v[8:11], v133 offset:32768
	ds_read_b128 v[12:15], v133 offset:33792
	ds_read_b128 v[44:47], v132 offset:32768
	ds_read_b128 v[202:205], v132 offset:33792
	ds_read_b128 v[206:209], v131 offset:32768
	ds_read_b128 v[222:225], v131 offset:33792
	s_waitcnt vmcnt(0)
	s_barrier
	s_waitcnt lgkmcnt(0)
	v_mfma_f32_16x16x32_bf16 v[28:31], v[16:19], v[0:3], v[124:127]
	v_mfma_f32_16x16x32_bf16 v[52:55], v[180:183], v[4:7], v[28:31]
	v_mfma_f32_16x16x32_bf16 v[28:31], v[184:187], v[0:3], v[120:123]
	v_mfma_f32_16x16x32_bf16 v[104:107], v[192:195], v[4:7], v[28:31]
	v_mfma_f32_16x16x32_bf16 v[28:31], v[16:19], v[8:11], v[116:119]
	v_mfma_f32_16x16x32_bf16 v[68:71], v[180:183], v[12:15], v[28:31]
	v_mfma_f32_16x16x32_bf16 v[28:31], v[184:187], v[8:11], v[112:115]
	v_mfma_f32_16x16x32_bf16 v[116:119], v[192:195], v[12:15], v[28:31]
	v_mfma_f32_16x16x32_bf16 v[28:31], v[16:19], v[44:47], v[108:111]
	v_mfma_f32_16x16x32_bf16 v[76:79], v[180:183], v[202:205], v[28:31]
	v_mfma_f32_16x16x32_bf16 v[28:31], v[184:187], v[44:47], v[188:191]
	v_mfma_f32_16x16x32_bf16 v[108:111], v[192:195], v[202:205], v[28:31]
	v_mfma_f32_16x16x32_bf16 v[28:31], v[16:19], v[206:209], v[100:103]
	v_mfma_f32_16x16x32_bf16 v[84:87], v[180:183], v[222:225], v[28:31]
	v_mfma_f32_16x16x32_bf16 v[28:31], v[184:187], v[206:209], v[96:99]
	v_mfma_f32_16x16x32_bf16 v[96:99], v[192:195], v[222:225], v[28:31]
	s_barrier
	ds_read_b128 v[188:191], v135
	ds_read_b128 v[228:231], v135 offset:1024
	ds_read_b128 v[232:235], v135 offset:2048
	ds_read_b128 v[236:239], v135 offset:3072
	s_waitcnt vmcnt(0)
	s_barrier
	s_waitcnt lgkmcnt(0)
	v_mfma_f32_16x16x32_bf16 v[28:31], v[188:191], v[0:3], v[92:95]
	v_mfma_f32_16x16x32_bf16 v[0:3], v[232:235], v[0:3], v[88:91]
	v_mfma_f32_16x16x32_bf16 v[28:31], v[228:231], v[4:7], v[28:31]
	v_mfma_f32_16x16x32_bf16 v[0:3], v[236:239], v[4:7], v[0:3]
	v_mfma_f32_16x16x32_bf16 v[4:7], v[188:191], v[8:11], v[156:159]
	v_mfma_f32_16x16x32_bf16 v[36:39], v[228:231], v[12:15], v[4:7]
	v_mfma_f32_16x16x32_bf16 v[4:7], v[232:235], v[8:11], v[80:83]
	v_mfma_f32_16x16x32_bf16 v[4:7], v[236:239], v[12:15], v[4:7]
	v_mfma_f32_16x16x32_bf16 v[8:11], v[188:191], v[44:47], v[160:163]
	v_mfma_f32_16x16x32_bf16 v[12:15], v[188:191], v[206:209], v[164:167]
	v_mfma_f32_16x16x32_bf16 v[40:43], v[228:231], v[202:205], v[8:11]
	v_mfma_f32_16x16x32_bf16 v[8:11], v[232:235], v[44:47], v[72:75]
	v_mfma_f32_16x16x32_bf16 v[44:47], v[228:231], v[222:225], v[12:15]
	v_mfma_f32_16x16x32_bf16 v[12:15], v[232:235], v[206:209], v[64:67]
	v_mfma_f32_16x16x32_bf16 v[8:11], v[236:239], v[202:205], v[8:11]
	v_mfma_f32_16x16x32_bf16 v[12:15], v[236:239], v[222:225], v[12:15]
	s_barrier
	s_barrier
	s_waitcnt lgkmcnt(0)
	s_movk_i32 s4, 0x100
	v_cmp_gt_u32_e32 vcc, s4, v128
	s_barrier
	s_and_saveexec_b64 s[4:5], vcc
	s_cbranch_execz .Lh2_epi
	s_barrier

.LBB0_138:
	ds_read_b128 v[140:143], v138
	ds_read_b128 v[144:147], v138 offset:1024
	ds_read_b128 v[148:151], v138 offset:2048
	ds_read_b128 v[152:155], v138 offset:3072
	s_add_u32 s8, s6, s65
	s_addc_u32 s9, s7, s66
	ds_read_b128 v[156:159], v134
	ds_read_b128 v[160:163], v134 offset:1024
	ds_read_b128 v[164:167], v133
	ds_read_b128 v[168:171], v133 offset:1024
	ds_read_b128 v[172:175], v132
	ds_read_b128 v[176:179], v132 offset:1024
	ds_read_b128 v[180:183], v131
	ds_read_b128 v[184:187], v131 offset:1024
	s_mov_b32 m0, s76
	s_add_u32 s98, s8, s44
	s_addc_u32 s99, s9, s45
	global_load_lds_dwordx4 v129, s[98:99]
	s_mov_b32 m0, s75
	s_nop 0
	global_load_lds_dwordx4 v130, s[98:99]
	s_waitcnt lgkmcnt(8)
	s_barrier
	s_waitcnt lgkmcnt(0)
	s_waitcnt lgkmcnt(0)
	v_mfma_f32_16x16x32_bf16 v[124:127], v[140:143], v[156:159], v[124:127]
	v_mfma_f32_16x16x32_bf16 v[120:123], v[148:151], v[156:159], v[120:123]
	v_mfma_f32_16x16x32_bf16 v[116:119], v[140:143], v[164:167], v[116:119]
	v_mfma_f32_16x16x32_bf16 v[112:115], v[148:151], v[164:167], v[112:115]
	v_mfma_f32_16x16x32_bf16 v[108:111], v[140:143], v[172:175], v[108:111]
	v_mfma_f32_16x16x32_bf16 v[104:107], v[148:151], v[172:175], v[104:107]
	v_mfma_f32_16x16x32_bf16 v[100:103], v[140:143], v[180:183], v[100:103]
	v_mfma_f32_16x16x32_bf16 v[96:99], v[148:151], v[180:183], v[96:99]
	v_mfma_f32_16x16x32_bf16 v[124:127], v[144:147], v[160:163], v[124:127]
	v_mfma_f32_16x16x32_bf16 v[120:123], v[152:155], v[160:163], v[120:123]
	v_mfma_f32_16x16x32_bf16 v[116:119], v[144:147], v[168:171], v[116:119]
	v_mfma_f32_16x16x32_bf16 v[112:115], v[152:155], v[168:171], v[112:115]
	v_mfma_f32_16x16x32_bf16 v[108:111], v[144:147], v[176:179], v[108:111]
	v_mfma_f32_16x16x32_bf16 v[104:107], v[152:155], v[176:179], v[104:107]
	v_mfma_f32_16x16x32_bf16 v[100:103], v[144:147], v[184:187], v[100:103]
	v_mfma_f32_16x16x32_bf16 v[96:99], v[152:155], v[184:187], v[96:99]
	s_barrier
	s_add_u32 s10, s6, s36
	s_addc_u32 s11, s7, s37
	ds_read_b128 v[188:191], v137
	ds_read_b128 v[192:195], v137 offset:1024
	ds_read_b128 v[202:205], v137 offset:2048
	ds_read_b128 v[206:209], v137 offset:3072
	s_mov_b32 m0, s63
	s_add_u32 s98, s10, s46
	s_addc_u32 s99, s11, s47
	global_load_lds_dwordx4 v129, s[98:99]
	s_mov_b32 m0, s64
	s_nop 0
	global_load_lds_dwordx4 v130, s[98:99]
	s_barrier
	s_waitcnt lgkmcnt(0)
	s_waitcnt lgkmcnt(0)
	v_mfma_f32_16x16x32_bf16 v[92:95], v[188:191], v[156:159], v[92:95]
	v_mfma_f32_16x16x32_bf16 v[88:91], v[202:205], v[156:159], v[88:91]
	v_mfma_f32_16x16x32_bf16 v[84:87], v[188:191], v[164:167], v[84:87]
	v_mfma_f32_16x16x32_bf16 v[80:83], v[202:205], v[164:167], v[80:83]
	v_mfma_f32_16x16x32_bf16 v[76:79], v[188:191], v[172:175], v[76:79]
	v_mfma_f32_16x16x32_bf16 v[72:75], v[202:205], v[172:175], v[72:75]
	v_mfma_f32_16x16x32_bf16 v[68:71], v[188:191], v[180:183], v[68:71]
	v_mfma_f32_16x16x32_bf16 v[64:67], v[202:205], v[180:183], v[64:67]
	v_mfma_f32_16x16x32_bf16 v[92:95], v[192:195], v[160:163], v[92:95]
	v_mfma_f32_16x16x32_bf16 v[88:91], v[206:209], v[160:163], v[88:91]
	v_mfma_f32_16x16x32_bf16 v[84:87], v[192:195], v[168:171], v[84:87]
	v_mfma_f32_16x16x32_bf16 v[80:83], v[206:209], v[168:171], v[80:83]
	v_mfma_f32_16x16x32_bf16 v[76:79], v[192:195], v[176:179], v[76:79]
	v_mfma_f32_16x16x32_bf16 v[72:75], v[206:209], v[176:179], v[72:75]
	v_mfma_f32_16x16x32_bf16 v[68:71], v[192:195], v[184:187], v[68:71]
	v_mfma_f32_16x16x32_bf16 v[64:67], v[206:209], v[184:187], v[64:67]
	s_barrier
	ds_read_b128 v[156:159], v134 offset:16384
	ds_read_b128 v[160:163], v134 offset:17408
	ds_read_b128 v[164:167], v133 offset:16384
	ds_read_b128 v[168:171], v133 offset:17408
	ds_read_b128 v[172:175], v132 offset:16384
	ds_read_b128 v[176:179], v132 offset:17408
	ds_read_b128 v[180:183], v131 offset:16384
	ds_read_b128 v[184:187], v131 offset:17408
	s_mov_b32 m0, s62
	s_add_u32 s98, s8, s48
	s_addc_u32 s99, s9, s49
	global_load_lds_dwordx4 v129, s[98:99]
	s_mov_b32 m0, s67
	s_nop 0
	global_load_lds_dwordx4 v130, s[98:99]
	s_barrier
	s_waitcnt lgkmcnt(0)
	s_waitcnt lgkmcnt(0)
	v_mfma_f32_16x16x32_bf16 v[60:63], v[140:143], v[156:159], v[60:63]
	v_mfma_f32_16x16x32_bf16 v[56:59], v[148:151], v[156:159], v[56:59]
	v_mfma_f32_16x16x32_bf16 v[52:55], v[140:143], v[164:167], v[52:55]
	v_mfma_f32_16x16x32_bf16 v[48:51], v[148:151], v[164:167], v[48:51]
	v_mfma_f32_16x16x32_bf16 v[44:47], v[140:143], v[172:175], v[44:47]
	v_mfma_f32_16x16x32_bf16 v[40:43], v[148:151], v[172:175], v[40:43]
	v_mfma_f32_16x16x32_bf16 v[36:39], v[140:143], v[180:183], v[36:39]
	v_mfma_f32_16x16x32_bf16 v[32:35], v[148:151], v[180:183], v[32:35]
	v_mfma_f32_16x16x32_bf16 v[60:63], v[144:147], v[160:163], v[60:63]
	v_mfma_f32_16x16x32_bf16 v[56:59], v[152:155], v[160:163], v[56:59]
	v_mfma_f32_16x16x32_bf16 v[52:55], v[144:147], v[168:171], v[52:55]
	v_mfma_f32_16x16x32_bf16 v[48:51], v[152:155], v[168:171], v[48:51]
	v_mfma_f32_16x16x32_bf16 v[44:47], v[144:147], v[176:179], v[44:47]
	v_mfma_f32_16x16x32_bf16 v[40:43], v[152:155], v[176:179], v[40:43]
	v_mfma_f32_16x16x32_bf16 v[36:39], v[144:147], v[184:187], v[36:39]
	v_mfma_f32_16x16x32_bf16 v[32:35], v[152:155], v[184:187], v[32:35]
	s_barrier
	s_mov_b32 m0, s68
	s_add_u32 s98, s10, s50
	s_addc_u32 s99, s11, s51
	global_load_lds_dwordx4 v129, s[98:99]
	s_mov_b32 m0, s69
	s_nop 0
	global_load_lds_dwordx4 v130, s[98:99]
	s_waitcnt vmcnt(6)
	s_barrier
	v_mfma_f32_16x16x32_bf16 v[28:31], v[188:191], v[156:159], v[28:31]
	v_mfma_f32_16x16x32_bf16 v[24:27], v[202:205], v[156:159], v[24:27]
	v_mfma_f32_16x16x32_bf16 v[20:23], v[188:191], v[164:167], v[20:23]
	v_mfma_f32_16x16x32_bf16 v[16:19], v[202:205], v[164:167], v[16:19]
	v_mfma_f32_16x16x32_bf16 v[12:15], v[188:191], v[172:175], v[12:15]
	v_mfma_f32_16x16x32_bf16 v[8:11], v[202:205], v[172:175], v[8:11]
	v_mfma_f32_16x16x32_bf16 v[4:7], v[188:191], v[180:183], v[4:7]
	v_mfma_f32_16x16x32_bf16 v[0:3], v[202:205], v[180:183], v[0:3]
	v_mfma_f32_16x16x32_bf16 v[28:31], v[192:195], v[160:163], v[28:31]
	v_mfma_f32_16x16x32_bf16 v[24:27], v[206:209], v[160:163], v[24:27]
	v_mfma_f32_16x16x32_bf16 v[20:23], v[192:195], v[168:171], v[20:23]
	v_mfma_f32_16x16x32_bf16 v[16:19], v[206:209], v[168:171], v[16:19]
	v_mfma_f32_16x16x32_bf16 v[12:15], v[192:195], v[176:179], v[12:15]
	v_mfma_f32_16x16x32_bf16 v[8:11], v[206:209], v[176:179], v[8:11]
	v_mfma_f32_16x16x32_bf16 v[4:7], v[192:195], v[184:187], v[4:7]
	v_mfma_f32_16x16x32_bf16 v[0:3], v[206:209], v[184:187], v[0:3]
	s_barrier
	ds_read_b128 v[140:143], v136
	ds_read_b128 v[144:147], v136 offset:1024
	ds_read_b128 v[148:151], v136 offset:2048
	ds_read_b128 v[152:155], v136 offset:3072
	ds_read_b128 v[156:159], v134 offset:32768
	ds_read_b128 v[160:163], v134 offset:33792
	ds_read_b128 v[164:167], v133 offset:32768
	ds_read_b128 v[168:171], v133 offset:33792
	ds_read_b128 v[172:175], v132 offset:32768
	ds_read_b128 v[176:179], v132 offset:33792
	ds_read_b128 v[180:183], v131 offset:32768
	ds_read_b128 v[184:187], v131 offset:33792
	s_mov_b32 m0, s70
	s_add_u32 s98, s8, s90
	s_addc_u32 s99, s9, s91
	global_load_lds_dwordx4 v129, s[98:99]
	s_mov_b32 m0, s71
	s_nop 0
	global_load_lds_dwordx4 v130, s[98:99]
	s_waitcnt lgkmcnt(8)
	s_barrier
	s_waitcnt lgkmcnt(0)
	s_waitcnt lgkmcnt(0)
	v_mfma_f32_16x16x32_bf16 v[124:127], v[140:143], v[156:159], v[124:127]
	v_mfma_f32_16x16x32_bf16 v[120:123], v[148:151], v[156:159], v[120:123]
	v_mfma_f32_16x16x32_bf16 v[116:119], v[140:143], v[164:167], v[116:119]
	v_mfma_f32_16x16x32_bf16 v[112:115], v[148:151], v[164:167], v[112:115]
	v_mfma_f32_16x16x32_bf16 v[108:111], v[140:143], v[172:175], v[108:111]
	v_mfma_f32_16x16x32_bf16 v[104:107], v[148:151], v[172:175], v[104:107]
	v_mfma_f32_16x16x32_bf16 v[100:103], v[140:143], v[180:183], v[100:103]
	v_mfma_f32_16x16x32_bf16 v[96:99], v[148:151], v[180:183], v[96:99]
	v_mfma_f32_16x16x32_bf16 v[124:127], v[144:147], v[160:163], v[124:127]
	v_mfma_f32_16x16x32_bf16 v[120:123], v[152:155], v[160:163], v[120:123]
	v_mfma_f32_16x16x32_bf16 v[116:119], v[144:147], v[168:171], v[116:119]
	v_mfma_f32_16x16x32_bf16 v[112:115], v[152:155], v[168:171], v[112:115]
	v_mfma_f32_16x16x32_bf16 v[108:111], v[144:147], v[176:179], v[108:111]
	v_mfma_f32_16x16x32_bf16 v[104:107], v[152:155], v[176:179], v[104:107]
	v_mfma_f32_16x16x32_bf16 v[100:103], v[144:147], v[184:187], v[100:103]
	v_mfma_f32_16x16x32_bf16 v[96:99], v[152:155], v[184:187], v[96:99]
	s_barrier
	ds_read_b128 v[188:191], v135
	ds_read_b128 v[192:195], v135 offset:1024
	ds_read_b128 v[202:205], v135 offset:2048
	ds_read_b128 v[206:209], v135 offset:3072
	s_mov_b32 m0, s28
	s_add_u32 s98, s10, s92
	s_addc_u32 s99, s11, s93
	global_load_lds_dwordx4 v129, s[98:99]
	s_mov_b32 m0, s29
	s_nop 0
	global_load_lds_dwordx4 v130, s[98:99]
	s_barrier
	s_waitcnt lgkmcnt(0)
	s_waitcnt lgkmcnt(0)
	v_mfma_f32_16x16x32_bf16 v[92:95], v[188:191], v[156:159], v[92:95]
	v_mfma_f32_16x16x32_bf16 v[88:91], v[202:205], v[156:159], v[88:91]
	v_mfma_f32_16x16x32_bf16 v[84:87], v[188:191], v[164:167], v[84:87]
	v_mfma_f32_16x16x32_bf16 v[80:83], v[202:205], v[164:167], v[80:83]
	v_mfma_f32_16x16x32_bf16 v[76:79], v[188:191], v[172:175], v[76:79]
	v_mfma_f32_16x16x32_bf16 v[72:75], v[202:205], v[172:175], v[72:75]
	v_mfma_f32_16x16x32_bf16 v[68:71], v[188:191], v[180:183], v[68:71]
	v_mfma_f32_16x16x32_bf16 v[64:67], v[202:205], v[180:183], v[64:67]
	v_mfma_f32_16x16x32_bf16 v[92:95], v[192:195], v[160:163], v[92:95]
	v_mfma_f32_16x16x32_bf16 v[88:91], v[206:209], v[160:163], v[88:91]
	v_mfma_f32_16x16x32_bf16 v[84:87], v[192:195], v[168:171], v[84:87]
	v_mfma_f32_16x16x32_bf16 v[80:83], v[206:209], v[168:171], v[80:83]
	v_mfma_f32_16x16x32_bf16 v[76:79], v[192:195], v[176:179], v[76:79]
	v_mfma_f32_16x16x32_bf16 v[72:75], v[206:209], v[176:179], v[72:75]
	v_mfma_f32_16x16x32_bf16 v[68:71], v[192:195], v[184:187], v[68:71]
	v_mfma_f32_16x16x32_bf16 v[64:67], v[206:209], v[184:187], v[64:67]
	v_mov_b32_e32 v210, v130
	s_barrier
	ds_read_b128 v[156:159], v134 offset:49152
	ds_read_b128 v[160:163], v134 offset:50176
	ds_read_b128 v[164:167], v133 offset:49152
	ds_read_b128 v[168:171], v133 offset:50176
	ds_read_b128 v[172:175], v132 offset:49152
	ds_read_b128 v[176:179], v132 offset:50176
	ds_read_b128 v[180:183], v131 offset:49152
	ds_read_b128 v[184:187], v131 offset:50176
	v_mov_b32_e32 v211, v197
	s_mov_b32 m0, s72
	s_add_u32 s98, s8, s96
	s_addc_u32 s99, s9, s97
	global_load_lds_dwordx4 v129, s[98:99]
	s_mov_b32 m0, s73
	s_nop 0
	global_load_lds_dwordx4 v130, s[98:99]
	s_barrier
	s_waitcnt lgkmcnt(0)
	s_waitcnt lgkmcnt(0)
	v_mfma_f32_16x16x32_bf16 v[60:63], v[140:143], v[156:159], v[60:63]
	v_mfma_f32_16x16x32_bf16 v[56:59], v[148:151], v[156:159], v[56:59]
	v_mfma_f32_16x16x32_bf16 v[52:55], v[140:143], v[164:167], v[52:55]
	v_mfma_f32_16x16x32_bf16 v[48:51], v[148:151], v[164:167], v[48:51]
	v_mfma_f32_16x16x32_bf16 v[44:47], v[140:143], v[172:175], v[44:47]
	v_mfma_f32_16x16x32_bf16 v[40:43], v[148:151], v[172:175], v[40:43]
	v_mfma_f32_16x16x32_bf16 v[36:39], v[140:143], v[180:183], v[36:39]
	v_mfma_f32_16x16x32_bf16 v[32:35], v[148:151], v[180:183], v[32:35]
	v_mfma_f32_16x16x32_bf16 v[60:63], v[144:147], v[160:163], v[60:63]
	v_mfma_f32_16x16x32_bf16 v[56:59], v[152:155], v[160:163], v[56:59]
	v_mfma_f32_16x16x32_bf16 v[52:55], v[144:147], v[168:171], v[52:55]
	v_mfma_f32_16x16x32_bf16 v[48:51], v[152:155], v[168:171], v[48:51]
	v_mfma_f32_16x16x32_bf16 v[44:47], v[144:147], v[176:179], v[44:47]
	v_mfma_f32_16x16x32_bf16 v[40:43], v[152:155], v[176:179], v[40:43]
	v_mfma_f32_16x16x32_bf16 v[36:39], v[144:147], v[184:187], v[36:39]
	v_mfma_f32_16x16x32_bf16 v[32:35], v[152:155], v[184:187], v[32:35]
	s_barrier
	v_mov_b32_e32 v196, v129
	s_mov_b32 m0, s33
	s_add_u32 s98, s10, vcc_lo
	s_addc_u32 s99, s11, vcc_hi
	global_load_lds_dwordx4 v129, s[98:99]
	s_mov_b32 m0, s74
	s_nop 0
	global_load_lds_dwordx4 v130, s[98:99]
	s_waitcnt vmcnt(6)
	s_barrier
	v_mfma_f32_16x16x32_bf16 v[28:31], v[188:191], v[156:159], v[28:31]
	v_mfma_f32_16x16x32_bf16 v[24:27], v[202:205], v[156:159], v[24:27]
	v_mfma_f32_16x16x32_bf16 v[20:23], v[188:191], v[164:167], v[20:23]
	v_mfma_f32_16x16x32_bf16 v[16:19], v[202:205], v[164:167], v[16:19]
	v_mfma_f32_16x16x32_bf16 v[12:15], v[188:191], v[172:175], v[12:15]
	v_mfma_f32_16x16x32_bf16 v[8:11], v[202:205], v[172:175], v[8:11]
	v_mfma_f32_16x16x32_bf16 v[4:7], v[188:191], v[180:183], v[4:7]
	v_mfma_f32_16x16x32_bf16 v[0:3], v[202:205], v[180:183], v[0:3]
	v_mfma_f32_16x16x32_bf16 v[28:31], v[192:195], v[160:163], v[28:31]
	v_mfma_f32_16x16x32_bf16 v[24:27], v[206:209], v[160:163], v[24:27]
	v_mfma_f32_16x16x32_bf16 v[20:23], v[192:195], v[168:171], v[20:23]
	v_mfma_f32_16x16x32_bf16 v[16:19], v[206:209], v[168:171], v[16:19]
	v_mfma_f32_16x16x32_bf16 v[12:15], v[192:195], v[176:179], v[12:15]
	v_mfma_f32_16x16x32_bf16 v[8:11], v[206:209], v[176:179], v[8:11]
	v_mfma_f32_16x16x32_bf16 v[4:7], v[192:195], v[184:187], v[4:7]
	v_mfma_f32_16x16x32_bf16 v[0:3], v[206:209], v[184:187], v[0:3]
	s_add_i32 s38, s38, 2
	s_add_u32 s6, s6, 0x100
	s_addc_u32 s7, s7, 0
	s_cmpk_lt_u32 s38, 0x54
	s_barrier
	s_cbranch_scc1 .LBB0_138
	s_add_u32 s4, s4, 0x2b80
	s_addc_u32 s5, s5, 0
	s_mov_b32 m0, s76
	ds_read_b128 v[140:143], v138
	ds_read_b128 v[144:147], v138 offset:1024
	ds_read_b128 v[148:151], v138 offset:2048
	ds_read_b128 v[152:155], v138 offset:3072
	ds_read_b128 v[156:159], v134
	ds_read_b128 v[160:163], v134 offset:1024
	ds_read_b128 v[164:167], v133
	ds_read_b128 v[168:171], v133 offset:1024
	ds_read_b128 v[172:175], v132
	ds_read_b128 v[176:179], v132 offset:1024
	ds_read_b128 v[180:183], v131
	ds_read_b128 v[184:187], v131 offset:1024
	s_nop 0
	global_load_lds_dwordx4 v129, s[4:5]
	s_mov_b32 m0, s75
	s_nop 0
	global_load_lds_dwordx4 v130, s[4:5]
	s_barrier
	s_waitcnt lgkmcnt(0)
	s_waitcnt lgkmcnt(0)
	v_mfma_f32_16x16x32_bf16 v[124:127], v[140:143], v[156:159], v[124:127]
	v_mfma_f32_16x16x32_bf16 v[120:123], v[148:151], v[156:159], v[120:123]
	v_mfma_f32_16x16x32_bf16 v[116:119], v[140:143], v[164:167], v[116:119]
	v_mfma_f32_16x16x32_bf16 v[112:115], v[148:151], v[164:167], v[112:115]
	v_mfma_f32_16x16x32_bf16 v[108:111], v[140:143], v[172:175], v[108:111]
	v_mfma_f32_16x16x32_bf16 v[100:103], v[140:143], v[180:183], v[100:103]
	v_mfma_f32_16x16x32_bf16 v[96:99], v[148:151], v[180:183], v[96:99]
	v_mfma_f32_16x16x32_bf16 v[124:127], v[144:147], v[160:163], v[124:127]
	v_mfma_f32_16x16x32_bf16 v[120:123], v[152:155], v[160:163], v[120:123]
	v_mfma_f32_16x16x32_bf16 v[116:119], v[144:147], v[168:171], v[116:119]
	v_mfma_f32_16x16x32_bf16 v[112:115], v[152:155], v[168:171], v[112:115]
	v_mfma_f32_16x16x32_bf16 v[108:111], v[144:147], v[176:179], v[108:111]
	v_mfma_f32_16x16x32_bf16 v[104:107], v[148:151], v[172:175], v[104:107]
	v_mfma_f32_16x16x32_bf16 v[100:103], v[144:147], v[184:187], v[100:103]
	v_mfma_f32_16x16x32_bf16 v[96:99], v[152:155], v[184:187], v[96:99]
	v_mfma_f32_16x16x32_bf16 v[188:191], v[152:155], v[176:179], v[104:107]
	s_barrier
	s_nop 2
	ds_read_b128 v[104:107], v137
	ds_read_b128 v[192:195], v137 offset:1024
	ds_read_b128 v[202:205], v137 offset:2048
	ds_read_b128 v[206:209], v137 offset:3072
	s_barrier
	s_waitcnt lgkmcnt(0)
	s_waitcnt lgkmcnt(0)
	v_mfma_f32_16x16x32_bf16 v[92:95], v[104:107], v[156:159], v[92:95]
	v_mfma_f32_16x16x32_bf16 v[88:91], v[202:205], v[156:159], v[88:91]
	v_mfma_f32_16x16x32_bf16 v[80:83], v[202:205], v[164:167], v[80:83]
	v_mfma_f32_16x16x32_bf16 v[72:75], v[202:205], v[172:175], v[72:75]
	v_mfma_f32_16x16x32_bf16 v[64:67], v[202:205], v[180:183], v[64:67]
	v_mfma_f32_16x16x32_bf16 v[92:95], v[192:195], v[160:163], v[92:95]
	v_mfma_f32_16x16x32_bf16 v[88:91], v[206:209], v[160:163], v[88:91]
	v_mfma_f32_16x16x32_bf16 v[84:87], v[104:107], v[164:167], v[84:87]
	v_mfma_f32_16x16x32_bf16 v[80:83], v[206:209], v[168:171], v[80:83]
	v_mfma_f32_16x16x32_bf16 v[76:79], v[104:107], v[172:175], v[76:79]
	v_mfma_f32_16x16x32_bf16 v[72:75], v[206:209], v[176:179], v[72:75]
	v_mfma_f32_16x16x32_bf16 v[68:71], v[104:107], v[180:183], v[68:71]
	v_mfma_f32_16x16x32_bf16 v[64:67], v[206:209], v[184:187], v[64:67]
	v_mfma_f32_16x16x32_bf16 v[156:159], v[192:195], v[168:171], v[84:87]
	v_mfma_f32_16x16x32_bf16 v[160:163], v[192:195], v[176:179], v[76:79]
	v_mfma_f32_16x16x32_bf16 v[164:167], v[192:195], v[184:187], v[68:71]
	s_barrier
	s_nop 1
	ds_read_b128 v[68:71], v134 offset:16384
	ds_read_b128 v[76:79], v134 offset:17408
	ds_read_b128 v[84:87], v133 offset:16384
	ds_read_b128 v[168:171], v133 offset:17408
	ds_read_b128 v[172:175], v132 offset:16384
	ds_read_b128 v[176:179], v132 offset:17408
	ds_read_b128 v[180:183], v131 offset:16384
	ds_read_b128 v[184:187], v131 offset:17408
	s_waitcnt vmcnt(4)
	s_barrier
	s_waitcnt lgkmcnt(0)
	s_waitcnt lgkmcnt(0)
	v_mfma_f32_16x16x32_bf16 v[60:63], v[140:143], v[68:71], v[60:63]
	v_mfma_f32_16x16x32_bf16 v[56:59], v[148:151], v[68:71], v[56:59]
	v_mfma_f32_16x16x32_bf16 v[48:51], v[148:151], v[84:87], v[48:51]
	v_mfma_f32_16x16x32_bf16 v[32:35], v[148:151], v[180:183], v[32:35]
	v_mfma_f32_16x16x32_bf16 v[60:63], v[144:147], v[76:79], v[60:63]
	v_mfma_f32_16x16x32_bf16 v[56:59], v[152:155], v[76:79], v[56:59]
	v_mfma_f32_16x16x32_bf16 v[52:55], v[140:143], v[84:87], v[52:55]
	v_mfma_f32_16x16x32_bf16 v[48:51], v[152:155], v[168:171], v[48:51]
	v_mfma_f32_16x16x32_bf16 v[44:47], v[140:143], v[172:175], v[44:47]
	v_mfma_f32_16x16x32_bf16 v[40:43], v[148:151], v[172:175], v[40:43]
	v_mfma_f32_16x16x32_bf16 v[36:39], v[140:143], v[180:183], v[36:39]
	v_mfma_f32_16x16x32_bf16 v[32:35], v[152:155], v[184:187], v[32:35]
	v_mfma_f32_16x16x32_bf16 v[210:213], v[144:147], v[168:171], v[52:55]
	v_mfma_f32_16x16x32_bf16 v[214:217], v[144:147], v[176:179], v[44:47]
	v_mfma_f32_16x16x32_bf16 v[218:221], v[152:155], v[176:179], v[40:43]
	v_mfma_f32_16x16x32_bf16 v[138:141], v[144:147], v[184:187], v[36:39]
	v_mfma_f32_16x16x32_bf16 v[24:27], v[202:205], v[68:71], v[24:27]
	v_mfma_f32_16x16x32_bf16 v[20:23], v[104:107], v[84:87], v[20:23]
	v_mfma_f32_16x16x32_bf16 v[28:31], v[104:107], v[68:71], v[28:31]
	v_mfma_f32_16x16x32_bf16 v[24:27], v[206:209], v[76:79], v[24:27]
	v_mfma_f32_16x16x32_bf16 v[20:23], v[192:195], v[168:171], v[20:23]
	v_mfma_f32_16x16x32_bf16 v[16:19], v[202:205], v[84:87], v[16:19]
	v_mfma_f32_16x16x32_bf16 v[12:15], v[104:107], v[172:175], v[12:15]
	v_mfma_f32_16x16x32_bf16 v[8:11], v[202:205], v[172:175], v[8:11]
	v_mfma_f32_16x16x32_bf16 v[4:7], v[104:107], v[180:183], v[4:7]
	v_mfma_f32_16x16x32_bf16 v[0:3], v[202:205], v[180:183], v[0:3]
	v_mfma_f32_16x16x32_bf16 v[142:145], v[192:195], v[76:79], v[28:31]
	v_mfma_f32_16x16x32_bf16 v[146:149], v[206:209], v[168:171], v[16:19]
	v_mfma_f32_16x16x32_bf16 v[150:153], v[192:195], v[176:179], v[12:15]
	v_mfma_f32_16x16x32_bf16 v[168:171], v[206:209], v[176:179], v[8:11]
	v_mfma_f32_16x16x32_bf16 v[172:175], v[192:195], v[184:187], v[4:7]
	v_mfma_f32_16x16x32_bf16 v[176:179], v[206:209], v[184:187], v[0:3]
	s_barrier
	ds_read_b128 v[16:19], v136
	ds_read_b128 v[180:183], v136 offset:1024
	ds_read_b128 v[184:187], v136 offset:2048
	ds_read_b128 v[192:195], v136 offset:3072
	ds_read_b128 v[0:3], v134 offset:32768
	ds_read_b128 v[4:7], v134 offset:33792
	ds_read_b128 v[8:11], v133 offset:32768
	ds_read_b128 v[12:15], v133 offset:33792
	ds_read_b128 v[44:47], v132 offset:32768
	ds_read_b128 v[202:205], v132 offset:33792
	ds_read_b128 v[206:209], v131 offset:32768
	ds_read_b128 v[222:225], v131 offset:33792
	s_waitcnt vmcnt(2)
	s_barrier
	s_waitcnt lgkmcnt(0)
	s_waitcnt lgkmcnt(0)
	v_mfma_f32_16x16x32_bf16 v[28:31], v[16:19], v[0:3], v[124:127]
	v_mfma_f32_16x16x32_bf16 v[52:55], v[180:183], v[4:7], v[28:31]
	v_mfma_f32_16x16x32_bf16 v[28:31], v[184:187], v[0:3], v[120:123]
	v_mfma_f32_16x16x32_bf16 v[104:107], v[192:195], v[4:7], v[28:31]
	v_mfma_f32_16x16x32_bf16 v[28:31], v[16:19], v[8:11], v[116:119]
	v_mfma_f32_16x16x32_bf16 v[68:71], v[180:183], v[12:15], v[28:31]
	v_mfma_f32_16x16x32_bf16 v[28:31], v[184:187], v[8:11], v[112:115]
	v_mfma_f32_16x16x32_bf16 v[116:119], v[192:195], v[12:15], v[28:31]
	v_mfma_f32_16x16x32_bf16 v[28:31], v[16:19], v[44:47], v[108:111]
	v_mfma_f32_16x16x32_bf16 v[76:79], v[180:183], v[202:205], v[28:31]
	v_mfma_f32_16x16x32_bf16 v[28:31], v[184:187], v[44:47], v[188:191]
	v_mfma_f32_16x16x32_bf16 v[108:111], v[192:195], v[202:205], v[28:31]
	v_mfma_f32_16x16x32_bf16 v[28:31], v[16:19], v[206:209], v[100:103]
	v_mfma_f32_16x16x32_bf16 v[84:87], v[180:183], v[222:225], v[28:31]
	v_mfma_f32_16x16x32_bf16 v[28:31], v[184:187], v[206:209], v[96:99]
	v_mfma_f32_16x16x32_bf16 v[96:99], v[192:195], v[222:225], v[28:31]
	s_barrier
	ds_read_b128 v[188:191], v135
	ds_read_b128 v[228:231], v135 offset:1024
	ds_read_b128 v[232:235], v135 offset:2048
	ds_read_b128 v[236:239], v135 offset:3072
	s_waitcnt vmcnt(0)
	s_barrier
	s_waitcnt lgkmcnt(0)
	s_waitcnt lgkmcnt(0)
	v_mfma_f32_16x16x32_bf16 v[28:31], v[188:191], v[0:3], v[92:95]
	v_mfma_f32_16x16x32_bf16 v[0:3], v[232:235], v[0:3], v[88:91]
	v_mfma_f32_16x16x32_bf16 v[28:31], v[228:231], v[4:7], v[28:31]
	v_mfma_f32_16x16x32_bf16 v[0:3], v[236:239], v[4:7], v[0:3]
	v_mfma_f32_16x16x32_bf16 v[4:7], v[188:191], v[8:11], v[156:159]
	v_mfma_f32_16x16x32_bf16 v[36:39], v[228:231], v[12:15], v[4:7]
	v_mfma_f32_16x16x32_bf16 v[4:7], v[232:235], v[8:11], v[80:83]
	v_mfma_f32_16x16x32_bf16 v[4:7], v[236:239], v[12:15], v[4:7]
	v_mfma_f32_16x16x32_bf16 v[8:11], v[188:191], v[44:47], v[160:163]
	v_mfma_f32_16x16x32_bf16 v[12:15], v[188:191], v[206:209], v[164:167]
	v_mfma_f32_16x16x32_bf16 v[40:43], v[228:231], v[202:205], v[8:11]
	v_mfma_f32_16x16x32_bf16 v[8:11], v[232:235], v[44:47], v[72:75]
	v_mfma_f32_16x16x32_bf16 v[44:47], v[228:231], v[222:225], v[12:15]
	v_mfma_f32_16x16x32_bf16 v[12:15], v[232:235], v[206:209], v[64:67]
	v_mfma_f32_16x16x32_bf16 v[8:11], v[236:239], v[202:205], v[8:11]
	v_mfma_f32_16x16x32_bf16 v[12:15], v[236:239], v[222:225], v[12:15]
	s_barrier
	ds_read_b128 v[64:67], v134 offset:49152
	ds_read_b128 v[134:137], v134 offset:50176
	ds_read_b128 v[154:157], v133 offset:49152
	ds_read_b128 v[158:161], v133 offset:50176
	ds_read_b128 v[162:165], v132 offset:49152
	ds_read_b128 v[202:205], v132 offset:50176
	ds_read_b128 v[206:209], v131 offset:49152
	ds_read_b128 v[130:133], v131 offset:50176
	s_barrier
	s_waitcnt lgkmcnt(0)
	s_waitcnt lgkmcnt(0)
	v_mfma_f32_16x16x32_bf16 v[56:59], v[184:187], v[64:67], v[56:59]
	v_mfma_f32_16x16x32_bf16 v[48:51], v[184:187], v[154:157], v[48:51]
	v_mfma_f32_16x16x32_bf16 v[60:63], v[16:19], v[64:67], v[60:63]
	v_mfma_f32_16x16x32_bf16 v[92:95], v[192:195], v[134:137], v[56:59]
	v_mfma_f32_16x16x32_bf16 v[56:59], v[16:19], v[154:157], v[210:213]
	v_mfma_f32_16x16x32_bf16 v[88:91], v[192:195], v[158:161], v[48:51]
	v_mfma_f32_16x16x32_bf16 v[48:51], v[16:19], v[162:165], v[214:217]
	v_mfma_f32_16x16x32_bf16 v[16:19], v[16:19], v[206:209], v[138:141]
	v_mfma_f32_16x16x32_bf16 v[120:123], v[180:183], v[202:205], v[48:51]
	v_mfma_f32_16x16x32_bf16 v[48:51], v[184:187], v[162:165], v[218:221]
	v_mfma_f32_16x16x32_bf16 v[124:127], v[180:183], v[130:133], v[16:19]
	v_mfma_f32_16x16x32_bf16 v[16:19], v[184:187], v[206:209], v[32:35]
	v_mfma_f32_16x16x32_bf16 v[100:103], v[180:183], v[134:137], v[60:63]
	v_mfma_f32_16x16x32_bf16 v[112:115], v[180:183], v[158:161], v[56:59]
	v_mfma_f32_16x16x32_bf16 v[80:83], v[192:195], v[202:205], v[48:51]
	v_mfma_f32_16x16x32_bf16 v[72:75], v[192:195], v[130:133], v[16:19]
	v_mfma_f32_16x16x32_bf16 v[16:19], v[188:191], v[64:67], v[142:145]
	v_mfma_f32_16x16x32_bf16 v[48:51], v[228:231], v[134:137], v[16:19]
	v_mfma_f32_16x16x32_bf16 v[16:19], v[232:235], v[64:67], v[24:27]
	v_mfma_f32_16x16x32_bf16 v[20:23], v[188:191], v[154:157], v[20:23]
	v_mfma_f32_16x16x32_bf16 v[24:27], v[188:191], v[162:165], v[150:153]
	v_mfma_f32_16x16x32_bf16 v[32:35], v[188:191], v[206:209], v[172:175]
	v_mfma_f32_16x16x32_bf16 v[56:59], v[228:231], v[158:161], v[20:23]
	v_mfma_f32_16x16x32_bf16 v[20:23], v[232:235], v[154:157], v[146:149]
	v_mfma_f32_16x16x32_bf16 v[60:63], v[228:231], v[202:205], v[24:27]
	v_mfma_f32_16x16x32_bf16 v[24:27], v[232:235], v[162:165], v[168:171]
	v_mfma_f32_16x16x32_bf16 v[64:67], v[228:231], v[130:133], v[32:35]
	v_mfma_f32_16x16x32_bf16 v[32:35], v[232:235], v[206:209], v[176:179]
	v_mfma_f32_16x16x32_bf16 v[16:19], v[236:239], v[134:137], v[16:19]
	v_mfma_f32_16x16x32_bf16 v[20:23], v[236:239], v[158:161], v[20:23]
	v_mfma_f32_16x16x32_bf16 v[24:27], v[236:239], v[202:205], v[24:27]
	v_mfma_f32_16x16x32_bf16 v[32:35], v[236:239], v[130:133], v[32:35]
	s_movk_i32 s4, 0x100
	v_cmp_gt_u32_e32 vcc, s4, v128
	s_barrier
	s_and_saveexec_b64 s[4:5], vcc
	s_cbranch_execz .LBB0_95
	s_barrier
	s_branch .LBB0_95

.Lhf_192:
	ds_read_b128 v[140:143], v129
	ds_read_b128 v[144:147], v129 offset:1024
	ds_read_b128 v[148:151], v129 offset:2048
	ds_read_b128 v[152:155], v129 offset:3072
	s_add_u32 s28, s56, s4
	s_addc_u32 s29, s57, s5
	ds_read_b128 v[156:159], v136
	ds_read_b128 v[160:163], v136 offset:1024
	ds_read_b128 v[164:167], v135
	ds_read_b128 v[168:171], v135 offset:1024
	ds_read_b128 v[172:175], v134
	ds_read_b128 v[176:179], v134 offset:1024
	ds_read_b128 v[180:183], v133
	ds_read_b128 v[184:187], v133 offset:1024
	s_add_i32 s40, s52, 0xc000
	s_mov_b32 m0, s40
	s_add_i32 s39, s52, 0xe000
	s_mov_b32 m0, s39
	s_nop 0
	s_waitcnt lgkmcnt(8)
	s_barrier
	s_waitcnt lgkmcnt(0)
	v_mfma_f32_16x16x32_bf16 v[124:127], v[140:143], v[156:159], v[124:127]
	v_mfma_f32_16x16x32_bf16 v[120:123], v[148:151], v[156:159], v[120:123]
	v_mfma_f32_16x16x32_bf16 v[116:119], v[140:143], v[164:167], v[116:119]
	v_mfma_f32_16x16x32_bf16 v[112:115], v[148:151], v[164:167], v[112:115]
	v_mfma_f32_16x16x32_bf16 v[108:111], v[140:143], v[172:175], v[108:111]
	v_mfma_f32_16x16x32_bf16 v[104:107], v[148:151], v[172:175], v[104:107]
	v_mfma_f32_16x16x32_bf16 v[100:103], v[140:143], v[180:183], v[100:103]
	v_mfma_f32_16x16x32_bf16 v[96:99], v[148:151], v[180:183], v[96:99]
	v_mfma_f32_16x16x32_bf16 v[124:127], v[144:147], v[160:163], v[124:127]
	v_mfma_f32_16x16x32_bf16 v[120:123], v[152:155], v[160:163], v[120:123]
	v_mfma_f32_16x16x32_bf16 v[116:119], v[144:147], v[168:171], v[116:119]
	v_mfma_f32_16x16x32_bf16 v[112:115], v[152:155], v[168:171], v[112:115]
	v_mfma_f32_16x16x32_bf16 v[108:111], v[144:147], v[176:179], v[108:111]
	v_mfma_f32_16x16x32_bf16 v[104:107], v[152:155], v[176:179], v[104:107]
	v_mfma_f32_16x16x32_bf16 v[100:103], v[144:147], v[184:187], v[100:103]
	v_mfma_f32_16x16x32_bf16 v[96:99], v[152:155], v[184:187], v[96:99]
	s_barrier
	s_add_u32 s58, s56, s36
	s_addc_u32 s59, s57, s37
	ds_read_b128 v[188:191], v139
	ds_read_b128 v[192:195], v139 offset:1024
	ds_read_b128 v[202:205], v139 offset:2048
	ds_read_b128 v[206:209], v139 offset:3072
	s_add_i32 m0, s52, 0x10000
	s_add_u32 s98, s58, s46
	s_addc_u32 s99, s59, s47
	global_load_lds_dwordx4 v128, s[98:99]
	s_add_i32 m0, s52, 0x12000
	s_nop 0
	global_load_lds_dwordx4 v130, s[98:99]
	s_barrier
	s_waitcnt lgkmcnt(0)
	v_mfma_f32_16x16x32_bf16 v[92:95], v[188:191], v[156:159], v[92:95]
	v_mfma_f32_16x16x32_bf16 v[88:91], v[202:205], v[156:159], v[88:91]
	v_mfma_f32_16x16x32_bf16 v[84:87], v[188:191], v[164:167], v[84:87]
	v_mfma_f32_16x16x32_bf16 v[80:83], v[202:205], v[164:167], v[80:83]
	v_mfma_f32_16x16x32_bf16 v[76:79], v[188:191], v[172:175], v[76:79]
	v_mfma_f32_16x16x32_bf16 v[72:75], v[202:205], v[172:175], v[72:75]
	v_mfma_f32_16x16x32_bf16 v[68:71], v[188:191], v[180:183], v[68:71]
	v_mfma_f32_16x16x32_bf16 v[64:67], v[202:205], v[180:183], v[64:67]
	v_mfma_f32_16x16x32_bf16 v[92:95], v[192:195], v[160:163], v[92:95]
	v_mfma_f32_16x16x32_bf16 v[88:91], v[206:209], v[160:163], v[88:91]
	v_mfma_f32_16x16x32_bf16 v[84:87], v[192:195], v[168:171], v[84:87]
	v_mfma_f32_16x16x32_bf16 v[80:83], v[206:209], v[168:171], v[80:83]
	v_mfma_f32_16x16x32_bf16 v[76:79], v[192:195], v[176:179], v[76:79]
	v_mfma_f32_16x16x32_bf16 v[72:75], v[206:209], v[176:179], v[72:75]
	v_mfma_f32_16x16x32_bf16 v[68:71], v[192:195], v[184:187], v[68:71]
	v_mfma_f32_16x16x32_bf16 v[64:67], v[206:209], v[184:187], v[64:67]
	s_barrier
	s_mov_b32 m0, s52
	s_add_u32 s98, s28, s48
	s_addc_u32 s99, s29, s49
	global_load_lds_dwordx4 v128, s[98:99]
	s_add_i32 m0, s52, 0x2000
	s_nop 0
	global_load_lds_dwordx4 v130, s[98:99]
	s_waitcnt vmcnt(4)
	s_barrier
	s_add_i32 m0, s52, 0x14000
	s_add_u32 s98, s58, s50
	s_addc_u32 s99, s59, s51
	global_load_lds_dwordx4 v128, s[98:99]
	s_add_i32 m0, s52, 0x16000
	s_nop 0
	global_load_lds_dwordx4 v130, s[98:99]
	s_barrier
	ds_read_b128 v[140:143], v138
	ds_read_b128 v[144:147], v138 offset:1024
	ds_read_b128 v[148:151], v138 offset:2048
	ds_read_b128 v[152:155], v138 offset:3072
	ds_read_b128 v[156:159], v136 offset:32768
	ds_read_b128 v[160:163], v136 offset:33792
	ds_read_b128 v[164:167], v135 offset:32768
	ds_read_b128 v[168:171], v135 offset:33792
	ds_read_b128 v[172:175], v134 offset:32768
	ds_read_b128 v[176:179], v134 offset:33792
	ds_read_b128 v[180:183], v133 offset:32768
	ds_read_b128 v[184:187], v133 offset:33792
	s_add_i32 m0, s52, 0x4000
	s_add_i32 m0, s52, 0x6000
	s_nop 0
	s_waitcnt lgkmcnt(8)
	s_barrier
	s_waitcnt lgkmcnt(0)
	v_mfma_f32_16x16x32_bf16 v[124:127], v[140:143], v[156:159], v[124:127]
	v_mfma_f32_16x16x32_bf16 v[120:123], v[148:151], v[156:159], v[120:123]
	v_mfma_f32_16x16x32_bf16 v[116:119], v[140:143], v[164:167], v[116:119]
	v_mfma_f32_16x16x32_bf16 v[112:115], v[148:151], v[164:167], v[112:115]
	v_mfma_f32_16x16x32_bf16 v[108:111], v[140:143], v[172:175], v[108:111]
	v_mfma_f32_16x16x32_bf16 v[104:107], v[148:151], v[172:175], v[104:107]
	v_mfma_f32_16x16x32_bf16 v[100:103], v[140:143], v[180:183], v[100:103]
	v_mfma_f32_16x16x32_bf16 v[96:99], v[148:151], v[180:183], v[96:99]
	v_mfma_f32_16x16x32_bf16 v[124:127], v[144:147], v[160:163], v[124:127]
	v_mfma_f32_16x16x32_bf16 v[120:123], v[152:155], v[160:163], v[120:123]
	v_mfma_f32_16x16x32_bf16 v[116:119], v[144:147], v[168:171], v[116:119]
	v_mfma_f32_16x16x32_bf16 v[112:115], v[152:155], v[168:171], v[112:115]
	v_mfma_f32_16x16x32_bf16 v[108:111], v[144:147], v[176:179], v[108:111]
	v_mfma_f32_16x16x32_bf16 v[104:107], v[152:155], v[176:179], v[104:107]
	v_mfma_f32_16x16x32_bf16 v[100:103], v[144:147], v[184:187], v[100:103]
	v_mfma_f32_16x16x32_bf16 v[96:99], v[152:155], v[184:187], v[96:99]
	s_barrier
	ds_read_b128 v[188:191], v137
	ds_read_b128 v[192:195], v137 offset:1024
	ds_read_b128 v[202:205], v137 offset:2048
	ds_read_b128 v[206:209], v137 offset:3072
	s_mov_b32 m0, s7
	s_add_u32 s98, s58, s68
	s_addc_u32 s99, s59, s69
	global_load_lds_dwordx4 v128, s[98:99]
	s_mov_b32 m0, s53
	s_nop 0
	global_load_lds_dwordx4 v130, s[98:99]
	s_barrier
	s_waitcnt lgkmcnt(0)
	v_mfma_f32_16x16x32_bf16 v[92:95], v[188:191], v[156:159], v[92:95]
	v_mfma_f32_16x16x32_bf16 v[88:91], v[202:205], v[156:159], v[88:91]
	v_mfma_f32_16x16x32_bf16 v[84:87], v[188:191], v[164:167], v[84:87]
	v_mfma_f32_16x16x32_bf16 v[80:83], v[202:205], v[164:167], v[80:83]
	v_mfma_f32_16x16x32_bf16 v[76:79], v[188:191], v[172:175], v[76:79]
	v_mfma_f32_16x16x32_bf16 v[72:75], v[202:205], v[172:175], v[72:75]
	v_mfma_f32_16x16x32_bf16 v[68:71], v[188:191], v[180:183], v[68:71]
	v_mfma_f32_16x16x32_bf16 v[64:67], v[202:205], v[180:183], v[64:67]
	v_mfma_f32_16x16x32_bf16 v[92:95], v[192:195], v[160:163], v[92:95]
	v_mfma_f32_16x16x32_bf16 v[88:91], v[206:209], v[160:163], v[88:91]
	v_mfma_f32_16x16x32_bf16 v[84:87], v[192:195], v[168:171], v[84:87]
	v_mfma_f32_16x16x32_bf16 v[80:83], v[206:209], v[168:171], v[80:83]
	v_mfma_f32_16x16x32_bf16 v[76:79], v[192:195], v[176:179], v[76:79]
	v_mfma_f32_16x16x32_bf16 v[72:75], v[206:209], v[176:179], v[72:75]
	v_mfma_f32_16x16x32_bf16 v[68:71], v[192:195], v[184:187], v[68:71]
	v_mfma_f32_16x16x32_bf16 v[64:67], v[206:209], v[184:187], v[64:67]
	v_mov_b32_e32 v210, v130
	s_barrier
	v_mov_b32_e32 v211, v197
	s_mov_b32 m0, s9
	s_add_u32 s98, s28, s70
	s_addc_u32 s99, s29, s71
	global_load_lds_dwordx4 v128, s[98:99]
	s_mov_b32 m0, s33
	s_nop 0
	global_load_lds_dwordx4 v130, s[98:99]
	s_waitcnt vmcnt(4)
	s_barrier
	v_mov_b32_e32 v196, v128
	s_mov_b32 m0, s65
	s_add_u32 s98, s58, s72
	s_addc_u32 s99, s59, s73
	global_load_lds_dwordx4 v128, s[98:99]
	s_mov_b32 m0, s66
	s_nop 0
	global_load_lds_dwordx4 v130, s[98:99]
	s_barrier
	s_add_i32 s38, s38, 2
	s_add_u32 s56, s56, 0x100
	s_addc_u32 s57, s57, 0
	s_cmp_lt_u32 s38, 28
	s_cbranch_scc1 .Lhf_192
	s_lshl_b64 s[4:5], s[10:11], 12
	v_readlane_b32 s10, v254, 12
	v_readlane_b32 s11, v254, 13
	s_add_u32 s4, s10, s4
	s_addc_u32 s5, s11, s5
	ds_read_b128 v[140:143], v129
	ds_read_b128 v[144:147], v129 offset:1024
	ds_read_b128 v[148:151], v129 offset:2048
	ds_read_b128 v[152:155], v129 offset:3072
	ds_read_b128 v[156:159], v136
	ds_read_b128 v[160:163], v136 offset:1024
	ds_read_b128 v[164:167], v135
	ds_read_b128 v[168:171], v135 offset:1024
	ds_read_b128 v[172:175], v134
	ds_read_b128 v[176:179], v134 offset:1024
	ds_read_b128 v[180:183], v133
	ds_read_b128 v[184:187], v133 offset:1024
	v_mov_b32_e32 v129, v197
	v_lshl_add_u64 v[128:129], s[4:5], 0, v[128:129]
	s_mov_b64 s[10:11], 0xf80
	s_mov_b32 m0, s40
	v_lshl_add_u64 v[128:129], v[128:129], 0, s[10:11]
	v_mov_b32_e32 v131, v197
	v_lshl_add_u64 v[128:129], s[4:5], 0, v[130:131]
	v_lshl_add_u64 v[128:129], v[128:129], 0, s[10:11]
	s_mov_b32 m0, s39
	s_nop 0
	s_barrier
	s_waitcnt lgkmcnt(0)
	v_mfma_f32_16x16x32_bf16 v[124:127], v[140:143], v[156:159], v[124:127]
	v_mfma_f32_16x16x32_bf16 v[116:119], v[140:143], v[164:167], v[116:119]
	v_mfma_f32_16x16x32_bf16 v[112:115], v[148:151], v[164:167], v[112:115]
	v_mfma_f32_16x16x32_bf16 v[108:111], v[140:143], v[172:175], v[108:111]
	v_mfma_f32_16x16x32_bf16 v[104:107], v[148:151], v[172:175], v[104:107]
	v_mfma_f32_16x16x32_bf16 v[100:103], v[140:143], v[180:183], v[100:103]
	v_mfma_f32_16x16x32_bf16 v[96:99], v[148:151], v[180:183], v[96:99]
	v_mfma_f32_16x16x32_bf16 v[124:127], v[144:147], v[160:163], v[124:127]
	v_mfma_f32_16x16x32_bf16 v[120:123], v[148:151], v[156:159], v[120:123]
	v_mfma_f32_16x16x32_bf16 v[116:119], v[144:147], v[168:171], v[116:119]
	v_mfma_f32_16x16x32_bf16 v[112:115], v[152:155], v[168:171], v[112:115]
	v_mfma_f32_16x16x32_bf16 v[108:111], v[144:147], v[176:179], v[108:111]
	v_mfma_f32_16x16x32_bf16 v[104:107], v[152:155], v[176:179], v[104:107]
	v_mfma_f32_16x16x32_bf16 v[100:103], v[144:147], v[184:187], v[100:103]
	v_mfma_f32_16x16x32_bf16 v[96:99], v[152:155], v[184:187], v[96:99]
	v_mfma_f32_16x16x32_bf16 v[128:131], v[152:155], v[160:163], v[120:123]
	s_barrier
	s_nop 0
	ds_read_b128 v[120:123], v139
	ds_read_b128 v[188:191], v139 offset:1024
	ds_read_b128 v[192:195], v139 offset:2048
	ds_read_b128 v[202:205], v139 offset:3072
	s_barrier
	s_waitcnt lgkmcnt(0)
	v_mfma_f32_16x16x32_bf16 v[76:79], v[120:123], v[172:175], v[76:79]
	v_mfma_f32_16x16x32_bf16 v[68:71], v[120:123], v[180:183], v[68:71]
	v_mfma_f32_16x16x32_bf16 v[64:67], v[192:195], v[180:183], v[64:67]
	v_mfma_f32_16x16x32_bf16 v[92:95], v[120:123], v[156:159], v[92:95]
	v_mfma_f32_16x16x32_bf16 v[88:91], v[192:195], v[156:159], v[88:91]
	v_mfma_f32_16x16x32_bf16 v[84:87], v[120:123], v[164:167], v[84:87]
	v_mfma_f32_16x16x32_bf16 v[80:83], v[192:195], v[164:167], v[80:83]
	v_mfma_f32_16x16x32_bf16 v[76:79], v[188:191], v[176:179], v[76:79]
	v_mfma_f32_16x16x32_bf16 v[72:75], v[192:195], v[172:175], v[72:75]
	v_mfma_f32_16x16x32_bf16 v[68:71], v[188:191], v[184:187], v[68:71]
	v_mfma_f32_16x16x32_bf16 v[64:67], v[202:205], v[184:187], v[64:67]
	v_mfma_f32_16x16x32_bf16 v[206:209], v[188:191], v[160:163], v[92:95]
	v_mfma_f32_16x16x32_bf16 v[156:159], v[202:205], v[160:163], v[88:91]
	v_mfma_f32_16x16x32_bf16 v[160:163], v[188:191], v[168:171], v[84:87]
	v_mfma_f32_16x16x32_bf16 v[164:167], v[202:205], v[168:171], v[80:83]
	v_mfma_f32_16x16x32_bf16 v[168:171], v[202:205], v[176:179], v[72:75]
	s_barrier
	s_nop 0
	s_waitcnt vmcnt(2)
	s_barrier
	s_waitcnt lgkmcnt(0)
	s_barrier
	s_nop 0
	ds_read_b128 v[8:11], v138
	ds_read_b128 v[16:19], v138 offset:1024
	ds_read_b128 v[176:179], v138 offset:2048
	ds_read_b128 v[180:183], v138 offset:3072
	ds_read_b128 v[20:23], v136 offset:32768
	ds_read_b128 v[24:27], v136 offset:33792
	ds_read_b128 v[28:31], v135 offset:32768
	ds_read_b128 v[56:59], v135 offset:33792
	ds_read_b128 v[188:191], v134 offset:32768
	ds_read_b128 v[192:195], v134 offset:33792
	ds_read_b128 v[202:205], v133 offset:32768
	ds_read_b128 v[210:213], v133 offset:33792
	s_waitcnt vmcnt(0)
	s_barrier
	s_waitcnt lgkmcnt(0)
	v_mfma_f32_16x16x32_bf16 v[72:75], v[8:11], v[20:23], v[124:127]
	v_mfma_f32_16x16x32_bf16 v[120:123], v[16:19], v[24:27], v[72:75]
	v_mfma_f32_16x16x32_bf16 v[72:75], v[176:179], v[20:23], v[128:131]
	v_mfma_f32_16x16x32_bf16 v[124:127], v[180:183], v[24:27], v[72:75]
	v_mfma_f32_16x16x32_bf16 v[72:75], v[8:11], v[28:31], v[116:119]
	v_mfma_f32_16x16x32_bf16 v[116:119], v[16:19], v[56:59], v[72:75]
	v_mfma_f32_16x16x32_bf16 v[72:75], v[176:179], v[28:31], v[112:115]
	v_mfma_f32_16x16x32_bf16 v[112:115], v[180:183], v[56:59], v[72:75]
	v_mfma_f32_16x16x32_bf16 v[72:75], v[8:11], v[188:191], v[108:111]
	v_mfma_f32_16x16x32_bf16 v[88:91], v[16:19], v[192:195], v[72:75]
	v_mfma_f32_16x16x32_bf16 v[72:75], v[176:179], v[188:191], v[104:107]
	v_mfma_f32_16x16x32_bf16 v[92:95], v[180:183], v[192:195], v[72:75]
	v_mfma_f32_16x16x32_bf16 v[72:75], v[8:11], v[202:205], v[100:103]
	v_mfma_f32_16x16x32_bf16 v[84:87], v[16:19], v[210:213], v[72:75]
	v_mfma_f32_16x16x32_bf16 v[72:75], v[176:179], v[202:205], v[96:99]
	v_mfma_f32_16x16x32_bf16 v[80:83], v[180:183], v[210:213], v[72:75]
	s_barrier
	ds_read_b128 v[128:131], v137
	ds_read_b128 v[214:217], v137 offset:1024
	ds_read_b128 v[218:221], v137 offset:2048
	ds_read_b128 v[222:225], v137 offset:3072
	s_waitcnt vmcnt(0)
	s_barrier
	s_waitcnt lgkmcnt(0)
	v_mfma_f32_16x16x32_bf16 v[72:75], v[128:131], v[20:23], v[206:209]
	v_mfma_f32_16x16x32_bf16 v[20:23], v[218:221], v[20:23], v[156:159]
	v_mfma_f32_16x16x32_bf16 v[108:111], v[222:225], v[24:27], v[20:23]
	v_mfma_f32_16x16x32_bf16 v[20:23], v[128:131], v[28:31], v[160:163]
	v_mfma_f32_16x16x32_bf16 v[100:103], v[214:217], v[56:59], v[20:23]
	v_mfma_f32_16x16x32_bf16 v[20:23], v[218:221], v[28:31], v[164:167]
	v_mfma_f32_16x16x32_bf16 v[96:99], v[222:225], v[56:59], v[20:23]
	v_mfma_f32_16x16x32_bf16 v[20:23], v[128:131], v[188:191], v[76:79]
	v_mfma_f32_16x16x32_bf16 v[104:107], v[214:217], v[24:27], v[72:75]
	v_mfma_f32_16x16x32_bf16 v[72:75], v[214:217], v[192:195], v[20:23]
	v_mfma_f32_16x16x32_bf16 v[20:23], v[218:221], v[188:191], v[168:171]
	v_mfma_f32_16x16x32_bf16 v[76:79], v[222:225], v[192:195], v[20:23]
	v_mfma_f32_16x16x32_bf16 v[20:23], v[128:131], v[202:205], v[68:71]
	v_mfma_f32_16x16x32_bf16 v[68:71], v[214:217], v[210:213], v[20:23]
	v_mfma_f32_16x16x32_bf16 v[20:23], v[218:221], v[202:205], v[64:67]
	v_mfma_f32_16x16x32_bf16 v[64:67], v[222:225], v[210:213], v[20:23]
	s_barrier
	s_barrier
	s_waitcnt lgkmcnt(0)
	s_movk_i32 s4, 0x100
	v_cmp_gt_u32_e32 vcc, s4, v132
	s_barrier
	s_and_saveexec_b64 s[4:5], vcc
	s_cbranch_execz .Lhf_195
	s_barrier

.LBB0_192:
	ds_read_b128 v[140:143], v129
	ds_read_b128 v[144:147], v129 offset:1024
	ds_read_b128 v[148:151], v129 offset:2048
	ds_read_b128 v[152:155], v129 offset:3072
	s_add_u32 s28, s56, s4
	s_addc_u32 s29, s57, s5
	ds_read_b128 v[156:159], v136
	ds_read_b128 v[160:163], v136 offset:1024
	ds_read_b128 v[164:167], v135
	ds_read_b128 v[168:171], v135 offset:1024
	ds_read_b128 v[172:175], v134
	ds_read_b128 v[176:179], v134 offset:1024
	ds_read_b128 v[180:183], v133
	ds_read_b128 v[184:187], v133 offset:1024
	s_add_i32 s40, s52, 0xc000
	s_mov_b32 m0, s40
	s_add_i32 s39, s52, 0xe000
	s_add_u32 s98, s28, s44
	s_addc_u32 s99, s29, s45
	global_load_lds_dwordx4 v128, s[98:99]
	s_mov_b32 m0, s39
	s_nop 0
	global_load_lds_dwordx4 v130, s[98:99]
	s_waitcnt lgkmcnt(8)
	s_barrier
	s_waitcnt lgkmcnt(0)
	s_waitcnt lgkmcnt(0)
	v_mfma_f32_16x16x32_bf16 v[124:127], v[140:143], v[156:159], v[124:127]
	v_mfma_f32_16x16x32_bf16 v[120:123], v[148:151], v[156:159], v[120:123]
	v_mfma_f32_16x16x32_bf16 v[116:119], v[140:143], v[164:167], v[116:119]
	v_mfma_f32_16x16x32_bf16 v[112:115], v[148:151], v[164:167], v[112:115]
	v_mfma_f32_16x16x32_bf16 v[108:111], v[140:143], v[172:175], v[108:111]
	v_mfma_f32_16x16x32_bf16 v[104:107], v[148:151], v[172:175], v[104:107]
	v_mfma_f32_16x16x32_bf16 v[100:103], v[140:143], v[180:183], v[100:103]
	v_mfma_f32_16x16x32_bf16 v[96:99], v[148:151], v[180:183], v[96:99]
	v_mfma_f32_16x16x32_bf16 v[124:127], v[144:147], v[160:163], v[124:127]
	v_mfma_f32_16x16x32_bf16 v[120:123], v[152:155], v[160:163], v[120:123]
	v_mfma_f32_16x16x32_bf16 v[116:119], v[144:147], v[168:171], v[116:119]
	v_mfma_f32_16x16x32_bf16 v[112:115], v[152:155], v[168:171], v[112:115]
	v_mfma_f32_16x16x32_bf16 v[108:111], v[144:147], v[176:179], v[108:111]
	v_mfma_f32_16x16x32_bf16 v[104:107], v[152:155], v[176:179], v[104:107]
	v_mfma_f32_16x16x32_bf16 v[100:103], v[144:147], v[184:187], v[100:103]
	v_mfma_f32_16x16x32_bf16 v[96:99], v[152:155], v[184:187], v[96:99]
	s_barrier
	s_add_u32 s58, s56, s36
	s_addc_u32 s59, s57, s37
	ds_read_b128 v[188:191], v139
	ds_read_b128 v[192:195], v139 offset:1024
	ds_read_b128 v[202:205], v139 offset:2048
	ds_read_b128 v[206:209], v139 offset:3072
	s_add_i32 m0, s52, 0x10000
	s_add_u32 s98, s58, s46
	s_addc_u32 s99, s59, s47
	global_load_lds_dwordx4 v128, s[98:99]
	s_add_i32 m0, s52, 0x12000
	s_nop 0
	global_load_lds_dwordx4 v130, s[98:99]
	s_barrier
	s_waitcnt lgkmcnt(0)
	s_waitcnt lgkmcnt(0)
	v_mfma_f32_16x16x32_bf16 v[92:95], v[188:191], v[156:159], v[92:95]
	v_mfma_f32_16x16x32_bf16 v[88:91], v[202:205], v[156:159], v[88:91]
	v_mfma_f32_16x16x32_bf16 v[84:87], v[188:191], v[164:167], v[84:87]
	v_mfma_f32_16x16x32_bf16 v[80:83], v[202:205], v[164:167], v[80:83]
	v_mfma_f32_16x16x32_bf16 v[76:79], v[188:191], v[172:175], v[76:79]
	v_mfma_f32_16x16x32_bf16 v[72:75], v[202:205], v[172:175], v[72:75]
	v_mfma_f32_16x16x32_bf16 v[68:71], v[188:191], v[180:183], v[68:71]
	v_mfma_f32_16x16x32_bf16 v[64:67], v[202:205], v[180:183], v[64:67]
	v_mfma_f32_16x16x32_bf16 v[92:95], v[192:195], v[160:163], v[92:95]
	v_mfma_f32_16x16x32_bf16 v[88:91], v[206:209], v[160:163], v[88:91]
	v_mfma_f32_16x16x32_bf16 v[84:87], v[192:195], v[168:171], v[84:87]
	v_mfma_f32_16x16x32_bf16 v[80:83], v[206:209], v[168:171], v[80:83]
	v_mfma_f32_16x16x32_bf16 v[76:79], v[192:195], v[176:179], v[76:79]
	v_mfma_f32_16x16x32_bf16 v[72:75], v[206:209], v[176:179], v[72:75]
	v_mfma_f32_16x16x32_bf16 v[68:71], v[192:195], v[184:187], v[68:71]
	v_mfma_f32_16x16x32_bf16 v[64:67], v[206:209], v[184:187], v[64:67]
	s_barrier
	ds_read_b128 v[156:159], v136 offset:16384
	ds_read_b128 v[160:163], v136 offset:17408
	ds_read_b128 v[164:167], v135 offset:16384
	ds_read_b128 v[168:171], v135 offset:17408
	ds_read_b128 v[172:175], v134 offset:16384
	ds_read_b128 v[176:179], v134 offset:17408
	ds_read_b128 v[180:183], v133 offset:16384
	ds_read_b128 v[184:187], v133 offset:17408
	s_mov_b32 m0, s52
	s_add_u32 s98, s28, s48
	s_addc_u32 s99, s29, s49
	global_load_lds_dwordx4 v128, s[98:99]
	s_add_i32 m0, s52, 0x2000
	s_nop 0
	global_load_lds_dwordx4 v130, s[98:99]
	s_barrier
	s_waitcnt lgkmcnt(0)
	s_waitcnt lgkmcnt(0)
	v_mfma_f32_16x16x32_bf16 v[60:63], v[140:143], v[156:159], v[60:63]
	v_mfma_f32_16x16x32_bf16 v[56:59], v[148:151], v[156:159], v[56:59]
	v_mfma_f32_16x16x32_bf16 v[52:55], v[140:143], v[164:167], v[52:55]
	v_mfma_f32_16x16x32_bf16 v[48:51], v[148:151], v[164:167], v[48:51]
	v_mfma_f32_16x16x32_bf16 v[44:47], v[140:143], v[172:175], v[44:47]
	v_mfma_f32_16x16x32_bf16 v[40:43], v[148:151], v[172:175], v[40:43]
	v_mfma_f32_16x16x32_bf16 v[36:39], v[140:143], v[180:183], v[36:39]
	v_mfma_f32_16x16x32_bf16 v[32:35], v[148:151], v[180:183], v[32:35]
	v_mfma_f32_16x16x32_bf16 v[60:63], v[144:147], v[160:163], v[60:63]
	v_mfma_f32_16x16x32_bf16 v[56:59], v[152:155], v[160:163], v[56:59]
	v_mfma_f32_16x16x32_bf16 v[52:55], v[144:147], v[168:171], v[52:55]
	v_mfma_f32_16x16x32_bf16 v[48:51], v[152:155], v[168:171], v[48:51]
	v_mfma_f32_16x16x32_bf16 v[44:47], v[144:147], v[176:179], v[44:47]
	v_mfma_f32_16x16x32_bf16 v[40:43], v[152:155], v[176:179], v[40:43]
	v_mfma_f32_16x16x32_bf16 v[36:39], v[144:147], v[184:187], v[36:39]
	v_mfma_f32_16x16x32_bf16 v[32:35], v[152:155], v[184:187], v[32:35]
	s_barrier
	s_add_i32 m0, s52, 0x14000
	s_add_u32 s98, s58, s50
	s_addc_u32 s99, s59, s51
	global_load_lds_dwordx4 v128, s[98:99]
	s_add_i32 m0, s52, 0x16000
	s_nop 0
	global_load_lds_dwordx4 v130, s[98:99]
	s_waitcnt vmcnt(6)
	s_barrier
	v_mfma_f32_16x16x32_bf16 v[28:31], v[188:191], v[156:159], v[28:31]
	v_mfma_f32_16x16x32_bf16 v[24:27], v[202:205], v[156:159], v[24:27]
	v_mfma_f32_16x16x32_bf16 v[20:23], v[188:191], v[164:167], v[20:23]
	v_mfma_f32_16x16x32_bf16 v[16:19], v[202:205], v[164:167], v[16:19]
	v_mfma_f32_16x16x32_bf16 v[12:15], v[188:191], v[172:175], v[12:15]
	v_mfma_f32_16x16x32_bf16 v[8:11], v[202:205], v[172:175], v[8:11]
	v_mfma_f32_16x16x32_bf16 v[4:7], v[188:191], v[180:183], v[4:7]
	v_mfma_f32_16x16x32_bf16 v[0:3], v[202:205], v[180:183], v[0:3]
	v_mfma_f32_16x16x32_bf16 v[28:31], v[192:195], v[160:163], v[28:31]
	v_mfma_f32_16x16x32_bf16 v[24:27], v[206:209], v[160:163], v[24:27]
	v_mfma_f32_16x16x32_bf16 v[20:23], v[192:195], v[168:171], v[20:23]
	v_mfma_f32_16x16x32_bf16 v[16:19], v[206:209], v[168:171], v[16:19]
	v_mfma_f32_16x16x32_bf16 v[12:15], v[192:195], v[176:179], v[12:15]
	v_mfma_f32_16x16x32_bf16 v[8:11], v[206:209], v[176:179], v[8:11]
	v_mfma_f32_16x16x32_bf16 v[4:7], v[192:195], v[184:187], v[4:7]
	v_mfma_f32_16x16x32_bf16 v[0:3], v[206:209], v[184:187], v[0:3]
	s_barrier
	ds_read_b128 v[140:143], v138
	ds_read_b128 v[144:147], v138 offset:1024
	ds_read_b128 v[148:151], v138 offset:2048
	ds_read_b128 v[152:155], v138 offset:3072
	ds_read_b128 v[156:159], v136 offset:32768
	ds_read_b128 v[160:163], v136 offset:33792
	ds_read_b128 v[164:167], v135 offset:32768
	ds_read_b128 v[168:171], v135 offset:33792
	ds_read_b128 v[172:175], v134 offset:32768
	ds_read_b128 v[176:179], v134 offset:33792
	ds_read_b128 v[180:183], v133 offset:32768
	ds_read_b128 v[184:187], v133 offset:33792
	s_add_i32 m0, s52, 0x4000
	s_add_u32 s98, s28, s54
	s_addc_u32 s99, s29, s55
	global_load_lds_dwordx4 v128, s[98:99]
	s_add_i32 m0, s52, 0x6000
	s_nop 0
	global_load_lds_dwordx4 v130, s[98:99]
	s_waitcnt lgkmcnt(8)
	s_barrier
	s_waitcnt lgkmcnt(0)
	s_waitcnt lgkmcnt(0)
	v_mfma_f32_16x16x32_bf16 v[124:127], v[140:143], v[156:159], v[124:127]
	v_mfma_f32_16x16x32_bf16 v[120:123], v[148:151], v[156:159], v[120:123]
	v_mfma_f32_16x16x32_bf16 v[116:119], v[140:143], v[164:167], v[116:119]
	v_mfma_f32_16x16x32_bf16 v[112:115], v[148:151], v[164:167], v[112:115]
	v_mfma_f32_16x16x32_bf16 v[108:111], v[140:143], v[172:175], v[108:111]
	v_mfma_f32_16x16x32_bf16 v[104:107], v[148:151], v[172:175], v[104:107]
	v_mfma_f32_16x16x32_bf16 v[100:103], v[140:143], v[180:183], v[100:103]
	v_mfma_f32_16x16x32_bf16 v[96:99], v[148:151], v[180:183], v[96:99]
	v_mfma_f32_16x16x32_bf16 v[124:127], v[144:147], v[160:163], v[124:127]
	v_mfma_f32_16x16x32_bf16 v[120:123], v[152:155], v[160:163], v[120:123]
	v_mfma_f32_16x16x32_bf16 v[116:119], v[144:147], v[168:171], v[116:119]
	v_mfma_f32_16x16x32_bf16 v[112:115], v[152:155], v[168:171], v[112:115]
	v_mfma_f32_16x16x32_bf16 v[108:111], v[144:147], v[176:179], v[108:111]
	v_mfma_f32_16x16x32_bf16 v[104:107], v[152:155], v[176:179], v[104:107]
	v_mfma_f32_16x16x32_bf16 v[100:103], v[144:147], v[184:187], v[100:103]
	v_mfma_f32_16x16x32_bf16 v[96:99], v[152:155], v[184:187], v[96:99]
	s_barrier
	ds_read_b128 v[188:191], v137
	ds_read_b128 v[192:195], v137 offset:1024
	ds_read_b128 v[202:205], v137 offset:2048
	ds_read_b128 v[206:209], v137 offset:3072
	s_mov_b32 m0, s7
	s_add_u32 s98, s58, s68
	s_addc_u32 s99, s59, s69
	global_load_lds_dwordx4 v128, s[98:99]
	s_mov_b32 m0, s53
	s_nop 0
	global_load_lds_dwordx4 v130, s[98:99]
	s_barrier
	s_waitcnt lgkmcnt(0)
	s_waitcnt lgkmcnt(0)
	v_mfma_f32_16x16x32_bf16 v[92:95], v[188:191], v[156:159], v[92:95]
	v_mfma_f32_16x16x32_bf16 v[88:91], v[202:205], v[156:159], v[88:91]
	v_mfma_f32_16x16x32_bf16 v[84:87], v[188:191], v[164:167], v[84:87]
	v_mfma_f32_16x16x32_bf16 v[80:83], v[202:205], v[164:167], v[80:83]
	v_mfma_f32_16x16x32_bf16 v[76:79], v[188:191], v[172:175], v[76:79]
	v_mfma_f32_16x16x32_bf16 v[72:75], v[202:205], v[172:175], v[72:75]
	v_mfma_f32_16x16x32_bf16 v[68:71], v[188:191], v[180:183], v[68:71]
	v_mfma_f32_16x16x32_bf16 v[64:67], v[202:205], v[180:183], v[64:67]
	v_mfma_f32_16x16x32_bf16 v[92:95], v[192:195], v[160:163], v[92:95]
	v_mfma_f32_16x16x32_bf16 v[88:91], v[206:209], v[160:163], v[88:91]
	v_mfma_f32_16x16x32_bf16 v[84:87], v[192:195], v[168:171], v[84:87]
	v_mfma_f32_16x16x32_bf16 v[80:83], v[206:209], v[168:171], v[80:83]
	v_mfma_f32_16x16x32_bf16 v[76:79], v[192:195], v[176:179], v[76:79]
	v_mfma_f32_16x16x32_bf16 v[72:75], v[206:209], v[176:179], v[72:75]
	v_mfma_f32_16x16x32_bf16 v[68:71], v[192:195], v[184:187], v[68:71]
	v_mfma_f32_16x16x32_bf16 v[64:67], v[206:209], v[184:187], v[64:67]
	v_mov_b32_e32 v210, v130
	s_barrier
	ds_read_b128 v[156:159], v136 offset:49152
	ds_read_b128 v[160:163], v136 offset:50176
	ds_read_b128 v[164:167], v135 offset:49152
	ds_read_b128 v[168:171], v135 offset:50176
	ds_read_b128 v[172:175], v134 offset:49152
	ds_read_b128 v[176:179], v134 offset:50176
	ds_read_b128 v[180:183], v133 offset:49152
	ds_read_b128 v[184:187], v133 offset:50176
	v_mov_b32_e32 v211, v197
	s_mov_b32 m0, s9
	s_add_u32 s98, s28, s70
	s_addc_u32 s99, s29, s71
	global_load_lds_dwordx4 v128, s[98:99]
	s_mov_b32 m0, s33
	s_nop 0
	global_load_lds_dwordx4 v130, s[98:99]
	s_barrier
	s_waitcnt lgkmcnt(0)
	s_waitcnt lgkmcnt(0)
	v_mfma_f32_16x16x32_bf16 v[60:63], v[140:143], v[156:159], v[60:63]
	v_mfma_f32_16x16x32_bf16 v[56:59], v[148:151], v[156:159], v[56:59]
	v_mfma_f32_16x16x32_bf16 v[52:55], v[140:143], v[164:167], v[52:55]
	v_mfma_f32_16x16x32_bf16 v[48:51], v[148:151], v[164:167], v[48:51]
	v_mfma_f32_16x16x32_bf16 v[44:47], v[140:143], v[172:175], v[44:47]
	v_mfma_f32_16x16x32_bf16 v[40:43], v[148:151], v[172:175], v[40:43]
	v_mfma_f32_16x16x32_bf16 v[36:39], v[140:143], v[180:183], v[36:39]
	v_mfma_f32_16x16x32_bf16 v[32:35], v[148:151], v[180:183], v[32:35]
	v_mfma_f32_16x16x32_bf16 v[60:63], v[144:147], v[160:163], v[60:63]
	v_mfma_f32_16x16x32_bf16 v[56:59], v[152:155], v[160:163], v[56:59]
	v_mfma_f32_16x16x32_bf16 v[52:55], v[144:147], v[168:171], v[52:55]
	v_mfma_f32_16x16x32_bf16 v[48:51], v[152:155], v[168:171], v[48:51]
	v_mfma_f32_16x16x32_bf16 v[44:47], v[144:147], v[176:179], v[44:47]
	v_mfma_f32_16x16x32_bf16 v[40:43], v[152:155], v[176:179], v[40:43]
	v_mfma_f32_16x16x32_bf16 v[36:39], v[144:147], v[184:187], v[36:39]
	v_mfma_f32_16x16x32_bf16 v[32:35], v[152:155], v[184:187], v[32:35]
	s_barrier
	v_mov_b32_e32 v196, v128
	s_mov_b32 m0, s65
	s_add_u32 s98, s58, s72
	s_addc_u32 s99, s59, s73
	global_load_lds_dwordx4 v128, s[98:99]
	s_mov_b32 m0, s66
	s_nop 0
	global_load_lds_dwordx4 v130, s[98:99]
	s_waitcnt vmcnt(6)
	s_barrier
	v_mfma_f32_16x16x32_bf16 v[28:31], v[188:191], v[156:159], v[28:31]
	v_mfma_f32_16x16x32_bf16 v[24:27], v[202:205], v[156:159], v[24:27]
	v_mfma_f32_16x16x32_bf16 v[20:23], v[188:191], v[164:167], v[20:23]
	v_mfma_f32_16x16x32_bf16 v[16:19], v[202:205], v[164:167], v[16:19]
	v_mfma_f32_16x16x32_bf16 v[12:15], v[188:191], v[172:175], v[12:15]
	v_mfma_f32_16x16x32_bf16 v[8:11], v[202:205], v[172:175], v[8:11]
	v_mfma_f32_16x16x32_bf16 v[4:7], v[188:191], v[180:183], v[4:7]
	v_mfma_f32_16x16x32_bf16 v[0:3], v[202:205], v[180:183], v[0:3]
	v_mfma_f32_16x16x32_bf16 v[28:31], v[192:195], v[160:163], v[28:31]
	v_mfma_f32_16x16x32_bf16 v[24:27], v[206:209], v[160:163], v[24:27]
	v_mfma_f32_16x16x32_bf16 v[20:23], v[192:195], v[168:171], v[20:23]
	v_mfma_f32_16x16x32_bf16 v[16:19], v[206:209], v[168:171], v[16:19]
	v_mfma_f32_16x16x32_bf16 v[12:15], v[192:195], v[176:179], v[12:15]
	v_mfma_f32_16x16x32_bf16 v[8:11], v[206:209], v[176:179], v[8:11]
	v_mfma_f32_16x16x32_bf16 v[4:7], v[192:195], v[184:187], v[4:7]
	v_mfma_f32_16x16x32_bf16 v[0:3], v[206:209], v[184:187], v[0:3]
	s_add_i32 s38, s38, 2
	s_add_u32 s56, s56, 0x100
	s_addc_u32 s57, s57, 0
	s_cmp_lt_u32 s38, 28
	s_barrier
	s_cbranch_scc1 .LBB0_192
	s_lshl_b64 s[4:5], s[10:11], 12
	v_readlane_b32 s10, v254, 12
	v_readlane_b32 s11, v254, 13
	s_add_u32 s4, s10, s4
	s_addc_u32 s5, s11, s5
	ds_read_b128 v[140:143], v129
	ds_read_b128 v[144:147], v129 offset:1024
	ds_read_b128 v[148:151], v129 offset:2048
	ds_read_b128 v[152:155], v129 offset:3072
	ds_read_b128 v[156:159], v136
	ds_read_b128 v[160:163], v136 offset:1024
	ds_read_b128 v[164:167], v135
	ds_read_b128 v[168:171], v135 offset:1024
	ds_read_b128 v[172:175], v134
	ds_read_b128 v[176:179], v134 offset:1024
	ds_read_b128 v[180:183], v133
	ds_read_b128 v[184:187], v133 offset:1024
	v_mov_b32_e32 v129, v197
	v_lshl_add_u64 v[128:129], s[4:5], 0, v[128:129]
	s_mov_b64 s[10:11], 0xf80
	s_mov_b32 m0, s40
	v_lshl_add_u64 v[128:129], v[128:129], 0, s[10:11]
	v_mov_b32_e32 v131, v197
	global_load_lds_dwordx4 v[128:129], off
	v_lshl_add_u64 v[128:129], s[4:5], 0, v[130:131]
	v_lshl_add_u64 v[128:129], v[128:129], 0, s[10:11]
	s_mov_b32 m0, s39
	s_nop 0
	global_load_lds_dwordx4 v[128:129], off
	s_barrier
	s_waitcnt lgkmcnt(0)
	s_waitcnt lgkmcnt(0)
	v_mfma_f32_16x16x32_bf16 v[124:127], v[140:143], v[156:159], v[124:127]
	v_mfma_f32_16x16x32_bf16 v[116:119], v[140:143], v[164:167], v[116:119]
	v_mfma_f32_16x16x32_bf16 v[112:115], v[148:151], v[164:167], v[112:115]
	v_mfma_f32_16x16x32_bf16 v[108:111], v[140:143], v[172:175], v[108:111]
	v_mfma_f32_16x16x32_bf16 v[104:107], v[148:151], v[172:175], v[104:107]
	v_mfma_f32_16x16x32_bf16 v[100:103], v[140:143], v[180:183], v[100:103]
	v_mfma_f32_16x16x32_bf16 v[96:99], v[148:151], v[180:183], v[96:99]
	v_mfma_f32_16x16x32_bf16 v[124:127], v[144:147], v[160:163], v[124:127]
	v_mfma_f32_16x16x32_bf16 v[120:123], v[148:151], v[156:159], v[120:123]
	v_mfma_f32_16x16x32_bf16 v[116:119], v[144:147], v[168:171], v[116:119]
	v_mfma_f32_16x16x32_bf16 v[112:115], v[152:155], v[168:171], v[112:115]
	v_mfma_f32_16x16x32_bf16 v[108:111], v[144:147], v[176:179], v[108:111]
	v_mfma_f32_16x16x32_bf16 v[104:107], v[152:155], v[176:179], v[104:107]
	v_mfma_f32_16x16x32_bf16 v[100:103], v[144:147], v[184:187], v[100:103]
	v_mfma_f32_16x16x32_bf16 v[96:99], v[152:155], v[184:187], v[96:99]
	v_mfma_f32_16x16x32_bf16 v[128:131], v[152:155], v[160:163], v[120:123]
	s_barrier
	s_nop 0
	ds_read_b128 v[120:123], v139
	ds_read_b128 v[188:191], v139 offset:1024
	ds_read_b128 v[192:195], v139 offset:2048
	ds_read_b128 v[202:205], v139 offset:3072
	s_barrier
	s_waitcnt lgkmcnt(0)
	s_waitcnt lgkmcnt(0)
	v_mfma_f32_16x16x32_bf16 v[76:79], v[120:123], v[172:175], v[76:79]
	v_mfma_f32_16x16x32_bf16 v[68:71], v[120:123], v[180:183], v[68:71]
	v_mfma_f32_16x16x32_bf16 v[64:67], v[192:195], v[180:183], v[64:67]
	v_mfma_f32_16x16x32_bf16 v[92:95], v[120:123], v[156:159], v[92:95]
	v_mfma_f32_16x16x32_bf16 v[88:91], v[192:195], v[156:159], v[88:91]
	v_mfma_f32_16x16x32_bf16 v[84:87], v[120:123], v[164:167], v[84:87]
	v_mfma_f32_16x16x32_bf16 v[80:83], v[192:195], v[164:167], v[80:83]
	v_mfma_f32_16x16x32_bf16 v[76:79], v[188:191], v[176:179], v[76:79]
	v_mfma_f32_16x16x32_bf16 v[72:75], v[192:195], v[172:175], v[72:75]
	v_mfma_f32_16x16x32_bf16 v[68:71], v[188:191], v[184:187], v[68:71]
	v_mfma_f32_16x16x32_bf16 v[64:67], v[202:205], v[184:187], v[64:67]
	v_mfma_f32_16x16x32_bf16 v[206:209], v[188:191], v[160:163], v[92:95]
	v_mfma_f32_16x16x32_bf16 v[156:159], v[202:205], v[160:163], v[88:91]
	v_mfma_f32_16x16x32_bf16 v[160:163], v[188:191], v[168:171], v[84:87]
	v_mfma_f32_16x16x32_bf16 v[164:167], v[202:205], v[168:171], v[80:83]
	v_mfma_f32_16x16x32_bf16 v[168:171], v[202:205], v[176:179], v[72:75]
	s_barrier
	s_nop 0
	ds_read_b128 v[72:75], v136 offset:16384
	ds_read_b128 v[80:83], v136 offset:17408
	ds_read_b128 v[84:87], v135 offset:16384
	ds_read_b128 v[88:91], v135 offset:17408
	ds_read_b128 v[92:95], v134 offset:16384
	ds_read_b128 v[172:175], v134 offset:17408
	ds_read_b128 v[176:179], v133 offset:16384
	ds_read_b128 v[180:183], v133 offset:17408
	s_waitcnt vmcnt(4)
	s_barrier
	s_waitcnt lgkmcnt(0)
	s_waitcnt lgkmcnt(0)
	v_mfma_f32_16x16x32_bf16 v[60:63], v[140:143], v[72:75], v[60:63]
	v_mfma_f32_16x16x32_bf16 v[52:55], v[140:143], v[84:87], v[52:55]
	v_mfma_f32_16x16x32_bf16 v[48:51], v[148:151], v[84:87], v[48:51]
	v_mfma_f32_16x16x32_bf16 v[44:47], v[140:143], v[92:95], v[44:47]
	v_mfma_f32_16x16x32_bf16 v[40:43], v[148:151], v[92:95], v[40:43]
	v_mfma_f32_16x16x32_bf16 v[36:39], v[140:143], v[176:179], v[36:39]
	v_mfma_f32_16x16x32_bf16 v[32:35], v[148:151], v[176:179], v[32:35]
	v_mfma_f32_16x16x32_bf16 v[60:63], v[144:147], v[80:83], v[60:63]
	v_mfma_f32_16x16x32_bf16 v[56:59], v[148:151], v[72:75], v[56:59]
	v_mfma_f32_16x16x32_bf16 v[52:55], v[144:147], v[88:91], v[52:55]
	v_mfma_f32_16x16x32_bf16 v[48:51], v[152:155], v[88:91], v[48:51]
	v_mfma_f32_16x16x32_bf16 v[44:47], v[144:147], v[172:175], v[44:47]
	v_mfma_f32_16x16x32_bf16 v[40:43], v[152:155], v[172:175], v[40:43]
	v_mfma_f32_16x16x32_bf16 v[36:39], v[144:147], v[180:183], v[36:39]
	v_mfma_f32_16x16x32_bf16 v[32:35], v[152:155], v[180:183], v[32:35]
	v_mfma_f32_16x16x32_bf16 v[184:187], v[152:155], v[80:83], v[56:59]
	v_mfma_f32_16x16x32_bf16 v[12:15], v[120:123], v[92:95], v[12:15]
	v_mfma_f32_16x16x32_bf16 v[4:7], v[120:123], v[176:179], v[4:7]
	v_mfma_f32_16x16x32_bf16 v[0:3], v[192:195], v[176:179], v[0:3]
	v_mfma_f32_16x16x32_bf16 v[28:31], v[120:123], v[72:75], v[28:31]
	v_mfma_f32_16x16x32_bf16 v[24:27], v[192:195], v[72:75], v[24:27]
	v_mfma_f32_16x16x32_bf16 v[20:23], v[120:123], v[84:87], v[20:23]
	v_mfma_f32_16x16x32_bf16 v[16:19], v[192:195], v[84:87], v[16:19]
	v_mfma_f32_16x16x32_bf16 v[12:15], v[188:191], v[172:175], v[12:15]
	v_mfma_f32_16x16x32_bf16 v[8:11], v[192:195], v[92:95], v[8:11]
	v_mfma_f32_16x16x32_bf16 v[4:7], v[188:191], v[180:183], v[4:7]
	v_mfma_f32_16x16x32_bf16 v[0:3], v[202:205], v[180:183], v[0:3]
	v_mfma_f32_16x16x32_bf16 v[140:143], v[188:191], v[80:83], v[28:31]
	v_mfma_f32_16x16x32_bf16 v[144:147], v[202:205], v[80:83], v[24:27]
	v_mfma_f32_16x16x32_bf16 v[148:151], v[188:191], v[88:91], v[20:23]
	v_mfma_f32_16x16x32_bf16 v[152:155], v[202:205], v[88:91], v[16:19]
	v_mfma_f32_16x16x32_bf16 v[172:175], v[202:205], v[172:175], v[8:11]
	s_barrier
	s_nop 0
	ds_read_b128 v[8:11], v138
	ds_read_b128 v[16:19], v138 offset:1024
	ds_read_b128 v[176:179], v138 offset:2048
	ds_read_b128 v[180:183], v138 offset:3072
	ds_read_b128 v[20:23], v136 offset:32768
	ds_read_b128 v[24:27], v136 offset:33792
	ds_read_b128 v[28:31], v135 offset:32768
	ds_read_b128 v[56:59], v135 offset:33792
	ds_read_b128 v[188:191], v134 offset:32768
	ds_read_b128 v[192:195], v134 offset:33792
	ds_read_b128 v[202:205], v133 offset:32768
	ds_read_b128 v[210:213], v133 offset:33792
	s_waitcnt vmcnt(2)
	s_barrier
	s_waitcnt lgkmcnt(0)
	s_waitcnt lgkmcnt(0)
	v_mfma_f32_16x16x32_bf16 v[72:75], v[8:11], v[20:23], v[124:127]
	v_mfma_f32_16x16x32_bf16 v[120:123], v[16:19], v[24:27], v[72:75]
	v_mfma_f32_16x16x32_bf16 v[72:75], v[176:179], v[20:23], v[128:131]
	v_mfma_f32_16x16x32_bf16 v[124:127], v[180:183], v[24:27], v[72:75]
	v_mfma_f32_16x16x32_bf16 v[72:75], v[8:11], v[28:31], v[116:119]
	v_mfma_f32_16x16x32_bf16 v[116:119], v[16:19], v[56:59], v[72:75]
	v_mfma_f32_16x16x32_bf16 v[72:75], v[176:179], v[28:31], v[112:115]
	v_mfma_f32_16x16x32_bf16 v[112:115], v[180:183], v[56:59], v[72:75]
	v_mfma_f32_16x16x32_bf16 v[72:75], v[8:11], v[188:191], v[108:111]
	v_mfma_f32_16x16x32_bf16 v[88:91], v[16:19], v[192:195], v[72:75]
	v_mfma_f32_16x16x32_bf16 v[72:75], v[176:179], v[188:191], v[104:107]
	v_mfma_f32_16x16x32_bf16 v[92:95], v[180:183], v[192:195], v[72:75]
	v_mfma_f32_16x16x32_bf16 v[72:75], v[8:11], v[202:205], v[100:103]
	v_mfma_f32_16x16x32_bf16 v[84:87], v[16:19], v[210:213], v[72:75]
	v_mfma_f32_16x16x32_bf16 v[72:75], v[176:179], v[202:205], v[96:99]
	v_mfma_f32_16x16x32_bf16 v[80:83], v[180:183], v[210:213], v[72:75]
	s_barrier
	ds_read_b128 v[128:131], v137
	ds_read_b128 v[214:217], v137 offset:1024
	ds_read_b128 v[218:221], v137 offset:2048
	ds_read_b128 v[222:225], v137 offset:3072
	s_waitcnt vmcnt(0)
	s_barrier
	s_waitcnt lgkmcnt(0)
	s_waitcnt lgkmcnt(0)
	v_mfma_f32_16x16x32_bf16 v[72:75], v[128:131], v[20:23], v[206:209]
	v_mfma_f32_16x16x32_bf16 v[20:23], v[218:221], v[20:23], v[156:159]
	v_mfma_f32_16x16x32_bf16 v[108:111], v[222:225], v[24:27], v[20:23]
	v_mfma_f32_16x16x32_bf16 v[20:23], v[128:131], v[28:31], v[160:163]
	v_mfma_f32_16x16x32_bf16 v[100:103], v[214:217], v[56:59], v[20:23]
	v_mfma_f32_16x16x32_bf16 v[20:23], v[218:221], v[28:31], v[164:167]
	v_mfma_f32_16x16x32_bf16 v[96:99], v[222:225], v[56:59], v[20:23]
	v_mfma_f32_16x16x32_bf16 v[20:23], v[128:131], v[188:191], v[76:79]
	v_mfma_f32_16x16x32_bf16 v[104:107], v[214:217], v[24:27], v[72:75]
	v_mfma_f32_16x16x32_bf16 v[72:75], v[214:217], v[192:195], v[20:23]
	v_mfma_f32_16x16x32_bf16 v[20:23], v[218:221], v[188:191], v[168:171]
	v_mfma_f32_16x16x32_bf16 v[76:79], v[222:225], v[192:195], v[20:23]
	v_mfma_f32_16x16x32_bf16 v[20:23], v[128:131], v[202:205], v[68:71]
	v_mfma_f32_16x16x32_bf16 v[68:71], v[214:217], v[210:213], v[20:23]
	v_mfma_f32_16x16x32_bf16 v[20:23], v[218:221], v[202:205], v[64:67]
	v_mfma_f32_16x16x32_bf16 v[64:67], v[222:225], v[210:213], v[20:23]
	s_barrier
	ds_read_b128 v[156:159], v136 offset:49152
	ds_read_b128 v[136:139], v136 offset:50176
	ds_read_b128 v[160:163], v135 offset:49152
	ds_read_b128 v[164:167], v135 offset:50176
	ds_read_b128 v[168:171], v134 offset:49152
	ds_read_b128 v[188:191], v134 offset:50176
	ds_read_b128 v[192:195], v133 offset:49152
	ds_read_b128 v[202:205], v133 offset:50176
	s_barrier
	s_waitcnt lgkmcnt(0)
	s_waitcnt lgkmcnt(0)
	v_mfma_f32_16x16x32_bf16 v[20:23], v[8:11], v[156:159], v[60:63]
	v_mfma_f32_16x16x32_bf16 v[56:59], v[16:19], v[136:139], v[20:23]
	v_mfma_f32_16x16x32_bf16 v[20:23], v[176:179], v[156:159], v[184:187]
	v_mfma_f32_16x16x32_bf16 v[60:63], v[180:183], v[136:139], v[20:23]
	v_mfma_f32_16x16x32_bf16 v[20:23], v[8:11], v[160:163], v[52:55]
	v_mfma_f32_16x16x32_bf16 v[52:55], v[16:19], v[164:167], v[20:23]
	v_mfma_f32_16x16x32_bf16 v[20:23], v[176:179], v[160:163], v[48:51]
	v_mfma_f32_16x16x32_bf16 v[48:51], v[180:183], v[164:167], v[20:23]
	v_mfma_f32_16x16x32_bf16 v[20:23], v[8:11], v[168:171], v[44:47]
	v_mfma_f32_16x16x32_bf16 v[24:27], v[16:19], v[188:191], v[20:23]
	v_mfma_f32_16x16x32_bf16 v[20:23], v[176:179], v[168:171], v[40:43]
	v_mfma_f32_16x16x32_bf16 v[8:11], v[8:11], v[192:195], v[36:39]
	v_mfma_f32_16x16x32_bf16 v[28:31], v[180:183], v[188:191], v[20:23]
	v_mfma_f32_16x16x32_bf16 v[20:23], v[16:19], v[202:205], v[8:11]
	v_mfma_f32_16x16x32_bf16 v[8:11], v[176:179], v[192:195], v[32:35]
	v_mfma_f32_16x16x32_bf16 v[16:19], v[180:183], v[202:205], v[8:11]
	v_mfma_f32_16x16x32_bf16 v[8:11], v[128:131], v[156:159], v[140:143]
	v_mfma_f32_16x16x32_bf16 v[40:43], v[214:217], v[136:139], v[8:11]
	v_mfma_f32_16x16x32_bf16 v[8:11], v[218:221], v[156:159], v[144:147]
	v_mfma_f32_16x16x32_bf16 v[44:47], v[222:225], v[136:139], v[8:11]
	v_mfma_f32_16x16x32_bf16 v[8:11], v[128:131], v[160:163], v[148:151]
	v_mfma_f32_16x16x32_bf16 v[36:39], v[214:217], v[164:167], v[8:11]
	v_mfma_f32_16x16x32_bf16 v[8:11], v[218:221], v[160:163], v[152:155]
	v_mfma_f32_16x16x32_bf16 v[32:35], v[222:225], v[164:167], v[8:11]
	v_mfma_f32_16x16x32_bf16 v[8:11], v[128:131], v[168:171], v[12:15]
	v_mfma_f32_16x16x32_bf16 v[12:15], v[218:221], v[168:171], v[172:175]
	v_mfma_f32_16x16x32_bf16 v[4:7], v[128:131], v[192:195], v[4:7]
	v_mfma_f32_16x16x32_bf16 v[0:3], v[218:221], v[192:195], v[0:3]
	v_mfma_f32_16x16x32_bf16 v[8:11], v[214:217], v[188:191], v[8:11]
	v_mfma_f32_16x16x32_bf16 v[12:15], v[222:225], v[188:191], v[12:15]
	v_mfma_f32_16x16x32_bf16 v[4:7], v[214:217], v[202:205], v[4:7]
	v_mfma_f32_16x16x32_bf16 v[0:3], v[222:225], v[202:205], v[0:3]
	s_movk_i32 s4, 0x100
	v_cmp_gt_u32_e32 vcc, s4, v132
	s_barrier
	s_and_saveexec_b64 s[4:5], vcc
	s_cbranch_execz .LBB0_195
	s_barrier

.Lh1_loop:
	ds_read_b128 v[140:143], v129
	ds_read_b128 v[144:147], v129 offset:1024
	ds_read_b128 v[148:151], v129 offset:2048
	ds_read_b128 v[152:155], v129 offset:3072
	s_add_u32 s28, s60, s56
	s_addc_u32 s29, s61, s57
	ds_read_b128 v[156:159], v136
	ds_read_b128 v[160:163], v136 offset:1024
	ds_read_b128 v[164:167], v135
	ds_read_b128 v[168:171], v135 offset:1024
	ds_read_b128 v[172:175], v134
	ds_read_b128 v[176:179], v134 offset:1024
	ds_read_b128 v[180:183], v133
	ds_read_b128 v[184:187], v133 offset:1024
	s_add_i32 s40, s53, 0xc000
	s_mov_b32 m0, s40
	s_add_i32 s39, s53, 0xe000
	s_mov_b32 m0, s39
	s_nop 0
	s_waitcnt lgkmcnt(8)
	s_barrier
	s_waitcnt lgkmcnt(0)
	v_mfma_f32_16x16x32_bf16 v[124:127], v[140:143], v[156:159], v[124:127]
	v_mfma_f32_16x16x32_bf16 v[120:123], v[148:151], v[156:159], v[120:123]
	v_mfma_f32_16x16x32_bf16 v[116:119], v[140:143], v[164:167], v[116:119]
	v_mfma_f32_16x16x32_bf16 v[112:115], v[148:151], v[164:167], v[112:115]
	v_mfma_f32_16x16x32_bf16 v[108:111], v[140:143], v[172:175], v[108:111]
	v_mfma_f32_16x16x32_bf16 v[104:107], v[148:151], v[172:175], v[104:107]
	v_mfma_f32_16x16x32_bf16 v[100:103], v[140:143], v[180:183], v[100:103]
	v_mfma_f32_16x16x32_bf16 v[96:99], v[148:151], v[180:183], v[96:99]
	v_mfma_f32_16x16x32_bf16 v[124:127], v[144:147], v[160:163], v[124:127]
	v_mfma_f32_16x16x32_bf16 v[120:123], v[152:155], v[160:163], v[120:123]
	v_mfma_f32_16x16x32_bf16 v[116:119], v[144:147], v[168:171], v[116:119]
	v_mfma_f32_16x16x32_bf16 v[112:115], v[152:155], v[168:171], v[112:115]
	v_mfma_f32_16x16x32_bf16 v[108:111], v[144:147], v[176:179], v[108:111]
	v_mfma_f32_16x16x32_bf16 v[104:107], v[152:155], v[176:179], v[104:107]
	v_mfma_f32_16x16x32_bf16 v[100:103], v[144:147], v[184:187], v[100:103]
	v_mfma_f32_16x16x32_bf16 v[96:99], v[152:155], v[184:187], v[96:99]
	s_barrier
	s_add_u32 s62, s60, s36
	s_addc_u32 s63, s61, s37
	ds_read_b128 v[188:191], v139
	ds_read_b128 v[192:195], v139 offset:1024
	ds_read_b128 v[202:205], v139 offset:2048
	ds_read_b128 v[206:209], v139 offset:3072
	s_mov_b32 m0, s68
	s_add_u32 s98, s62, s46
	s_addc_u32 s99, s63, s47
	global_load_lds_dwordx4 v128, s[98:99]
	s_mov_b32 m0, s69
	s_nop 0
	global_load_lds_dwordx4 v130, s[98:99]
	s_barrier
	s_waitcnt lgkmcnt(0)
	v_mfma_f32_16x16x32_bf16 v[92:95], v[188:191], v[156:159], v[92:95]
	v_mfma_f32_16x16x32_bf16 v[88:91], v[202:205], v[156:159], v[88:91]
	v_mfma_f32_16x16x32_bf16 v[84:87], v[188:191], v[164:167], v[84:87]
	v_mfma_f32_16x16x32_bf16 v[80:83], v[202:205], v[164:167], v[80:83]
	v_mfma_f32_16x16x32_bf16 v[76:79], v[188:191], v[172:175], v[76:79]
	v_mfma_f32_16x16x32_bf16 v[72:75], v[202:205], v[172:175], v[72:75]
	v_mfma_f32_16x16x32_bf16 v[68:71], v[188:191], v[180:183], v[68:71]
	v_mfma_f32_16x16x32_bf16 v[64:67], v[202:205], v[180:183], v[64:67]
	v_mfma_f32_16x16x32_bf16 v[92:95], v[192:195], v[160:163], v[92:95]
	v_mfma_f32_16x16x32_bf16 v[88:91], v[206:209], v[160:163], v[88:91]
	v_mfma_f32_16x16x32_bf16 v[84:87], v[192:195], v[168:171], v[84:87]
	v_mfma_f32_16x16x32_bf16 v[80:83], v[206:209], v[168:171], v[80:83]
	v_mfma_f32_16x16x32_bf16 v[76:79], v[192:195], v[176:179], v[76:79]
	v_mfma_f32_16x16x32_bf16 v[72:75], v[206:209], v[176:179], v[72:75]
	v_mfma_f32_16x16x32_bf16 v[68:71], v[192:195], v[184:187], v[68:71]
	v_mfma_f32_16x16x32_bf16 v[64:67], v[206:209], v[184:187], v[64:67]
	s_barrier
	s_mov_b32 m0, s53
	s_add_u32 s98, s28, s48
	s_addc_u32 s99, s29, s49
	global_load_lds_dwordx4 v128, s[98:99]
	s_mov_b32 m0, s11
	s_nop 0
	global_load_lds_dwordx4 v130, s[98:99]
	s_waitcnt vmcnt(4)
	s_barrier
	s_mov_b32 m0, s9
	s_add_u32 s98, s62, s50
	s_addc_u32 s99, s63, s51
	global_load_lds_dwordx4 v128, s[98:99]
	s_mov_b32 m0, s70
	s_nop 0
	global_load_lds_dwordx4 v130, s[98:99]
	s_barrier
	ds_read_b128 v[140:143], v138
	ds_read_b128 v[144:147], v138 offset:1024
	ds_read_b128 v[148:151], v138 offset:2048
	ds_read_b128 v[152:155], v138 offset:3072
	ds_read_b128 v[156:159], v136 offset:32768
	ds_read_b128 v[160:163], v136 offset:33792
	ds_read_b128 v[164:167], v135 offset:32768
	ds_read_b128 v[168:171], v135 offset:33792
	ds_read_b128 v[172:175], v134 offset:32768
	ds_read_b128 v[176:179], v134 offset:33792
	ds_read_b128 v[180:183], v133 offset:32768
	ds_read_b128 v[184:187], v133 offset:33792
	s_mov_b32 m0, s71
	s_mov_b32 m0, s72
	s_nop 0
	s_waitcnt lgkmcnt(8)
	s_barrier
	s_waitcnt lgkmcnt(0)
	v_mfma_f32_16x16x32_bf16 v[124:127], v[140:143], v[156:159], v[124:127]
	v_mfma_f32_16x16x32_bf16 v[120:123], v[148:151], v[156:159], v[120:123]
	v_mfma_f32_16x16x32_bf16 v[116:119], v[140:143], v[164:167], v[116:119]
	v_mfma_f32_16x16x32_bf16 v[112:115], v[148:151], v[164:167], v[112:115]
	v_mfma_f32_16x16x32_bf16 v[108:111], v[140:143], v[172:175], v[108:111]
	v_mfma_f32_16x16x32_bf16 v[104:107], v[148:151], v[172:175], v[104:107]
	v_mfma_f32_16x16x32_bf16 v[100:103], v[140:143], v[180:183], v[100:103]
	v_mfma_f32_16x16x32_bf16 v[96:99], v[148:151], v[180:183], v[96:99]
	v_mfma_f32_16x16x32_bf16 v[124:127], v[144:147], v[160:163], v[124:127]
	v_mfma_f32_16x16x32_bf16 v[120:123], v[152:155], v[160:163], v[120:123]
	v_mfma_f32_16x16x32_bf16 v[116:119], v[144:147], v[168:171], v[116:119]
	v_mfma_f32_16x16x32_bf16 v[112:115], v[152:155], v[168:171], v[112:115]
	v_mfma_f32_16x16x32_bf16 v[108:111], v[144:147], v[176:179], v[108:111]
	v_mfma_f32_16x16x32_bf16 v[104:107], v[152:155], v[176:179], v[104:107]
	v_mfma_f32_16x16x32_bf16 v[100:103], v[144:147], v[184:187], v[100:103]
	v_mfma_f32_16x16x32_bf16 v[96:99], v[152:155], v[184:187], v[96:99]
	s_barrier
	ds_read_b128 v[188:191], v137
	ds_read_b128 v[192:195], v137 offset:1024
	ds_read_b128 v[202:205], v137 offset:2048
	ds_read_b128 v[206:209], v137 offset:3072
	s_mov_b32 m0, s66
	s_add_u32 s98, s62, s90
	s_addc_u32 s99, s63, s91
	global_load_lds_dwordx4 v128, s[98:99]
	s_mov_b32 m0, s64
	s_nop 0
	global_load_lds_dwordx4 v130, s[98:99]
	s_barrier
	s_waitcnt lgkmcnt(0)
	v_mfma_f32_16x16x32_bf16 v[92:95], v[188:191], v[156:159], v[92:95]
	v_mfma_f32_16x16x32_bf16 v[88:91], v[202:205], v[156:159], v[88:91]
	v_mfma_f32_16x16x32_bf16 v[84:87], v[188:191], v[164:167], v[84:87]
	v_mfma_f32_16x16x32_bf16 v[80:83], v[202:205], v[164:167], v[80:83]
	v_mfma_f32_16x16x32_bf16 v[76:79], v[188:191], v[172:175], v[76:79]
	v_mfma_f32_16x16x32_bf16 v[72:75], v[202:205], v[172:175], v[72:75]
	v_mfma_f32_16x16x32_bf16 v[68:71], v[188:191], v[180:183], v[68:71]
	v_mfma_f32_16x16x32_bf16 v[64:67], v[202:205], v[180:183], v[64:67]
	v_mfma_f32_16x16x32_bf16 v[92:95], v[192:195], v[160:163], v[92:95]
	v_mfma_f32_16x16x32_bf16 v[88:91], v[206:209], v[160:163], v[88:91]
	v_mfma_f32_16x16x32_bf16 v[84:87], v[192:195], v[168:171], v[84:87]
	v_mfma_f32_16x16x32_bf16 v[80:83], v[206:209], v[168:171], v[80:83]
	v_mfma_f32_16x16x32_bf16 v[76:79], v[192:195], v[176:179], v[76:79]
	v_mfma_f32_16x16x32_bf16 v[72:75], v[206:209], v[176:179], v[72:75]
	v_mfma_f32_16x16x32_bf16 v[68:71], v[192:195], v[184:187], v[68:71]
	v_mfma_f32_16x16x32_bf16 v[64:67], v[206:209], v[184:187], v[64:67]
	v_mov_b32_e32 v210, v130
	s_barrier
	v_mov_b32_e32 v211, v197
	s_mov_b32 m0, s65
	s_add_u32 s98, s28, s92
	s_addc_u32 s99, s29, s93
	global_load_lds_dwordx4 v128, s[98:99]
	s_mov_b32 m0, s67
	s_nop 0
	global_load_lds_dwordx4 v130, s[98:99]
	s_waitcnt vmcnt(4)
	s_barrier
	v_mov_b32_e32 v196, v128
	s_mov_b32 m0, s33
	s_add_u32 s98, s62, s96
	s_addc_u32 s99, s63, s97
	global_load_lds_dwordx4 v128, s[98:99]
	s_mov_b32 m0, s73
	s_nop 0
	global_load_lds_dwordx4 v130, s[98:99]
	s_barrier
	s_add_i32 s38, s38, 2
	s_add_u32 s60, s60, 0x100
	s_addc_u32 s61, s61, 0
	s_cmp_lt_u32 s38, 28
	s_cbranch_scc1 .Lh1_loop
	ds_read_b128 v[140:143], v129
	ds_read_b128 v[144:147], v129 offset:1024
	ds_read_b128 v[148:151], v129 offset:2048
	ds_read_b128 v[152:155], v129 offset:3072
	ds_read_b128 v[156:159], v136
	ds_read_b128 v[160:163], v136 offset:1024
	ds_read_b128 v[164:167], v135
	ds_read_b128 v[168:171], v135 offset:1024
	ds_read_b128 v[172:175], v134
	ds_read_b128 v[176:179], v134 offset:1024
	ds_read_b128 v[180:183], v133
	ds_read_b128 v[184:187], v133 offset:1024
	v_mov_b32_e32 v129, v197
	v_lshl_add_u64 v[128:129], s[58:59], 0, v[128:129]
	s_mov_b64 s[28:29], 0xf80
	s_mov_b32 m0, s40
	v_lshl_add_u64 v[128:129], v[128:129], 0, s[28:29]
	v_mov_b32_e32 v131, v197
	v_lshl_add_u64 v[128:129], s[58:59], 0, v[130:131]
	v_lshl_add_u64 v[128:129], v[128:129], 0, s[28:29]
	s_mov_b32 m0, s39
	s_nop 0
	s_barrier
	s_waitcnt lgkmcnt(0)
	v_mfma_f32_16x16x32_bf16 v[124:127], v[140:143], v[156:159], v[124:127]
	v_mfma_f32_16x16x32_bf16 v[120:123], v[148:151], v[156:159], v[120:123]
	v_mfma_f32_16x16x32_bf16 v[116:119], v[140:143], v[164:167], v[116:119]
	v_mfma_f32_16x16x32_bf16 v[112:115], v[148:151], v[164:167], v[112:115]
	v_mfma_f32_16x16x32_bf16 v[108:111], v[140:143], v[172:175], v[108:111]
	v_mfma_f32_16x16x32_bf16 v[100:103], v[140:143], v[180:183], v[100:103]
	v_mfma_f32_16x16x32_bf16 v[96:99], v[148:151], v[180:183], v[96:99]
	v_mfma_f32_16x16x32_bf16 v[124:127], v[144:147], v[160:163], v[124:127]
	v_mfma_f32_16x16x32_bf16 v[120:123], v[152:155], v[160:163], v[120:123]
	v_mfma_f32_16x16x32_bf16 v[116:119], v[144:147], v[168:171], v[116:119]
	v_mfma_f32_16x16x32_bf16 v[112:115], v[152:155], v[168:171], v[112:115]
	v_mfma_f32_16x16x32_bf16 v[108:111], v[144:147], v[176:179], v[108:111]
	v_mfma_f32_16x16x32_bf16 v[104:107], v[148:151], v[172:175], v[104:107]
	v_mfma_f32_16x16x32_bf16 v[100:103], v[144:147], v[184:187], v[100:103]
	v_mfma_f32_16x16x32_bf16 v[96:99], v[152:155], v[184:187], v[96:99]
	v_mfma_f32_16x16x32_bf16 v[128:131], v[152:155], v[176:179], v[104:107]
	s_barrier
	s_nop 2
	ds_read_b128 v[104:107], v139
	ds_read_b128 v[188:191], v139 offset:1024
	ds_read_b128 v[192:195], v139 offset:2048
	ds_read_b128 v[202:205], v139 offset:3072
	s_barrier
	s_waitcnt lgkmcnt(0)
	v_mfma_f32_16x16x32_bf16 v[92:95], v[104:107], v[156:159], v[92:95]
	v_mfma_f32_16x16x32_bf16 v[84:87], v[104:107], v[164:167], v[84:87]
	v_mfma_f32_16x16x32_bf16 v[76:79], v[104:107], v[172:175], v[76:79]
	v_mfma_f32_16x16x32_bf16 v[68:71], v[104:107], v[180:183], v[68:71]
	v_mfma_f32_16x16x32_bf16 v[64:67], v[192:195], v[180:183], v[64:67]
	v_mfma_f32_16x16x32_bf16 v[92:95], v[188:191], v[160:163], v[92:95]
	v_mfma_f32_16x16x32_bf16 v[88:91], v[192:195], v[156:159], v[88:91]
	v_mfma_f32_16x16x32_bf16 v[84:87], v[188:191], v[168:171], v[84:87]
	v_mfma_f32_16x16x32_bf16 v[80:83], v[192:195], v[164:167], v[80:83]
	v_mfma_f32_16x16x32_bf16 v[76:79], v[188:191], v[176:179], v[76:79]
	v_mfma_f32_16x16x32_bf16 v[72:75], v[192:195], v[172:175], v[72:75]
	v_mfma_f32_16x16x32_bf16 v[68:71], v[188:191], v[184:187], v[68:71]
	v_mfma_f32_16x16x32_bf16 v[64:67], v[202:205], v[184:187], v[64:67]
	v_mfma_f32_16x16x32_bf16 v[156:159], v[202:205], v[160:163], v[88:91]
	v_mfma_f32_16x16x32_bf16 v[160:163], v[202:205], v[168:171], v[80:83]
	v_mfma_f32_16x16x32_bf16 v[164:167], v[202:205], v[176:179], v[72:75]
	s_barrier
	s_nop 0
	s_waitcnt vmcnt(2)
	s_barrier
	s_waitcnt lgkmcnt(0)
	s_barrier
	ds_read_b128 v[16:19], v138
	ds_read_b128 v[180:183], v138 offset:1024
	ds_read_b128 v[184:187], v138 offset:2048
	ds_read_b128 v[188:191], v138 offset:3072
	ds_read_b128 v[0:3], v136 offset:32768
	ds_read_b128 v[4:7], v136 offset:33792
	ds_read_b128 v[8:11], v135 offset:32768
	ds_read_b128 v[12:15], v135 offset:33792
	ds_read_b128 v[44:47], v134 offset:32768
	ds_read_b128 v[192:195], v134 offset:33792
	ds_read_b128 v[202:205], v133 offset:32768
	ds_read_b128 v[218:221], v133 offset:33792
	s_waitcnt vmcnt(0)
	s_barrier
	s_waitcnt lgkmcnt(0)
	v_mfma_f32_16x16x32_bf16 v[28:31], v[16:19], v[0:3], v[124:127]
	v_mfma_f32_16x16x32_bf16 v[52:55], v[180:183], v[4:7], v[28:31]
	v_mfma_f32_16x16x32_bf16 v[28:31], v[184:187], v[0:3], v[120:123]
	v_mfma_f32_16x16x32_bf16 v[104:107], v[188:191], v[4:7], v[28:31]
	v_mfma_f32_16x16x32_bf16 v[28:31], v[16:19], v[8:11], v[116:119]
	v_mfma_f32_16x16x32_bf16 v[72:75], v[180:183], v[12:15], v[28:31]
	v_mfma_f32_16x16x32_bf16 v[28:31], v[184:187], v[8:11], v[112:115]
	v_mfma_f32_16x16x32_bf16 v[116:119], v[188:191], v[12:15], v[28:31]
	v_mfma_f32_16x16x32_bf16 v[28:31], v[16:19], v[44:47], v[108:111]
	v_mfma_f32_16x16x32_bf16 v[80:83], v[180:183], v[192:195], v[28:31]
	v_mfma_f32_16x16x32_bf16 v[28:31], v[184:187], v[44:47], v[128:131]
	v_mfma_f32_16x16x32_bf16 v[108:111], v[188:191], v[192:195], v[28:31]
	v_mfma_f32_16x16x32_bf16 v[28:31], v[16:19], v[202:205], v[100:103]
	v_mfma_f32_16x16x32_bf16 v[88:91], v[180:183], v[218:221], v[28:31]
	v_mfma_f32_16x16x32_bf16 v[28:31], v[184:187], v[202:205], v[96:99]
	v_mfma_f32_16x16x32_bf16 v[96:99], v[188:191], v[218:221], v[28:31]
	s_barrier
	ds_read_b128 v[128:131], v137
	ds_read_b128 v[222:225], v137 offset:1024
	ds_read_b128 v[228:231], v137 offset:2048
	ds_read_b128 v[232:235], v137 offset:3072
	s_waitcnt vmcnt(0)
	s_barrier
	s_waitcnt lgkmcnt(0)
	v_mfma_f32_16x16x32_bf16 v[28:31], v[128:131], v[0:3], v[92:95]
	v_mfma_f32_16x16x32_bf16 v[0:3], v[228:231], v[0:3], v[156:159]
	v_mfma_f32_16x16x32_bf16 v[28:31], v[222:225], v[4:7], v[28:31]
	v_mfma_f32_16x16x32_bf16 v[0:3], v[232:235], v[4:7], v[0:3]
	v_mfma_f32_16x16x32_bf16 v[4:7], v[128:131], v[8:11], v[84:87]
	v_mfma_f32_16x16x32_bf16 v[36:39], v[222:225], v[12:15], v[4:7]
	v_mfma_f32_16x16x32_bf16 v[4:7], v[228:231], v[8:11], v[160:163]
	v_mfma_f32_16x16x32_bf16 v[4:7], v[232:235], v[12:15], v[4:7]
	v_mfma_f32_16x16x32_bf16 v[8:11], v[128:131], v[44:47], v[76:79]
	v_mfma_f32_16x16x32_bf16 v[12:15], v[128:131], v[202:205], v[68:71]
	v_mfma_f32_16x16x32_bf16 v[40:43], v[222:225], v[192:195], v[8:11]
	v_mfma_f32_16x16x32_bf16 v[8:11], v[228:231], v[44:47], v[164:167]
	v_mfma_f32_16x16x32_bf16 v[44:47], v[222:225], v[218:221], v[12:15]
	v_mfma_f32_16x16x32_bf16 v[12:15], v[228:231], v[202:205], v[64:67]
	v_mfma_f32_16x16x32_bf16 v[8:11], v[232:235], v[192:195], v[8:11]
	v_mfma_f32_16x16x32_bf16 v[12:15], v[232:235], v[218:221], v[12:15]
	s_barrier
	s_barrier
	s_waitcnt lgkmcnt(0)
	s_movk_i32 s9, 0x100
	v_cmp_gt_u32_e32 vcc, s9, v132
	s_barrier
	s_and_saveexec_b64 s[28:29], vcc
	s_cbranch_execz .Lh1_epi
	s_barrier

.LBB0_255:
	ds_read_b128 v[140:143], v129
	ds_read_b128 v[144:147], v129 offset:1024
	ds_read_b128 v[148:151], v129 offset:2048
	ds_read_b128 v[152:155], v129 offset:3072
	s_add_u32 s28, s60, s56
	s_addc_u32 s29, s61, s57
	ds_read_b128 v[156:159], v136
	ds_read_b128 v[160:163], v136 offset:1024
	ds_read_b128 v[164:167], v135
	ds_read_b128 v[168:171], v135 offset:1024
	ds_read_b128 v[172:175], v134
	ds_read_b128 v[176:179], v134 offset:1024
	ds_read_b128 v[180:183], v133
	ds_read_b128 v[184:187], v133 offset:1024
	s_add_i32 s40, s53, 0xc000
	s_mov_b32 m0, s40
	s_add_i32 s39, s53, 0xe000
	s_add_u32 s98, s28, s44
	s_addc_u32 s99, s29, s45
	global_load_lds_dwordx4 v128, s[98:99]
	s_mov_b32 m0, s39
	s_nop 0
	global_load_lds_dwordx4 v130, s[98:99]
	s_waitcnt lgkmcnt(8)
	s_barrier
	s_waitcnt lgkmcnt(0)
	s_waitcnt lgkmcnt(0)
	v_mfma_f32_16x16x32_bf16 v[124:127], v[140:143], v[156:159], v[124:127]
	v_mfma_f32_16x16x32_bf16 v[120:123], v[148:151], v[156:159], v[120:123]
	v_mfma_f32_16x16x32_bf16 v[116:119], v[140:143], v[164:167], v[116:119]
	v_mfma_f32_16x16x32_bf16 v[112:115], v[148:151], v[164:167], v[112:115]
	v_mfma_f32_16x16x32_bf16 v[108:111], v[140:143], v[172:175], v[108:111]
	v_mfma_f32_16x16x32_bf16 v[104:107], v[148:151], v[172:175], v[104:107]
	v_mfma_f32_16x16x32_bf16 v[100:103], v[140:143], v[180:183], v[100:103]
	v_mfma_f32_16x16x32_bf16 v[96:99], v[148:151], v[180:183], v[96:99]
	v_mfma_f32_16x16x32_bf16 v[124:127], v[144:147], v[160:163], v[124:127]
	v_mfma_f32_16x16x32_bf16 v[120:123], v[152:155], v[160:163], v[120:123]
	v_mfma_f32_16x16x32_bf16 v[116:119], v[144:147], v[168:171], v[116:119]
	v_mfma_f32_16x16x32_bf16 v[112:115], v[152:155], v[168:171], v[112:115]
	v_mfma_f32_16x16x32_bf16 v[108:111], v[144:147], v[176:179], v[108:111]
	v_mfma_f32_16x16x32_bf16 v[104:107], v[152:155], v[176:179], v[104:107]
	v_mfma_f32_16x16x32_bf16 v[100:103], v[144:147], v[184:187], v[100:103]
	v_mfma_f32_16x16x32_bf16 v[96:99], v[152:155], v[184:187], v[96:99]
	s_barrier
	s_add_u32 s62, s60, s36
	s_addc_u32 s63, s61, s37
	ds_read_b128 v[188:191], v139
	ds_read_b128 v[192:195], v139 offset:1024
	ds_read_b128 v[202:205], v139 offset:2048
	ds_read_b128 v[206:209], v139 offset:3072
	s_mov_b32 m0, s68
	s_add_u32 s98, s62, s46
	s_addc_u32 s99, s63, s47
	global_load_lds_dwordx4 v128, s[98:99]
	s_mov_b32 m0, s69
	s_nop 0
	global_load_lds_dwordx4 v130, s[98:99]
	s_barrier
	s_waitcnt lgkmcnt(0)
	s_waitcnt lgkmcnt(0)
	v_mfma_f32_16x16x32_bf16 v[92:95], v[188:191], v[156:159], v[92:95]
	v_mfma_f32_16x16x32_bf16 v[88:91], v[202:205], v[156:159], v[88:91]
	v_mfma_f32_16x16x32_bf16 v[84:87], v[188:191], v[164:167], v[84:87]
	v_mfma_f32_16x16x32_bf16 v[80:83], v[202:205], v[164:167], v[80:83]
	v_mfma_f32_16x16x32_bf16 v[76:79], v[188:191], v[172:175], v[76:79]
	v_mfma_f32_16x16x32_bf16 v[72:75], v[202:205], v[172:175], v[72:75]
	v_mfma_f32_16x16x32_bf16 v[68:71], v[188:191], v[180:183], v[68:71]
	v_mfma_f32_16x16x32_bf16 v[64:67], v[202:205], v[180:183], v[64:67]
	v_mfma_f32_16x16x32_bf16 v[92:95], v[192:195], v[160:163], v[92:95]
	v_mfma_f32_16x16x32_bf16 v[88:91], v[206:209], v[160:163], v[88:91]
	v_mfma_f32_16x16x32_bf16 v[84:87], v[192:195], v[168:171], v[84:87]
	v_mfma_f32_16x16x32_bf16 v[80:83], v[206:209], v[168:171], v[80:83]
	v_mfma_f32_16x16x32_bf16 v[76:79], v[192:195], v[176:179], v[76:79]
	v_mfma_f32_16x16x32_bf16 v[72:75], v[206:209], v[176:179], v[72:75]
	v_mfma_f32_16x16x32_bf16 v[68:71], v[192:195], v[184:187], v[68:71]
	v_mfma_f32_16x16x32_bf16 v[64:67], v[206:209], v[184:187], v[64:67]
	s_barrier
	ds_read_b128 v[156:159], v136 offset:16384
	ds_read_b128 v[160:163], v136 offset:17408
	ds_read_b128 v[164:167], v135 offset:16384
	ds_read_b128 v[168:171], v135 offset:17408
	ds_read_b128 v[172:175], v134 offset:16384
	ds_read_b128 v[176:179], v134 offset:17408
	ds_read_b128 v[180:183], v133 offset:16384
	ds_read_b128 v[184:187], v133 offset:17408
	s_mov_b32 m0, s53
	s_add_u32 s98, s28, s48
	s_addc_u32 s99, s29, s49
	global_load_lds_dwordx4 v128, s[98:99]
	s_mov_b32 m0, s11
	s_nop 0
	global_load_lds_dwordx4 v130, s[98:99]
	s_barrier
	s_waitcnt lgkmcnt(0)
	s_waitcnt lgkmcnt(0)
	v_mfma_f32_16x16x32_bf16 v[60:63], v[140:143], v[156:159], v[60:63]
	v_mfma_f32_16x16x32_bf16 v[56:59], v[148:151], v[156:159], v[56:59]
	v_mfma_f32_16x16x32_bf16 v[52:55], v[140:143], v[164:167], v[52:55]
	v_mfma_f32_16x16x32_bf16 v[48:51], v[148:151], v[164:167], v[48:51]
	v_mfma_f32_16x16x32_bf16 v[44:47], v[140:143], v[172:175], v[44:47]
	v_mfma_f32_16x16x32_bf16 v[40:43], v[148:151], v[172:175], v[40:43]
	v_mfma_f32_16x16x32_bf16 v[36:39], v[140:143], v[180:183], v[36:39]
	v_mfma_f32_16x16x32_bf16 v[32:35], v[148:151], v[180:183], v[32:35]
	v_mfma_f32_16x16x32_bf16 v[60:63], v[144:147], v[160:163], v[60:63]
	v_mfma_f32_16x16x32_bf16 v[56:59], v[152:155], v[160:163], v[56:59]
	v_mfma_f32_16x16x32_bf16 v[52:55], v[144:147], v[168:171], v[52:55]
	v_mfma_f32_16x16x32_bf16 v[48:51], v[152:155], v[168:171], v[48:51]
	v_mfma_f32_16x16x32_bf16 v[44:47], v[144:147], v[176:179], v[44:47]
	v_mfma_f32_16x16x32_bf16 v[40:43], v[152:155], v[176:179], v[40:43]
	v_mfma_f32_16x16x32_bf16 v[36:39], v[144:147], v[184:187], v[36:39]
	v_mfma_f32_16x16x32_bf16 v[32:35], v[152:155], v[184:187], v[32:35]
	s_barrier
	s_mov_b32 m0, s9
	s_add_u32 s98, s62, s50
	s_addc_u32 s99, s63, s51
	global_load_lds_dwordx4 v128, s[98:99]
	s_mov_b32 m0, s70
	s_nop 0
	global_load_lds_dwordx4 v130, s[98:99]
	s_waitcnt vmcnt(6)
	s_barrier
	v_mfma_f32_16x16x32_bf16 v[28:31], v[188:191], v[156:159], v[28:31]
	v_mfma_f32_16x16x32_bf16 v[24:27], v[202:205], v[156:159], v[24:27]
	v_mfma_f32_16x16x32_bf16 v[20:23], v[188:191], v[164:167], v[20:23]
	v_mfma_f32_16x16x32_bf16 v[16:19], v[202:205], v[164:167], v[16:19]
	v_mfma_f32_16x16x32_bf16 v[12:15], v[188:191], v[172:175], v[12:15]
	v_mfma_f32_16x16x32_bf16 v[8:11], v[202:205], v[172:175], v[8:11]
	v_mfma_f32_16x16x32_bf16 v[4:7], v[188:191], v[180:183], v[4:7]
	v_mfma_f32_16x16x32_bf16 v[0:3], v[202:205], v[180:183], v[0:3]
	v_mfma_f32_16x16x32_bf16 v[28:31], v[192:195], v[160:163], v[28:31]
	v_mfma_f32_16x16x32_bf16 v[24:27], v[206:209], v[160:163], v[24:27]
	v_mfma_f32_16x16x32_bf16 v[20:23], v[192:195], v[168:171], v[20:23]
	v_mfma_f32_16x16x32_bf16 v[16:19], v[206:209], v[168:171], v[16:19]
	v_mfma_f32_16x16x32_bf16 v[12:15], v[192:195], v[176:179], v[12:15]
	v_mfma_f32_16x16x32_bf16 v[8:11], v[206:209], v[176:179], v[8:11]
	v_mfma_f32_16x16x32_bf16 v[4:7], v[192:195], v[184:187], v[4:7]
	v_mfma_f32_16x16x32_bf16 v[0:3], v[206:209], v[184:187], v[0:3]
	s_barrier
	ds_read_b128 v[140:143], v138
	ds_read_b128 v[144:147], v138 offset:1024
	ds_read_b128 v[148:151], v138 offset:2048
	ds_read_b128 v[152:155], v138 offset:3072
	ds_read_b128 v[156:159], v136 offset:32768
	ds_read_b128 v[160:163], v136 offset:33792
	ds_read_b128 v[164:167], v135 offset:32768
	ds_read_b128 v[168:171], v135 offset:33792
	ds_read_b128 v[172:175], v134 offset:32768
	ds_read_b128 v[176:179], v134 offset:33792
	ds_read_b128 v[180:183], v133 offset:32768
	ds_read_b128 v[184:187], v133 offset:33792
	s_mov_b32 m0, s71
	s_add_u32 s98, s28, s74
	s_addc_u32 s99, s29, s75
	global_load_lds_dwordx4 v128, s[98:99]
	s_mov_b32 m0, s72
	s_nop 0
	global_load_lds_dwordx4 v130, s[98:99]
	s_waitcnt lgkmcnt(8)
	s_barrier
	s_waitcnt lgkmcnt(0)
	s_waitcnt lgkmcnt(0)
	v_mfma_f32_16x16x32_bf16 v[124:127], v[140:143], v[156:159], v[124:127]
	v_mfma_f32_16x16x32_bf16 v[120:123], v[148:151], v[156:159], v[120:123]
	v_mfma_f32_16x16x32_bf16 v[116:119], v[140:143], v[164:167], v[116:119]
	v_mfma_f32_16x16x32_bf16 v[112:115], v[148:151], v[164:167], v[112:115]
	v_mfma_f32_16x16x32_bf16 v[108:111], v[140:143], v[172:175], v[108:111]
	v_mfma_f32_16x16x32_bf16 v[104:107], v[148:151], v[172:175], v[104:107]
	v_mfma_f32_16x16x32_bf16 v[100:103], v[140:143], v[180:183], v[100:103]
	v_mfma_f32_16x16x32_bf16 v[96:99], v[148:151], v[180:183], v[96:99]
	v_mfma_f32_16x16x32_bf16 v[124:127], v[144:147], v[160:163], v[124:127]
	v_mfma_f32_16x16x32_bf16 v[120:123], v[152:155], v[160:163], v[120:123]
	v_mfma_f32_16x16x32_bf16 v[116:119], v[144:147], v[168:171], v[116:119]
	v_mfma_f32_16x16x32_bf16 v[112:115], v[152:155], v[168:171], v[112:115]
	v_mfma_f32_16x16x32_bf16 v[108:111], v[144:147], v[176:179], v[108:111]
	v_mfma_f32_16x16x32_bf16 v[104:107], v[152:155], v[176:179], v[104:107]
	v_mfma_f32_16x16x32_bf16 v[100:103], v[144:147], v[184:187], v[100:103]
	v_mfma_f32_16x16x32_bf16 v[96:99], v[152:155], v[184:187], v[96:99]
	s_barrier
	ds_read_b128 v[188:191], v137
	ds_read_b128 v[192:195], v137 offset:1024
	ds_read_b128 v[202:205], v137 offset:2048
	ds_read_b128 v[206:209], v137 offset:3072
	s_mov_b32 m0, s66
	s_add_u32 s98, s62, s90
	s_addc_u32 s99, s63, s91
	global_load_lds_dwordx4 v128, s[98:99]
	s_mov_b32 m0, s64
	s_nop 0
	global_load_lds_dwordx4 v130, s[98:99]
	s_barrier
	s_waitcnt lgkmcnt(0)
	s_waitcnt lgkmcnt(0)
	v_mfma_f32_16x16x32_bf16 v[92:95], v[188:191], v[156:159], v[92:95]
	v_mfma_f32_16x16x32_bf16 v[88:91], v[202:205], v[156:159], v[88:91]
	v_mfma_f32_16x16x32_bf16 v[84:87], v[188:191], v[164:167], v[84:87]
	v_mfma_f32_16x16x32_bf16 v[80:83], v[202:205], v[164:167], v[80:83]
	v_mfma_f32_16x16x32_bf16 v[76:79], v[188:191], v[172:175], v[76:79]
	v_mfma_f32_16x16x32_bf16 v[72:75], v[202:205], v[172:175], v[72:75]
	v_mfma_f32_16x16x32_bf16 v[68:71], v[188:191], v[180:183], v[68:71]
	v_mfma_f32_16x16x32_bf16 v[64:67], v[202:205], v[180:183], v[64:67]
	v_mfma_f32_16x16x32_bf16 v[92:95], v[192:195], v[160:163], v[92:95]
	v_mfma_f32_16x16x32_bf16 v[88:91], v[206:209], v[160:163], v[88:91]
	v_mfma_f32_16x16x32_bf16 v[84:87], v[192:195], v[168:171], v[84:87]
	v_mfma_f32_16x16x32_bf16 v[80:83], v[206:209], v[168:171], v[80:83]
	v_mfma_f32_16x16x32_bf16 v[76:79], v[192:195], v[176:179], v[76:79]
	v_mfma_f32_16x16x32_bf16 v[72:75], v[206:209], v[176:179], v[72:75]
	v_mfma_f32_16x16x32_bf16 v[68:71], v[192:195], v[184:187], v[68:71]
	v_mfma_f32_16x16x32_bf16 v[64:67], v[206:209], v[184:187], v[64:67]
	v_mov_b32_e32 v210, v130
	s_barrier
	ds_read_b128 v[156:159], v136 offset:49152
	ds_read_b128 v[160:163], v136 offset:50176
	ds_read_b128 v[164:167], v135 offset:49152
	ds_read_b128 v[168:171], v135 offset:50176
	ds_read_b128 v[172:175], v134 offset:49152
	ds_read_b128 v[176:179], v134 offset:50176
	ds_read_b128 v[180:183], v133 offset:49152
	ds_read_b128 v[184:187], v133 offset:50176
	v_mov_b32_e32 v211, v197
	s_mov_b32 m0, s65
	s_add_u32 s98, s28, s92
	s_addc_u32 s99, s29, s93
	global_load_lds_dwordx4 v128, s[98:99]
	s_mov_b32 m0, s67
	s_nop 0
	global_load_lds_dwordx4 v130, s[98:99]
	s_barrier
	s_waitcnt lgkmcnt(0)
	s_waitcnt lgkmcnt(0)
	v_mfma_f32_16x16x32_bf16 v[60:63], v[140:143], v[156:159], v[60:63]
	v_mfma_f32_16x16x32_bf16 v[56:59], v[148:151], v[156:159], v[56:59]
	v_mfma_f32_16x16x32_bf16 v[52:55], v[140:143], v[164:167], v[52:55]
	v_mfma_f32_16x16x32_bf16 v[48:51], v[148:151], v[164:167], v[48:51]
	v_mfma_f32_16x16x32_bf16 v[44:47], v[140:143], v[172:175], v[44:47]
	v_mfma_f32_16x16x32_bf16 v[40:43], v[148:151], v[172:175], v[40:43]
	v_mfma_f32_16x16x32_bf16 v[36:39], v[140:143], v[180:183], v[36:39]
	v_mfma_f32_16x16x32_bf16 v[32:35], v[148:151], v[180:183], v[32:35]
	v_mfma_f32_16x16x32_bf16 v[60:63], v[144:147], v[160:163], v[60:63]
	v_mfma_f32_16x16x32_bf16 v[56:59], v[152:155], v[160:163], v[56:59]
	v_mfma_f32_16x16x32_bf16 v[52:55], v[144:147], v[168:171], v[52:55]
	v_mfma_f32_16x16x32_bf16 v[48:51], v[152:155], v[168:171], v[48:51]
	v_mfma_f32_16x16x32_bf16 v[44:47], v[144:147], v[176:179], v[44:47]
	v_mfma_f32_16x16x32_bf16 v[40:43], v[152:155], v[176:179], v[40:43]
	v_mfma_f32_16x16x32_bf16 v[36:39], v[144:147], v[184:187], v[36:39]
	v_mfma_f32_16x16x32_bf16 v[32:35], v[152:155], v[184:187], v[32:35]
	s_barrier
	v_mov_b32_e32 v196, v128
	s_mov_b32 m0, s33
	s_add_u32 s98, s62, s96
	s_addc_u32 s99, s63, s97
	global_load_lds_dwordx4 v128, s[98:99]
	s_mov_b32 m0, s73
	s_nop 0
	global_load_lds_dwordx4 v130, s[98:99]
	s_waitcnt vmcnt(6)
	s_barrier
	v_mfma_f32_16x16x32_bf16 v[28:31], v[188:191], v[156:159], v[28:31]
	v_mfma_f32_16x16x32_bf16 v[24:27], v[202:205], v[156:159], v[24:27]
	v_mfma_f32_16x16x32_bf16 v[20:23], v[188:191], v[164:167], v[20:23]
	v_mfma_f32_16x16x32_bf16 v[16:19], v[202:205], v[164:167], v[16:19]
	v_mfma_f32_16x16x32_bf16 v[12:15], v[188:191], v[172:175], v[12:15]
	v_mfma_f32_16x16x32_bf16 v[8:11], v[202:205], v[172:175], v[8:11]
	v_mfma_f32_16x16x32_bf16 v[4:7], v[188:191], v[180:183], v[4:7]
	v_mfma_f32_16x16x32_bf16 v[0:3], v[202:205], v[180:183], v[0:3]
	v_mfma_f32_16x16x32_bf16 v[28:31], v[192:195], v[160:163], v[28:31]
	v_mfma_f32_16x16x32_bf16 v[24:27], v[206:209], v[160:163], v[24:27]
	v_mfma_f32_16x16x32_bf16 v[20:23], v[192:195], v[168:171], v[20:23]
	v_mfma_f32_16x16x32_bf16 v[16:19], v[206:209], v[168:171], v[16:19]
	v_mfma_f32_16x16x32_bf16 v[12:15], v[192:195], v[176:179], v[12:15]
	v_mfma_f32_16x16x32_bf16 v[8:11], v[206:209], v[176:179], v[8:11]
	v_mfma_f32_16x16x32_bf16 v[4:7], v[192:195], v[184:187], v[4:7]
	v_mfma_f32_16x16x32_bf16 v[0:3], v[206:209], v[184:187], v[0:3]
	s_add_i32 s38, s38, 2
	s_add_u32 s60, s60, 0x100
	s_addc_u32 s61, s61, 0
	s_cmp_lt_u32 s38, 28
	s_barrier
	s_cbranch_scc1 .LBB0_255
	ds_read_b128 v[140:143], v129
	ds_read_b128 v[144:147], v129 offset:1024
	ds_read_b128 v[148:151], v129 offset:2048
	ds_read_b128 v[152:155], v129 offset:3072
	ds_read_b128 v[156:159], v136
	ds_read_b128 v[160:163], v136 offset:1024
	ds_read_b128 v[164:167], v135
	ds_read_b128 v[168:171], v135 offset:1024
	ds_read_b128 v[172:175], v134
	ds_read_b128 v[176:179], v134 offset:1024
	ds_read_b128 v[180:183], v133
	ds_read_b128 v[184:187], v133 offset:1024
	v_mov_b32_e32 v129, v197
	v_lshl_add_u64 v[128:129], s[58:59], 0, v[128:129]
	s_mov_b64 s[28:29], 0xf80
	s_mov_b32 m0, s40
	v_lshl_add_u64 v[128:129], v[128:129], 0, s[28:29]
	v_mov_b32_e32 v131, v197
	global_load_lds_dwordx4 v[128:129], off
	v_lshl_add_u64 v[128:129], s[58:59], 0, v[130:131]
	v_lshl_add_u64 v[128:129], v[128:129], 0, s[28:29]
	s_mov_b32 m0, s39
	s_nop 0
	global_load_lds_dwordx4 v[128:129], off
	s_barrier
	s_waitcnt lgkmcnt(0)
	s_waitcnt lgkmcnt(0)
	v_mfma_f32_16x16x32_bf16 v[124:127], v[140:143], v[156:159], v[124:127]
	v_mfma_f32_16x16x32_bf16 v[120:123], v[148:151], v[156:159], v[120:123]
	v_mfma_f32_16x16x32_bf16 v[116:119], v[140:143], v[164:167], v[116:119]
	v_mfma_f32_16x16x32_bf16 v[112:115], v[148:151], v[164:167], v[112:115]
	v_mfma_f32_16x16x32_bf16 v[108:111], v[140:143], v[172:175], v[108:111]
	v_mfma_f32_16x16x32_bf16 v[100:103], v[140:143], v[180:183], v[100:103]
	v_mfma_f32_16x16x32_bf16 v[96:99], v[148:151], v[180:183], v[96:99]
	v_mfma_f32_16x16x32_bf16 v[124:127], v[144:147], v[160:163], v[124:127]
	v_mfma_f32_16x16x32_bf16 v[120:123], v[152:155], v[160:163], v[120:123]
	v_mfma_f32_16x16x32_bf16 v[116:119], v[144:147], v[168:171], v[116:119]
	v_mfma_f32_16x16x32_bf16 v[112:115], v[152:155], v[168:171], v[112:115]
	v_mfma_f32_16x16x32_bf16 v[108:111], v[144:147], v[176:179], v[108:111]
	v_mfma_f32_16x16x32_bf16 v[104:107], v[148:151], v[172:175], v[104:107]
	v_mfma_f32_16x16x32_bf16 v[100:103], v[144:147], v[184:187], v[100:103]
	v_mfma_f32_16x16x32_bf16 v[96:99], v[152:155], v[184:187], v[96:99]
	v_mfma_f32_16x16x32_bf16 v[128:131], v[152:155], v[176:179], v[104:107]
	s_barrier
	s_nop 2
	ds_read_b128 v[104:107], v139
	ds_read_b128 v[188:191], v139 offset:1024
	ds_read_b128 v[192:195], v139 offset:2048
	ds_read_b128 v[202:205], v139 offset:3072
	s_barrier
	s_waitcnt lgkmcnt(0)
	s_waitcnt lgkmcnt(0)
	v_mfma_f32_16x16x32_bf16 v[92:95], v[104:107], v[156:159], v[92:95]
	v_mfma_f32_16x16x32_bf16 v[84:87], v[104:107], v[164:167], v[84:87]
	v_mfma_f32_16x16x32_bf16 v[76:79], v[104:107], v[172:175], v[76:79]
	v_mfma_f32_16x16x32_bf16 v[68:71], v[104:107], v[180:183], v[68:71]
	v_mfma_f32_16x16x32_bf16 v[64:67], v[192:195], v[180:183], v[64:67]
	v_mfma_f32_16x16x32_bf16 v[92:95], v[188:191], v[160:163], v[92:95]
	v_mfma_f32_16x16x32_bf16 v[88:91], v[192:195], v[156:159], v[88:91]
	v_mfma_f32_16x16x32_bf16 v[84:87], v[188:191], v[168:171], v[84:87]
	v_mfma_f32_16x16x32_bf16 v[80:83], v[192:195], v[164:167], v[80:83]
	v_mfma_f32_16x16x32_bf16 v[76:79], v[188:191], v[176:179], v[76:79]
	v_mfma_f32_16x16x32_bf16 v[72:75], v[192:195], v[172:175], v[72:75]
	v_mfma_f32_16x16x32_bf16 v[68:71], v[188:191], v[184:187], v[68:71]
	v_mfma_f32_16x16x32_bf16 v[64:67], v[202:205], v[184:187], v[64:67]
	v_mfma_f32_16x16x32_bf16 v[156:159], v[202:205], v[160:163], v[88:91]
	v_mfma_f32_16x16x32_bf16 v[160:163], v[202:205], v[168:171], v[80:83]
	v_mfma_f32_16x16x32_bf16 v[164:167], v[202:205], v[176:179], v[72:75]
	s_barrier
	s_nop 0
	ds_read_b128 v[72:75], v136 offset:16384
	ds_read_b128 v[80:83], v136 offset:17408
	ds_read_b128 v[88:91], v135 offset:16384
	ds_read_b128 v[168:171], v135 offset:17408
	ds_read_b128 v[172:175], v134 offset:16384
	ds_read_b128 v[176:179], v134 offset:17408
	ds_read_b128 v[180:183], v133 offset:16384
	ds_read_b128 v[184:187], v133 offset:17408
	s_waitcnt vmcnt(4)
	s_barrier
	s_waitcnt lgkmcnt(0)
	s_waitcnt lgkmcnt(0)
	v_mfma_f32_16x16x32_bf16 v[60:63], v[140:143], v[72:75], v[60:63]
	v_mfma_f32_16x16x32_bf16 v[56:59], v[148:151], v[72:75], v[56:59]
	v_mfma_f32_16x16x32_bf16 v[48:51], v[148:151], v[88:91], v[48:51]
	v_mfma_f32_16x16x32_bf16 v[32:35], v[148:151], v[180:183], v[32:35]
	v_mfma_f32_16x16x32_bf16 v[60:63], v[144:147], v[80:83], v[60:63]
	v_mfma_f32_16x16x32_bf16 v[56:59], v[152:155], v[80:83], v[56:59]
	v_mfma_f32_16x16x32_bf16 v[52:55], v[140:143], v[88:91], v[52:55]
	v_mfma_f32_16x16x32_bf16 v[48:51], v[152:155], v[168:171], v[48:51]
	v_mfma_f32_16x16x32_bf16 v[44:47], v[140:143], v[172:175], v[44:47]
	v_mfma_f32_16x16x32_bf16 v[40:43], v[148:151], v[172:175], v[40:43]
	v_mfma_f32_16x16x32_bf16 v[36:39], v[140:143], v[180:183], v[36:39]
	v_mfma_f32_16x16x32_bf16 v[32:35], v[152:155], v[184:187], v[32:35]
	v_mfma_f32_16x16x32_bf16 v[206:209], v[144:147], v[168:171], v[52:55]
	v_mfma_f32_16x16x32_bf16 v[210:213], v[144:147], v[176:179], v[44:47]
	v_mfma_f32_16x16x32_bf16 v[214:217], v[152:155], v[176:179], v[40:43]
	v_mfma_f32_16x16x32_bf16 v[140:143], v[144:147], v[184:187], v[36:39]
	v_mfma_f32_16x16x32_bf16 v[24:27], v[192:195], v[72:75], v[24:27]
	v_mfma_f32_16x16x32_bf16 v[20:23], v[104:107], v[88:91], v[20:23]
	v_mfma_f32_16x16x32_bf16 v[28:31], v[104:107], v[72:75], v[28:31]
	v_mfma_f32_16x16x32_bf16 v[24:27], v[202:205], v[80:83], v[24:27]
	v_mfma_f32_16x16x32_bf16 v[20:23], v[188:191], v[168:171], v[20:23]
	v_mfma_f32_16x16x32_bf16 v[16:19], v[192:195], v[88:91], v[16:19]
	v_mfma_f32_16x16x32_bf16 v[12:15], v[104:107], v[172:175], v[12:15]
	v_mfma_f32_16x16x32_bf16 v[8:11], v[192:195], v[172:175], v[8:11]
	v_mfma_f32_16x16x32_bf16 v[4:7], v[104:107], v[180:183], v[4:7]
	v_mfma_f32_16x16x32_bf16 v[0:3], v[192:195], v[180:183], v[0:3]
	v_mfma_f32_16x16x32_bf16 v[144:147], v[188:191], v[80:83], v[28:31]
	v_mfma_f32_16x16x32_bf16 v[148:151], v[202:205], v[168:171], v[16:19]
	v_mfma_f32_16x16x32_bf16 v[152:155], v[188:191], v[176:179], v[12:15]
	v_mfma_f32_16x16x32_bf16 v[168:171], v[202:205], v[176:179], v[8:11]
	v_mfma_f32_16x16x32_bf16 v[172:175], v[188:191], v[184:187], v[4:7]
	v_mfma_f32_16x16x32_bf16 v[176:179], v[202:205], v[184:187], v[0:3]
	s_barrier
	ds_read_b128 v[16:19], v138
	ds_read_b128 v[180:183], v138 offset:1024
	ds_read_b128 v[184:187], v138 offset:2048
	ds_read_b128 v[188:191], v138 offset:3072
	ds_read_b128 v[0:3], v136 offset:32768
	ds_read_b128 v[4:7], v136 offset:33792
	ds_read_b128 v[8:11], v135 offset:32768
	ds_read_b128 v[12:15], v135 offset:33792
	ds_read_b128 v[44:47], v134 offset:32768
	ds_read_b128 v[192:195], v134 offset:33792
	ds_read_b128 v[202:205], v133 offset:32768
	ds_read_b128 v[218:221], v133 offset:33792
	s_waitcnt vmcnt(2)
	s_barrier
	s_waitcnt lgkmcnt(0)
	s_waitcnt lgkmcnt(0)
	v_mfma_f32_16x16x32_bf16 v[28:31], v[16:19], v[0:3], v[124:127]
	v_mfma_f32_16x16x32_bf16 v[52:55], v[180:183], v[4:7], v[28:31]
	v_mfma_f32_16x16x32_bf16 v[28:31], v[184:187], v[0:3], v[120:123]
	v_mfma_f32_16x16x32_bf16 v[104:107], v[188:191], v[4:7], v[28:31]
	v_mfma_f32_16x16x32_bf16 v[28:31], v[16:19], v[8:11], v[116:119]
	v_mfma_f32_16x16x32_bf16 v[72:75], v[180:183], v[12:15], v[28:31]
	v_mfma_f32_16x16x32_bf16 v[28:31], v[184:187], v[8:11], v[112:115]
	v_mfma_f32_16x16x32_bf16 v[116:119], v[188:191], v[12:15], v[28:31]
	v_mfma_f32_16x16x32_bf16 v[28:31], v[16:19], v[44:47], v[108:111]
	v_mfma_f32_16x16x32_bf16 v[80:83], v[180:183], v[192:195], v[28:31]
	v_mfma_f32_16x16x32_bf16 v[28:31], v[184:187], v[44:47], v[128:131]
	v_mfma_f32_16x16x32_bf16 v[108:111], v[188:191], v[192:195], v[28:31]
	v_mfma_f32_16x16x32_bf16 v[28:31], v[16:19], v[202:205], v[100:103]
	v_mfma_f32_16x16x32_bf16 v[88:91], v[180:183], v[218:221], v[28:31]
	v_mfma_f32_16x16x32_bf16 v[28:31], v[184:187], v[202:205], v[96:99]
	v_mfma_f32_16x16x32_bf16 v[96:99], v[188:191], v[218:221], v[28:31]
	s_barrier
	ds_read_b128 v[128:131], v137
	ds_read_b128 v[222:225], v137 offset:1024
	ds_read_b128 v[228:231], v137 offset:2048
	ds_read_b128 v[232:235], v137 offset:3072
	s_waitcnt vmcnt(0)
	s_barrier
	s_waitcnt lgkmcnt(0)
	s_waitcnt lgkmcnt(0)
	v_mfma_f32_16x16x32_bf16 v[28:31], v[128:131], v[0:3], v[92:95]
	v_mfma_f32_16x16x32_bf16 v[0:3], v[228:231], v[0:3], v[156:159]
	v_mfma_f32_16x16x32_bf16 v[28:31], v[222:225], v[4:7], v[28:31]
	v_mfma_f32_16x16x32_bf16 v[0:3], v[232:235], v[4:7], v[0:3]
	v_mfma_f32_16x16x32_bf16 v[4:7], v[128:131], v[8:11], v[84:87]
	v_mfma_f32_16x16x32_bf16 v[36:39], v[222:225], v[12:15], v[4:7]
	v_mfma_f32_16x16x32_bf16 v[4:7], v[228:231], v[8:11], v[160:163]
	v_mfma_f32_16x16x32_bf16 v[4:7], v[232:235], v[12:15], v[4:7]
	v_mfma_f32_16x16x32_bf16 v[8:11], v[128:131], v[44:47], v[76:79]
	v_mfma_f32_16x16x32_bf16 v[12:15], v[128:131], v[202:205], v[68:71]
	v_mfma_f32_16x16x32_bf16 v[40:43], v[222:225], v[192:195], v[8:11]
	v_mfma_f32_16x16x32_bf16 v[8:11], v[228:231], v[44:47], v[164:167]
	v_mfma_f32_16x16x32_bf16 v[44:47], v[222:225], v[218:221], v[12:15]
	v_mfma_f32_16x16x32_bf16 v[12:15], v[228:231], v[202:205], v[64:67]
	v_mfma_f32_16x16x32_bf16 v[8:11], v[232:235], v[192:195], v[8:11]
	v_mfma_f32_16x16x32_bf16 v[12:15], v[232:235], v[218:221], v[12:15]
	s_barrier
	ds_read_b128 v[64:67], v136 offset:49152
	ds_read_b128 v[136:139], v136 offset:50176
	ds_read_b128 v[156:159], v135 offset:49152
	ds_read_b128 v[160:163], v135 offset:50176
	ds_read_b128 v[164:167], v134 offset:49152
	ds_read_b128 v[192:195], v134 offset:50176
	ds_read_b128 v[202:205], v133 offset:49152
	ds_read_b128 v[218:221], v133 offset:50176
	s_barrier
	s_waitcnt lgkmcnt(0)
	s_waitcnt lgkmcnt(0)
	v_mfma_f32_16x16x32_bf16 v[56:59], v[184:187], v[64:67], v[56:59]
	v_mfma_f32_16x16x32_bf16 v[48:51], v[184:187], v[156:159], v[48:51]
	v_mfma_f32_16x16x32_bf16 v[60:63], v[16:19], v[64:67], v[60:63]
	v_mfma_f32_16x16x32_bf16 v[92:95], v[188:191], v[136:139], v[56:59]
	v_mfma_f32_16x16x32_bf16 v[56:59], v[16:19], v[156:159], v[206:209]
	v_mfma_f32_16x16x32_bf16 v[84:87], v[188:191], v[160:163], v[48:51]
	v_mfma_f32_16x16x32_bf16 v[48:51], v[16:19], v[164:167], v[210:213]
	v_mfma_f32_16x16x32_bf16 v[16:19], v[16:19], v[202:205], v[140:143]
	v_mfma_f32_16x16x32_bf16 v[120:123], v[180:183], v[192:195], v[48:51]
	v_mfma_f32_16x16x32_bf16 v[48:51], v[184:187], v[164:167], v[214:217]
	v_mfma_f32_16x16x32_bf16 v[124:127], v[180:183], v[218:221], v[16:19]
	v_mfma_f32_16x16x32_bf16 v[16:19], v[184:187], v[202:205], v[32:35]
	v_mfma_f32_16x16x32_bf16 v[100:103], v[180:183], v[136:139], v[60:63]
	v_mfma_f32_16x16x32_bf16 v[112:115], v[180:183], v[160:163], v[56:59]
	v_mfma_f32_16x16x32_bf16 v[76:79], v[188:191], v[192:195], v[48:51]
	v_mfma_f32_16x16x32_bf16 v[68:71], v[188:191], v[218:221], v[16:19]
	v_mfma_f32_16x16x32_bf16 v[16:19], v[128:131], v[64:67], v[144:147]
	v_mfma_f32_16x16x32_bf16 v[48:51], v[222:225], v[136:139], v[16:19]
	v_mfma_f32_16x16x32_bf16 v[16:19], v[228:231], v[64:67], v[24:27]
	v_mfma_f32_16x16x32_bf16 v[20:23], v[128:131], v[156:159], v[20:23]
	v_mfma_f32_16x16x32_bf16 v[24:27], v[128:131], v[164:167], v[152:155]
	v_mfma_f32_16x16x32_bf16 v[32:35], v[128:131], v[202:205], v[172:175]
	v_mfma_f32_16x16x32_bf16 v[56:59], v[222:225], v[160:163], v[20:23]
	v_mfma_f32_16x16x32_bf16 v[20:23], v[228:231], v[156:159], v[148:151]
	v_mfma_f32_16x16x32_bf16 v[60:63], v[222:225], v[192:195], v[24:27]
	v_mfma_f32_16x16x32_bf16 v[24:27], v[228:231], v[164:167], v[168:171]
	v_mfma_f32_16x16x32_bf16 v[64:67], v[222:225], v[218:221], v[32:35]
	v_mfma_f32_16x16x32_bf16 v[32:35], v[228:231], v[202:205], v[176:179]
	v_mfma_f32_16x16x32_bf16 v[16:19], v[232:235], v[136:139], v[16:19]
	v_mfma_f32_16x16x32_bf16 v[20:23], v[232:235], v[160:163], v[20:23]
	v_mfma_f32_16x16x32_bf16 v[24:27], v[232:235], v[192:195], v[24:27]
	v_mfma_f32_16x16x32_bf16 v[32:35], v[232:235], v[218:221], v[32:35]
	s_movk_i32 s9, 0x100
	v_cmp_gt_u32_e32 vcc, s9, v132
	s_barrier
	s_and_saveexec_b64 s[28:29], vcc
	s_cbranch_execz .LBB0_212
	s_barrier
	s_branch .LBB0_212

.LBB0_314:
	ds_read_b128 v[172:175], v170
	ds_read_b128 v[176:179], v170 offset:1024
	ds_read_b128 v[180:183], v170 offset:2048
	ds_read_b128 v[184:187], v170 offset:3072
	s_add_u32 s8, s37, vcc_lo
	s_addc_u32 s9, s38, vcc_hi
	ds_read_b128 v[188:191], v166
	ds_read_b128 v[192:195], v166 offset:1024
	ds_read_b128 v[202:205], v165
	ds_read_b128 v[206:209], v165 offset:1024
	ds_read_b128 v[210:213], v163
	ds_read_b128 v[214:217], v163 offset:1024
	ds_read_b128 v[218:221], v162
	ds_read_b128 v[236:239], v162 offset:1024
	s_add_i32 s40, s34, 0xc000
	s_mov_b32 m0, s40
	s_add_i32 s41, s34, 0xe000
	s_add_u32 s98, s8, s94
	s_addc_u32 s99, s9, s95
	global_load_lds_dwordx4 v160, s[98:99]
	s_mov_b32 m0, s41
	s_nop 0
	global_load_lds_dwordx4 v161, s[98:99]
	s_waitcnt lgkmcnt(8)
	s_barrier
	s_waitcnt lgkmcnt(0)
	s_waitcnt lgkmcnt(0)
	v_mfma_f32_16x16x32_bf16 v[44:47], v[172:175], v[188:191], v[44:47]
	v_mfma_f32_16x16x32_bf16 v[40:43], v[180:183], v[188:191], v[40:43]
	v_mfma_f32_16x16x32_bf16 v[60:63], v[172:175], v[202:205], v[60:63]
	v_mfma_f32_16x16x32_bf16 v[56:59], v[180:183], v[202:205], v[56:59]
	v_mfma_f32_16x16x32_bf16 v[76:79], v[172:175], v[210:213], v[76:79]
	v_mfma_f32_16x16x32_bf16 v[72:75], v[180:183], v[210:213], v[72:75]
	v_mfma_f32_16x16x32_bf16 v[92:95], v[172:175], v[218:221], v[92:95]
	v_mfma_f32_16x16x32_bf16 v[88:91], v[180:183], v[218:221], v[88:91]
	v_mfma_f32_16x16x32_bf16 v[44:47], v[176:179], v[192:195], v[44:47]
	v_mfma_f32_16x16x32_bf16 v[40:43], v[184:187], v[192:195], v[40:43]
	v_mfma_f32_16x16x32_bf16 v[60:63], v[176:179], v[206:209], v[60:63]
	v_mfma_f32_16x16x32_bf16 v[56:59], v[184:187], v[206:209], v[56:59]
	v_mfma_f32_16x16x32_bf16 v[76:79], v[176:179], v[214:217], v[76:79]
	v_mfma_f32_16x16x32_bf16 v[72:75], v[184:187], v[214:217], v[72:75]
	v_mfma_f32_16x16x32_bf16 v[92:95], v[176:179], v[236:239], v[92:95]
	v_mfma_f32_16x16x32_bf16 v[88:91], v[184:187], v[236:239], v[88:91]
	s_barrier
	s_add_i32 s39, s39, 2
	s_add_u32 s28, s6, vcc_lo
	s_addc_u32 s29, s7, vcc_hi
	ds_read_b128 v[240:243], v169
	ds_read_b128 v[244:247], v169 offset:1024
	ds_read_b128 v[248:251], v169 offset:2048
	ds_read_b128 v[228:231], v169 offset:3072
	s_mov_b32 m0, s59
	s_add_u32 s98, s28, s0
	s_addc_u32 s99, s29, s1
	global_load_lds_dwordx4 v160, s[98:99]
	s_mov_b32 m0, s61
	s_nop 0
	global_load_lds_dwordx4 v161, s[98:99]
	s_barrier
	s_waitcnt lgkmcnt(0)
	s_waitcnt lgkmcnt(0)
	v_mfma_f32_16x16x32_bf16 v[32:35], v[240:243], v[188:191], v[32:35]
	v_mfma_f32_16x16x32_bf16 v[36:39], v[248:251], v[188:191], v[36:39]
	v_mfma_f32_16x16x32_bf16 v[48:51], v[240:243], v[202:205], v[48:51]
	v_mfma_f32_16x16x32_bf16 v[52:55], v[248:251], v[202:205], v[52:55]
	v_mfma_f32_16x16x32_bf16 v[64:67], v[240:243], v[210:213], v[64:67]
	v_mfma_f32_16x16x32_bf16 v[68:71], v[248:251], v[210:213], v[68:71]
	v_mfma_f32_16x16x32_bf16 v[80:83], v[240:243], v[218:221], v[80:83]
	v_mfma_f32_16x16x32_bf16 v[84:87], v[248:251], v[218:221], v[84:87]
	v_mfma_f32_16x16x32_bf16 v[32:35], v[244:247], v[192:195], v[32:35]
	v_mfma_f32_16x16x32_bf16 v[36:39], v[228:231], v[192:195], v[36:39]
	v_mfma_f32_16x16x32_bf16 v[48:51], v[244:247], v[206:209], v[48:51]
	v_mfma_f32_16x16x32_bf16 v[52:55], v[228:231], v[206:209], v[52:55]
	v_mfma_f32_16x16x32_bf16 v[64:67], v[244:247], v[214:217], v[64:67]
	v_mfma_f32_16x16x32_bf16 v[68:71], v[228:231], v[214:217], v[68:71]
	v_mfma_f32_16x16x32_bf16 v[80:83], v[244:247], v[236:239], v[80:83]
	v_mfma_f32_16x16x32_bf16 v[84:87], v[228:231], v[236:239], v[84:87]
	s_add_u32 s92, s90, vcc_lo
	s_addc_u32 s93, s91, vcc_hi
	s_barrier
	ds_read_b128 v[188:191], v166 offset:16384
	ds_read_b128 v[192:195], v166 offset:17408
	ds_read_b128 v[202:205], v165 offset:16384
	ds_read_b128 v[206:209], v165 offset:17408
	ds_read_b128 v[210:213], v163 offset:16384
	ds_read_b128 v[214:217], v163 offset:17408
	ds_read_b128 v[218:221], v162 offset:16384
	ds_read_b128 v[236:239], v162 offset:17408
	s_mov_b32 m0, s34
	s_add_u32 s98, s92, s0
	s_addc_u32 s99, s93, s1
	global_load_lds_dwordx4 v160, s[98:99]
	s_mov_b32 m0, s79
	s_nop 0
	global_load_lds_dwordx4 v161, s[98:99]
	s_barrier
	s_waitcnt lgkmcnt(0)
	s_waitcnt lgkmcnt(0)
	v_mfma_f32_16x16x32_bf16 v[108:111], v[172:175], v[188:191], v[108:111]
	v_mfma_f32_16x16x32_bf16 v[104:107], v[180:183], v[188:191], v[104:107]
	v_mfma_f32_16x16x32_bf16 v[124:127], v[172:175], v[202:205], v[124:127]
	v_mfma_f32_16x16x32_bf16 v[120:123], v[180:183], v[202:205], v[120:123]
	v_mfma_f32_16x16x32_bf16 v[140:143], v[172:175], v[210:213], v[140:143]
	v_mfma_f32_16x16x32_bf16 v[136:139], v[180:183], v[210:213], v[136:139]
	v_mfma_f32_16x16x32_bf16 v[156:159], v[172:175], v[218:221], v[156:159]
	v_mfma_f32_16x16x32_bf16 v[152:155], v[180:183], v[218:221], v[152:155]
	v_mfma_f32_16x16x32_bf16 v[108:111], v[176:179], v[192:195], v[108:111]
	v_mfma_f32_16x16x32_bf16 v[104:107], v[184:187], v[192:195], v[104:107]
	v_mfma_f32_16x16x32_bf16 v[124:127], v[176:179], v[206:209], v[124:127]
	v_mfma_f32_16x16x32_bf16 v[120:123], v[184:187], v[206:209], v[120:123]
	v_mfma_f32_16x16x32_bf16 v[140:143], v[176:179], v[214:217], v[140:143]
	v_mfma_f32_16x16x32_bf16 v[136:139], v[184:187], v[214:217], v[136:139]
	v_mfma_f32_16x16x32_bf16 v[156:159], v[176:179], v[236:239], v[156:159]
	v_mfma_f32_16x16x32_bf16 v[152:155], v[184:187], v[236:239], v[152:155]
	s_barrier
	s_add_u32 s96, s82, vcc_lo
	s_addc_u32 s97, s36, vcc_hi
	s_mov_b32 m0, s52
	s_add_u32 s98, s96, s0
	s_addc_u32 s99, s97, s1
	global_load_lds_dwordx4 v160, s[98:99]
	s_mov_b32 m0, s53
	s_nop 0
	global_load_lds_dwordx4 v161, s[98:99]
	s_waitcnt vmcnt(6)
	s_barrier
	v_mfma_f32_16x16x32_bf16 v[96:99], v[240:243], v[188:191], v[96:99]
	v_mfma_f32_16x16x32_bf16 v[100:103], v[248:251], v[188:191], v[100:103]
	v_mfma_f32_16x16x32_bf16 v[112:115], v[240:243], v[202:205], v[112:115]
	v_mfma_f32_16x16x32_bf16 v[116:119], v[248:251], v[202:205], v[116:119]
	v_mfma_f32_16x16x32_bf16 v[128:131], v[240:243], v[210:213], v[128:131]
	v_mfma_f32_16x16x32_bf16 v[132:135], v[248:251], v[210:213], v[132:135]
	v_mfma_f32_16x16x32_bf16 v[144:147], v[240:243], v[218:221], v[144:147]
	v_mfma_f32_16x16x32_bf16 v[148:151], v[248:251], v[218:221], v[148:151]
	v_mfma_f32_16x16x32_bf16 v[96:99], v[244:247], v[192:195], v[96:99]
	v_mfma_f32_16x16x32_bf16 v[100:103], v[228:231], v[192:195], v[100:103]
	v_mfma_f32_16x16x32_bf16 v[112:115], v[244:247], v[206:209], v[112:115]
	v_mfma_f32_16x16x32_bf16 v[116:119], v[228:231], v[206:209], v[116:119]
	v_mfma_f32_16x16x32_bf16 v[128:131], v[244:247], v[214:217], v[128:131]
	v_mfma_f32_16x16x32_bf16 v[132:135], v[228:231], v[214:217], v[132:135]
	v_mfma_f32_16x16x32_bf16 v[144:147], v[244:247], v[236:239], v[144:147]
	v_mfma_f32_16x16x32_bf16 v[148:151], v[228:231], v[236:239], v[148:151]
	s_barrier
	ds_read_b128 v[172:175], v168
	ds_read_b128 v[176:179], v168 offset:1024
	ds_read_b128 v[180:183], v168 offset:2048
	ds_read_b128 v[184:187], v168 offset:3072
	ds_read_b128 v[188:191], v166 offset:32768
	ds_read_b128 v[192:195], v166 offset:33792
	ds_read_b128 v[202:205], v165 offset:32768
	ds_read_b128 v[206:209], v165 offset:33792
	ds_read_b128 v[210:213], v163 offset:32768
	ds_read_b128 v[214:217], v163 offset:33792
	ds_read_b128 v[218:221], v162 offset:32768
	ds_read_b128 v[228:231], v162 offset:33792
	s_mov_b32 m0, s68
	s_add_u32 s98, s8, s0
	s_addc_u32 s99, s9, s1
	global_load_lds_dwordx4 v160, s[98:99]
	s_mov_b32 m0, s69
	s_nop 0
	global_load_lds_dwordx4 v161, s[98:99]
	s_waitcnt lgkmcnt(8)
	s_barrier
	s_waitcnt lgkmcnt(0)
	s_waitcnt lgkmcnt(0)
	v_mfma_f32_16x16x32_bf16 v[44:47], v[172:175], v[188:191], v[44:47]
	v_mfma_f32_16x16x32_bf16 v[40:43], v[180:183], v[188:191], v[40:43]
	v_mfma_f32_16x16x32_bf16 v[60:63], v[172:175], v[202:205], v[60:63]
	v_mfma_f32_16x16x32_bf16 v[56:59], v[180:183], v[202:205], v[56:59]
	v_mfma_f32_16x16x32_bf16 v[76:79], v[172:175], v[210:213], v[76:79]
	v_mfma_f32_16x16x32_bf16 v[72:75], v[180:183], v[210:213], v[72:75]
	v_mfma_f32_16x16x32_bf16 v[92:95], v[172:175], v[218:221], v[92:95]
	v_mfma_f32_16x16x32_bf16 v[88:91], v[180:183], v[218:221], v[88:91]
	v_mfma_f32_16x16x32_bf16 v[44:47], v[176:179], v[192:195], v[44:47]
	v_mfma_f32_16x16x32_bf16 v[40:43], v[184:187], v[192:195], v[40:43]
	v_mfma_f32_16x16x32_bf16 v[60:63], v[176:179], v[206:209], v[60:63]
	v_mfma_f32_16x16x32_bf16 v[56:59], v[184:187], v[206:209], v[56:59]
	v_mfma_f32_16x16x32_bf16 v[76:79], v[176:179], v[214:217], v[76:79]
	v_mfma_f32_16x16x32_bf16 v[72:75], v[184:187], v[214:217], v[72:75]
	v_mfma_f32_16x16x32_bf16 v[92:95], v[176:179], v[228:231], v[92:95]
	v_mfma_f32_16x16x32_bf16 v[88:91], v[184:187], v[228:231], v[88:91]
	s_barrier
	ds_read_b128 v[236:239], v167
	ds_read_b128 v[240:243], v167 offset:1024
	ds_read_b128 v[244:247], v167 offset:2048
	ds_read_b128 v[248:251], v167 offset:3072
	s_mov_b32 m0, s70
	s_add_u32 s98, s28, s30
	s_addc_u32 s99, s29, s31
	global_load_lds_dwordx4 v160, s[98:99]
	s_mov_b32 m0, s71
	s_nop 0
	global_load_lds_dwordx4 v161, s[98:99]
	s_barrier
	s_waitcnt lgkmcnt(0)
	s_waitcnt lgkmcnt(0)
	v_mfma_f32_16x16x32_bf16 v[32:35], v[236:239], v[188:191], v[32:35]
	v_mfma_f32_16x16x32_bf16 v[36:39], v[244:247], v[188:191], v[36:39]
	v_mfma_f32_16x16x32_bf16 v[48:51], v[236:239], v[202:205], v[48:51]
	v_mfma_f32_16x16x32_bf16 v[52:55], v[244:247], v[202:205], v[52:55]
	v_mfma_f32_16x16x32_bf16 v[64:67], v[236:239], v[210:213], v[64:67]
	v_mfma_f32_16x16x32_bf16 v[68:71], v[244:247], v[210:213], v[68:71]
	v_mfma_f32_16x16x32_bf16 v[80:83], v[236:239], v[218:221], v[80:83]
	v_mfma_f32_16x16x32_bf16 v[84:87], v[244:247], v[218:221], v[84:87]
	v_mfma_f32_16x16x32_bf16 v[32:35], v[240:243], v[192:195], v[32:35]
	v_mfma_f32_16x16x32_bf16 v[36:39], v[248:251], v[192:195], v[36:39]
	v_mfma_f32_16x16x32_bf16 v[48:51], v[240:243], v[206:209], v[48:51]
	v_mfma_f32_16x16x32_bf16 v[52:55], v[248:251], v[206:209], v[52:55]
	v_mfma_f32_16x16x32_bf16 v[64:67], v[240:243], v[214:217], v[64:67]
	v_mfma_f32_16x16x32_bf16 v[68:71], v[248:251], v[214:217], v[68:71]
	v_mfma_f32_16x16x32_bf16 v[80:83], v[240:243], v[228:231], v[80:83]
	v_mfma_f32_16x16x32_bf16 v[84:87], v[248:251], v[228:231], v[84:87]
	v_mov_b32_e32 v222, v161
	s_barrier
	ds_read_b128 v[188:191], v166 offset:49152
	ds_read_b128 v[192:195], v166 offset:50176
	ds_read_b128 v[202:205], v165 offset:49152
	ds_read_b128 v[206:209], v165 offset:50176
	ds_read_b128 v[210:213], v163 offset:49152
	ds_read_b128 v[214:217], v163 offset:50176
	ds_read_b128 v[218:221], v162 offset:49152
	ds_read_b128 v[228:231], v162 offset:50176
	v_mov_b32_e32 v223, v197
	s_mov_b32 m0, s72
	s_add_u32 s98, s92, s30
	s_addc_u32 s99, s93, s31
	global_load_lds_dwordx4 v160, s[98:99]
	s_mov_b32 m0, s73
	s_nop 0
	global_load_lds_dwordx4 v161, s[98:99]
	s_barrier
	s_waitcnt lgkmcnt(0)
	s_waitcnt lgkmcnt(0)
	v_mfma_f32_16x16x32_bf16 v[108:111], v[172:175], v[188:191], v[108:111]
	v_mfma_f32_16x16x32_bf16 v[104:107], v[180:183], v[188:191], v[104:107]
	v_mfma_f32_16x16x32_bf16 v[124:127], v[172:175], v[202:205], v[124:127]
	v_mfma_f32_16x16x32_bf16 v[120:123], v[180:183], v[202:205], v[120:123]
	v_mfma_f32_16x16x32_bf16 v[140:143], v[172:175], v[210:213], v[140:143]
	v_mfma_f32_16x16x32_bf16 v[136:139], v[180:183], v[210:213], v[136:139]
	v_mfma_f32_16x16x32_bf16 v[156:159], v[172:175], v[218:221], v[156:159]
	v_mfma_f32_16x16x32_bf16 v[152:155], v[180:183], v[218:221], v[152:155]
	v_mfma_f32_16x16x32_bf16 v[108:111], v[176:179], v[192:195], v[108:111]
	v_mfma_f32_16x16x32_bf16 v[104:107], v[184:187], v[192:195], v[104:107]
	v_mfma_f32_16x16x32_bf16 v[124:127], v[176:179], v[206:209], v[124:127]
	v_mfma_f32_16x16x32_bf16 v[120:123], v[184:187], v[206:209], v[120:123]
	v_mfma_f32_16x16x32_bf16 v[140:143], v[176:179], v[214:217], v[140:143]
	v_mfma_f32_16x16x32_bf16 v[136:139], v[184:187], v[214:217], v[136:139]
	v_mfma_f32_16x16x32_bf16 v[156:159], v[176:179], v[228:231], v[156:159]
	v_mfma_f32_16x16x32_bf16 v[152:155], v[184:187], v[228:231], v[152:155]
	s_barrier
	v_mov_b32_e32 v196, v160
	s_mov_b32 m0, s75
	s_add_u32 s98, s96, s30
	s_addc_u32 s99, s97, s31
	global_load_lds_dwordx4 v160, s[98:99]
	s_mov_b32 m0, s89
	s_nop 0
	global_load_lds_dwordx4 v161, s[98:99]
	s_waitcnt vmcnt(6)
	s_barrier
	v_mfma_f32_16x16x32_bf16 v[96:99], v[236:239], v[188:191], v[96:99]
	v_mfma_f32_16x16x32_bf16 v[100:103], v[244:247], v[188:191], v[100:103]
	v_mfma_f32_16x16x32_bf16 v[112:115], v[236:239], v[202:205], v[112:115]
	v_mfma_f32_16x16x32_bf16 v[116:119], v[244:247], v[202:205], v[116:119]
	v_mfma_f32_16x16x32_bf16 v[128:131], v[236:239], v[210:213], v[128:131]
	v_mfma_f32_16x16x32_bf16 v[132:135], v[244:247], v[210:213], v[132:135]
	v_mfma_f32_16x16x32_bf16 v[144:147], v[236:239], v[218:221], v[144:147]
	v_mfma_f32_16x16x32_bf16 v[148:151], v[244:247], v[218:221], v[148:151]
	v_mfma_f32_16x16x32_bf16 v[96:99], v[240:243], v[192:195], v[96:99]
	v_mfma_f32_16x16x32_bf16 v[100:103], v[248:251], v[192:195], v[100:103]
	v_mfma_f32_16x16x32_bf16 v[112:115], v[240:243], v[206:209], v[112:115]
	v_mfma_f32_16x16x32_bf16 v[116:119], v[248:251], v[206:209], v[116:119]
	v_mfma_f32_16x16x32_bf16 v[128:131], v[240:243], v[214:217], v[128:131]
	v_mfma_f32_16x16x32_bf16 v[132:135], v[248:251], v[214:217], v[132:135]
	v_mfma_f32_16x16x32_bf16 v[144:147], v[240:243], v[228:231], v[144:147]
	v_mfma_f32_16x16x32_bf16 v[148:151], v[248:251], v[228:231], v[148:151]
	s_add_u32 vcc_lo, vcc_lo, 0x100
	s_addc_u32 vcc_hi, vcc_hi, 0
	s_cmp_lt_u32 s39, s74
	s_barrier
	s_cbranch_scc1 .LBB0_314
	s_add_i32 s34, s33, -1
	s_lshl_b64 s[6:7], s[34:35], 7
	s_add_u32 s6, s84, s6
	s_addc_u32 s7, s85, s7
	s_mov_b32 m0, s40
	ds_read_b128 v[172:175], v170
	ds_read_b128 v[176:179], v170 offset:1024
	ds_read_b128 v[180:183], v170 offset:2048
	ds_read_b128 v[184:187], v170 offset:3072
	ds_read_b128 v[188:191], v166
	ds_read_b128 v[192:195], v166 offset:1024
	ds_read_b128 v[202:205], v165
	ds_read_b128 v[206:209], v165 offset:1024
	ds_read_b128 v[210:213], v163
	ds_read_b128 v[214:217], v163 offset:1024
	ds_read_b128 v[218:221], v162
	ds_read_b128 v[228:231], v162 offset:1024
	s_nop 0
	global_load_lds_dwordx4 v160, s[6:7]
	s_mov_b32 m0, s41
	s_nop 0
	global_load_lds_dwordx4 v161, s[6:7]
	s_barrier
	s_waitcnt lgkmcnt(0)
	s_waitcnt lgkmcnt(0)
	v_mfma_f32_16x16x32_bf16 v[40:43], v[180:183], v[188:191], v[40:43]
	v_mfma_f32_16x16x32_bf16 v[56:59], v[180:183], v[202:205], v[56:59]
	v_mfma_f32_16x16x32_bf16 v[72:75], v[180:183], v[210:213], v[72:75]
	v_mfma_f32_16x16x32_bf16 v[92:95], v[172:175], v[218:221], v[92:95]
	v_mfma_f32_16x16x32_bf16 v[88:91], v[180:183], v[218:221], v[88:91]
	v_mfma_f32_16x16x32_bf16 v[44:47], v[172:175], v[188:191], v[44:47]
	v_mfma_f32_16x16x32_bf16 v[40:43], v[184:187], v[192:195], v[40:43]
	v_mfma_f32_16x16x32_bf16 v[60:63], v[172:175], v[202:205], v[60:63]
	v_mfma_f32_16x16x32_bf16 v[56:59], v[184:187], v[206:209], v[56:59]
	v_mfma_f32_16x16x32_bf16 v[76:79], v[172:175], v[210:213], v[76:79]
	v_mfma_f32_16x16x32_bf16 v[72:75], v[184:187], v[214:217], v[72:75]
	v_mfma_f32_16x16x32_bf16 v[92:95], v[176:179], v[228:231], v[92:95]
	v_mfma_f32_16x16x32_bf16 v[88:91], v[184:187], v[228:231], v[88:91]
	v_mfma_f32_16x16x32_bf16 v[44:47], v[176:179], v[192:195], v[44:47]
	v_mfma_f32_16x16x32_bf16 v[60:63], v[176:179], v[206:209], v[60:63]
	v_mfma_f32_16x16x32_bf16 v[76:79], v[176:179], v[214:217], v[76:79]
	s_barrier
	ds_read_b128 v[236:239], v169
	ds_read_b128 v[240:243], v169 offset:1024
	ds_read_b128 v[244:247], v169 offset:2048
	ds_read_b128 v[248:251], v169 offset:3072
	s_barrier
	s_waitcnt lgkmcnt(0)
	s_waitcnt lgkmcnt(0)
	v_mfma_f32_16x16x32_bf16 v[36:39], v[244:247], v[188:191], v[36:39]
	v_mfma_f32_16x16x32_bf16 v[32:35], v[236:239], v[188:191], v[32:35]
	v_mfma_f32_16x16x32_bf16 v[188:191], v[248:251], v[192:195], v[36:39]
	v_mfma_f32_16x16x32_bf16 v[36:39], v[236:239], v[202:205], v[48:51]
	v_mfma_f32_16x16x32_bf16 v[48:51], v[240:243], v[206:209], v[36:39]
	v_mfma_f32_16x16x32_bf16 v[36:39], v[244:247], v[202:205], v[52:55]
	v_mfma_f32_16x16x32_bf16 v[32:35], v[240:243], v[192:195], v[32:35]
	v_mfma_f32_16x16x32_bf16 v[192:195], v[248:251], v[206:209], v[36:39]
	v_mfma_f32_16x16x32_bf16 v[36:39], v[236:239], v[210:213], v[64:67]
	v_mfma_f32_16x16x32_bf16 v[64:67], v[240:243], v[214:217], v[36:39]
	v_mfma_f32_16x16x32_bf16 v[36:39], v[244:247], v[210:213], v[68:71]
	v_mfma_f32_16x16x32_bf16 v[202:205], v[248:251], v[214:217], v[36:39]
	v_mfma_f32_16x16x32_bf16 v[36:39], v[236:239], v[218:221], v[80:83]
	v_mfma_f32_16x16x32_bf16 v[80:83], v[240:243], v[228:231], v[36:39]
	v_mfma_f32_16x16x32_bf16 v[36:39], v[244:247], v[218:221], v[84:87]
	v_mfma_f32_16x16x32_bf16 v[206:209], v[248:251], v[228:231], v[36:39]
	s_barrier
	s_nop 4
	ds_read_b128 v[36:39], v166 offset:16384
	ds_read_b128 v[52:55], v166 offset:17408
	ds_read_b128 v[68:71], v165 offset:16384
	ds_read_b128 v[84:87], v165 offset:17408
	ds_read_b128 v[210:213], v163 offset:16384
	ds_read_b128 v[214:217], v163 offset:17408
	ds_read_b128 v[218:221], v162 offset:16384
	ds_read_b128 v[228:231], v162 offset:17408
	s_waitcnt vmcnt(4)
	s_barrier
	s_waitcnt lgkmcnt(0)
	s_waitcnt lgkmcnt(0)
	v_mfma_f32_16x16x32_bf16 v[108:111], v[172:175], v[36:39], v[108:111]
	v_mfma_f32_16x16x32_bf16 v[222:225], v[176:179], v[52:55], v[108:111]
	v_mfma_f32_16x16x32_bf16 v[108:111], v[172:175], v[68:71], v[124:127]
	v_mfma_f32_16x16x32_bf16 v[124:127], v[176:179], v[84:87], v[108:111]
	v_mfma_f32_16x16x32_bf16 v[108:111], v[180:183], v[68:71], v[120:123]
	v_mfma_f32_16x16x32_bf16 v[120:123], v[184:187], v[84:87], v[108:111]
	v_mfma_f32_16x16x32_bf16 v[108:111], v[172:175], v[210:213], v[140:143]
	v_mfma_f32_16x16x32_bf16 v[140:143], v[176:179], v[214:217], v[108:111]
	v_mfma_f32_16x16x32_bf16 v[108:111], v[180:183], v[210:213], v[136:139]
	v_mfma_f32_16x16x32_bf16 v[136:139], v[184:187], v[214:217], v[108:111]
	v_mfma_f32_16x16x32_bf16 v[108:111], v[172:175], v[218:221], v[156:159]
	v_mfma_f32_16x16x32_bf16 v[104:107], v[180:183], v[36:39], v[104:107]
	v_mfma_f32_16x16x32_bf16 v[156:159], v[176:179], v[228:231], v[108:111]
	v_mfma_f32_16x16x32_bf16 v[108:111], v[180:183], v[218:221], v[152:155]
	v_mfma_f32_16x16x32_bf16 v[104:107], v[184:187], v[52:55], v[104:107]
	v_mfma_f32_16x16x32_bf16 v[152:155], v[184:187], v[228:231], v[108:111]
	v_mfma_f32_16x16x32_bf16 v[96:99], v[236:239], v[36:39], v[96:99]
	v_mfma_f32_16x16x32_bf16 v[36:39], v[244:247], v[36:39], v[100:103]
	v_mfma_f32_16x16x32_bf16 v[172:175], v[248:251], v[52:55], v[36:39]
	v_mfma_f32_16x16x32_bf16 v[36:39], v[236:239], v[68:71], v[112:115]
	v_mfma_f32_16x16x32_bf16 v[112:115], v[240:243], v[84:87], v[36:39]
	v_mfma_f32_16x16x32_bf16 v[36:39], v[244:247], v[68:71], v[116:119]
	v_mfma_f32_16x16x32_bf16 v[180:183], v[248:251], v[84:87], v[36:39]
	v_mfma_f32_16x16x32_bf16 v[36:39], v[236:239], v[210:213], v[128:131]
	v_mfma_f32_16x16x32_bf16 v[128:131], v[240:243], v[214:217], v[36:39]
	v_mfma_f32_16x16x32_bf16 v[36:39], v[244:247], v[210:213], v[132:135]
	v_mfma_f32_16x16x32_bf16 v[184:187], v[248:251], v[214:217], v[36:39]
	v_mfma_f32_16x16x32_bf16 v[36:39], v[236:239], v[218:221], v[144:147]
	v_mfma_f32_16x16x32_bf16 v[96:99], v[240:243], v[52:55], v[96:99]
	v_mfma_f32_16x16x32_bf16 v[144:147], v[240:243], v[228:231], v[36:39]
	v_mfma_f32_16x16x32_bf16 v[36:39], v[244:247], v[218:221], v[148:151]
	v_mfma_f32_16x16x32_bf16 v[210:213], v[248:251], v[228:231], v[36:39]
	s_barrier
	ds_read_b128 v[148:151], v168
	ds_read_b128 v[214:217], v168 offset:1024
	ds_read_b128 v[218:221], v168 offset:2048
	ds_read_b128 v[228:231], v168 offset:3072
	ds_read_b128 v[100:103], v166 offset:32768
	ds_read_b128 v[108:111], v166 offset:33792
	ds_read_b128 v[116:119], v165 offset:32768
	ds_read_b128 v[132:135], v165 offset:33792
	ds_read_b128 v[236:239], v163 offset:32768
	ds_read_b128 v[240:243], v163 offset:33792
	ds_read_b128 v[244:247], v162 offset:32768
	ds_read_b128 v[248:251], v162 offset:33792
	s_waitcnt vmcnt(2)
	s_barrier
	s_waitcnt lgkmcnt(0)
	s_waitcnt lgkmcnt(0)
	v_mfma_f32_16x16x32_bf16 v[36:39], v[148:151], v[100:103], v[44:47]
	v_mfma_f32_16x16x32_bf16 v[44:47], v[148:151], v[116:119], v[60:63]
	v_mfma_f32_16x16x32_bf16 v[52:55], v[214:217], v[132:135], v[44:47]
	v_mfma_f32_16x16x32_bf16 v[44:47], v[218:221], v[116:119], v[56:59]
	v_mfma_f32_16x16x32_bf16 v[56:59], v[228:231], v[132:135], v[44:47]
	v_mfma_f32_16x16x32_bf16 v[44:47], v[148:151], v[236:239], v[76:79]
	v_mfma_f32_16x16x32_bf16 v[68:71], v[214:217], v[240:243], v[44:47]
	v_mfma_f32_16x16x32_bf16 v[44:47], v[218:221], v[236:239], v[72:75]
	v_mfma_f32_16x16x32_bf16 v[72:75], v[228:231], v[240:243], v[44:47]
	v_mfma_f32_16x16x32_bf16 v[44:47], v[148:151], v[244:247], v[92:95]
	v_mfma_f32_16x16x32_bf16 v[40:43], v[218:221], v[100:103], v[40:43]
	v_mfma_f32_16x16x32_bf16 v[84:87], v[214:217], v[248:251], v[44:47]
	v_mfma_f32_16x16x32_bf16 v[44:47], v[218:221], v[244:247], v[88:91]
	v_mfma_f32_16x16x32_bf16 v[36:39], v[214:217], v[108:111], v[36:39]
	v_mfma_f32_16x16x32_bf16 v[40:43], v[228:231], v[108:111], v[40:43]
	v_mfma_f32_16x16x32_bf16 v[88:91], v[228:231], v[248:251], v[44:47]
	s_barrier
	s_nop 2
	ds_read_b128 v[44:47], v167
	ds_read_b128 v[60:63], v167 offset:1024
	ds_read_b128 v[76:79], v167 offset:2048
	ds_read_b128 v[232:235], v167 offset:3072
	s_waitcnt vmcnt(0)
	s_barrier
	s_waitcnt lgkmcnt(0)
	s_waitcnt lgkmcnt(0)
	v_mfma_f32_16x16x32_bf16 v[92:95], v[76:79], v[100:103], v[188:191]
	v_mfma_f32_16x16x32_bf16 v[176:179], v[232:235], v[108:111], v[92:95]
	v_mfma_f32_16x16x32_bf16 v[92:95], v[76:79], v[116:119], v[192:195]
	v_mfma_f32_16x16x32_bf16 v[32:35], v[44:47], v[100:103], v[32:35]
	v_mfma_f32_16x16x32_bf16 v[48:51], v[44:47], v[116:119], v[48:51]
	v_mfma_f32_16x16x32_bf16 v[168:171], v[232:235], v[132:135], v[92:95]
	v_mfma_f32_16x16x32_bf16 v[64:67], v[44:47], v[236:239], v[64:67]
	v_mfma_f32_16x16x32_bf16 v[92:95], v[76:79], v[236:239], v[202:205]
	v_mfma_f32_16x16x32_bf16 v[80:83], v[44:47], v[244:247], v[80:83]
	v_mfma_f32_16x16x32_bf16 v[100:103], v[76:79], v[244:247], v[206:209]
	v_mfma_f32_16x16x32_bf16 v[32:35], v[60:63], v[108:111], v[32:35]
	v_mfma_f32_16x16x32_bf16 v[48:51], v[60:63], v[132:135], v[48:51]
	v_mfma_f32_16x16x32_bf16 v[64:67], v[60:63], v[240:243], v[64:67]
	v_mfma_f32_16x16x32_bf16 v[92:95], v[232:235], v[240:243], v[92:95]
	v_mfma_f32_16x16x32_bf16 v[80:83], v[60:63], v[248:251], v[80:83]
	v_mfma_f32_16x16x32_bf16 v[108:111], v[232:235], v[248:251], v[100:103]
	s_barrier
	ds_read_b128 v[188:191], v166 offset:49152
	ds_read_b128 v[192:195], v166 offset:50176
	ds_read_b128 v[202:205], v165 offset:49152
	ds_read_b128 v[206:209], v165 offset:50176
	ds_read_b128 v[236:239], v163 offset:49152
	ds_read_b128 v[240:243], v163 offset:50176
	ds_read_b128 v[244:247], v162 offset:49152
	ds_read_b128 v[160:163], v162 offset:50176
	s_barrier
	s_waitcnt lgkmcnt(0)
	s_waitcnt lgkmcnt(0)
	v_mfma_f32_16x16x32_bf16 v[116:119], v[148:151], v[202:205], v[124:127]
	v_mfma_f32_16x16x32_bf16 v[124:127], v[148:151], v[236:239], v[140:143]
	v_mfma_f32_16x16x32_bf16 v[132:135], v[214:217], v[240:243], v[124:127]
	v_mfma_f32_16x16x32_bf16 v[124:127], v[218:221], v[236:239], v[136:139]
	v_mfma_f32_16x16x32_bf16 v[136:139], v[228:231], v[240:243], v[124:127]
	v_mfma_f32_16x16x32_bf16 v[124:127], v[148:151], v[244:247], v[156:159]
	v_mfma_f32_16x16x32_bf16 v[100:103], v[148:151], v[188:191], v[222:225]
	v_mfma_f32_16x16x32_bf16 v[104:107], v[218:221], v[188:191], v[104:107]
	v_mfma_f32_16x16x32_bf16 v[120:123], v[218:221], v[202:205], v[120:123]
	v_mfma_f32_16x16x32_bf16 v[148:151], v[214:217], v[160:163], v[124:127]
	v_mfma_f32_16x16x32_bf16 v[124:127], v[218:221], v[244:247], v[152:155]
	v_mfma_f32_16x16x32_bf16 v[100:103], v[214:217], v[192:195], v[100:103]
	v_mfma_f32_16x16x32_bf16 v[104:107], v[228:231], v[192:195], v[104:107]
	v_mfma_f32_16x16x32_bf16 v[116:119], v[214:217], v[206:209], v[116:119]
	v_mfma_f32_16x16x32_bf16 v[120:123], v[228:231], v[206:209], v[120:123]
	v_mfma_f32_16x16x32_bf16 v[152:155], v[228:231], v[160:163], v[124:127]
	v_mfma_f32_16x16x32_bf16 v[96:99], v[44:47], v[188:191], v[96:99]
	v_mfma_f32_16x16x32_bf16 v[112:115], v[44:47], v[202:205], v[112:115]
	v_mfma_f32_16x16x32_bf16 v[128:131], v[44:47], v[236:239], v[128:131]
	v_mfma_f32_16x16x32_bf16 v[44:47], v[44:47], v[244:247], v[144:147]
	v_mfma_f32_16x16x32_bf16 v[124:127], v[76:79], v[188:191], v[172:175]
	v_mfma_f32_16x16x32_bf16 v[140:143], v[76:79], v[202:205], v[180:183]
	v_mfma_f32_16x16x32_bf16 v[156:159], v[76:79], v[236:239], v[184:187]
	v_mfma_f32_16x16x32_bf16 v[144:147], v[60:63], v[160:163], v[44:47]
	v_mfma_f32_16x16x32_bf16 v[44:47], v[76:79], v[244:247], v[210:213]
	v_mfma_f32_16x16x32_bf16 v[96:99], v[60:63], v[192:195], v[96:99]
	v_mfma_f32_16x16x32_bf16 v[124:127], v[232:235], v[192:195], v[124:127]
	v_mfma_f32_16x16x32_bf16 v[112:115], v[60:63], v[206:209], v[112:115]
	v_mfma_f32_16x16x32_bf16 v[140:143], v[232:235], v[206:209], v[140:143]
	v_mfma_f32_16x16x32_bf16 v[128:131], v[60:63], v[240:243], v[128:131]
	v_mfma_f32_16x16x32_bf16 v[156:159], v[232:235], v[240:243], v[156:159]
	v_mfma_f32_16x16x32_bf16 v[160:163], v[232:235], v[160:163], v[44:47]
	s_movk_i32 s6, 0x100
	v_cmp_gt_u32_e32 vcc, s6, v164
	s_barrier
	s_and_saveexec_b64 s[6:7], vcc
	s_cbranch_execz .LBB0_317
	s_barrier

.LBB0_568:
	ds_read_b128 v[140:143], v129
	ds_read_b128 v[144:147], v129 offset:1024
	ds_read_b128 v[148:151], v129 offset:2048
	ds_read_b128 v[152:155], v129 offset:3072
	s_add_u32 s28, s8, s10
	s_addc_u32 s29, s9, s11
	ds_read_b128 v[156:159], v136
	ds_read_b128 v[160:163], v136 offset:1024
	ds_read_b128 v[164:167], v135
	ds_read_b128 v[168:171], v135 offset:1024
	ds_read_b128 v[172:175], v134
	ds_read_b128 v[176:179], v134 offset:1024
	ds_read_b128 v[180:183], v133
	ds_read_b128 v[184:187], v133 offset:1024
	s_add_i32 s39, s68, 0xc000
	s_mov_b32 m0, s39
	s_add_i32 s38, s68, 0xe000
	s_add_u32 s98, s28, s44
	s_addc_u32 s99, s29, s45
	global_load_lds_dwordx4 v128, s[98:99]
	s_mov_b32 m0, s38
	s_nop 0
	global_load_lds_dwordx4 v130, s[98:99]
	s_waitcnt lgkmcnt(8)
	s_barrier
	s_waitcnt lgkmcnt(0)
	s_waitcnt lgkmcnt(0)
	v_mfma_f32_16x16x32_bf16 v[124:127], v[140:143], v[156:159], v[124:127]
	v_mfma_f32_16x16x32_bf16 v[120:123], v[148:151], v[156:159], v[120:123]
	v_mfma_f32_16x16x32_bf16 v[116:119], v[140:143], v[164:167], v[116:119]
	v_mfma_f32_16x16x32_bf16 v[112:115], v[148:151], v[164:167], v[112:115]
	v_mfma_f32_16x16x32_bf16 v[108:111], v[140:143], v[172:175], v[108:111]
	v_mfma_f32_16x16x32_bf16 v[104:107], v[148:151], v[172:175], v[104:107]
	v_mfma_f32_16x16x32_bf16 v[100:103], v[140:143], v[180:183], v[100:103]
	v_mfma_f32_16x16x32_bf16 v[96:99], v[148:151], v[180:183], v[96:99]
	v_mfma_f32_16x16x32_bf16 v[124:127], v[144:147], v[160:163], v[124:127]
	v_mfma_f32_16x16x32_bf16 v[120:123], v[152:155], v[160:163], v[120:123]
	v_mfma_f32_16x16x32_bf16 v[116:119], v[144:147], v[168:171], v[116:119]
	v_mfma_f32_16x16x32_bf16 v[112:115], v[152:155], v[168:171], v[112:115]
	v_mfma_f32_16x16x32_bf16 v[108:111], v[144:147], v[176:179], v[108:111]
	v_mfma_f32_16x16x32_bf16 v[104:107], v[152:155], v[176:179], v[104:107]
	v_mfma_f32_16x16x32_bf16 v[100:103], v[144:147], v[184:187], v[100:103]
	v_mfma_f32_16x16x32_bf16 v[96:99], v[152:155], v[184:187], v[96:99]
	s_barrier
	s_add_u32 s56, s6, s10
	s_addc_u32 s57, s7, s11
	ds_read_b128 v[188:191], v139
	ds_read_b128 v[192:195], v139 offset:1024
	ds_read_b128 v[202:205], v139 offset:2048
	ds_read_b128 v[206:209], v139 offset:3072
	s_add_i32 m0, s68, 0x10000
	s_add_u32 s98, s56, s0
	s_addc_u32 s99, s57, s1
	global_load_lds_dwordx4 v128, s[98:99]
	s_add_i32 m0, s68, 0x12000
	s_nop 0
	global_load_lds_dwordx4 v130, s[98:99]
	s_barrier
	s_waitcnt lgkmcnt(0)
	s_waitcnt lgkmcnt(0)
	v_mfma_f32_16x16x32_bf16 v[92:95], v[188:191], v[156:159], v[92:95]
	v_mfma_f32_16x16x32_bf16 v[88:91], v[202:205], v[156:159], v[88:91]
	v_mfma_f32_16x16x32_bf16 v[84:87], v[188:191], v[164:167], v[84:87]
	v_mfma_f32_16x16x32_bf16 v[80:83], v[202:205], v[164:167], v[80:83]
	v_mfma_f32_16x16x32_bf16 v[76:79], v[188:191], v[172:175], v[76:79]
	v_mfma_f32_16x16x32_bf16 v[72:75], v[202:205], v[172:175], v[72:75]
	v_mfma_f32_16x16x32_bf16 v[68:71], v[188:191], v[180:183], v[68:71]
	v_mfma_f32_16x16x32_bf16 v[64:67], v[202:205], v[180:183], v[64:67]
	v_mfma_f32_16x16x32_bf16 v[92:95], v[192:195], v[160:163], v[92:95]
	v_mfma_f32_16x16x32_bf16 v[88:91], v[206:209], v[160:163], v[88:91]
	v_mfma_f32_16x16x32_bf16 v[84:87], v[192:195], v[168:171], v[84:87]
	v_mfma_f32_16x16x32_bf16 v[80:83], v[206:209], v[168:171], v[80:83]
	v_mfma_f32_16x16x32_bf16 v[76:79], v[192:195], v[176:179], v[76:79]
	v_mfma_f32_16x16x32_bf16 v[72:75], v[206:209], v[176:179], v[72:75]
	v_mfma_f32_16x16x32_bf16 v[68:71], v[192:195], v[184:187], v[68:71]
	v_mfma_f32_16x16x32_bf16 v[64:67], v[206:209], v[184:187], v[64:67]
	s_barrier
	ds_read_b128 v[156:159], v136 offset:16384
	ds_read_b128 v[160:163], v136 offset:17408
	ds_read_b128 v[164:167], v135 offset:16384
	ds_read_b128 v[168:171], v135 offset:17408
	ds_read_b128 v[172:175], v134 offset:16384
	ds_read_b128 v[176:179], v134 offset:17408
	ds_read_b128 v[180:183], v133 offset:16384
	ds_read_b128 v[184:187], v133 offset:17408
	s_mov_b32 m0, s68
	s_add_u32 s98, s28, s0
	s_addc_u32 s99, s29, s1
	global_load_lds_dwordx4 v128, s[98:99]
	s_add_i32 m0, s68, 0x2000
	s_nop 0
	global_load_lds_dwordx4 v130, s[98:99]
	s_barrier
	s_waitcnt lgkmcnt(0)
	s_waitcnt lgkmcnt(0)
	v_mfma_f32_16x16x32_bf16 v[60:63], v[140:143], v[156:159], v[60:63]
	v_mfma_f32_16x16x32_bf16 v[56:59], v[148:151], v[156:159], v[56:59]
	v_mfma_f32_16x16x32_bf16 v[52:55], v[140:143], v[164:167], v[52:55]
	v_mfma_f32_16x16x32_bf16 v[48:51], v[148:151], v[164:167], v[48:51]
	v_mfma_f32_16x16x32_bf16 v[44:47], v[140:143], v[172:175], v[44:47]
	v_mfma_f32_16x16x32_bf16 v[40:43], v[148:151], v[172:175], v[40:43]
	v_mfma_f32_16x16x32_bf16 v[36:39], v[140:143], v[180:183], v[36:39]
	v_mfma_f32_16x16x32_bf16 v[32:35], v[148:151], v[180:183], v[32:35]
	v_mfma_f32_16x16x32_bf16 v[60:63], v[144:147], v[160:163], v[60:63]
	v_mfma_f32_16x16x32_bf16 v[56:59], v[152:155], v[160:163], v[56:59]
	v_mfma_f32_16x16x32_bf16 v[52:55], v[144:147], v[168:171], v[52:55]
	v_mfma_f32_16x16x32_bf16 v[48:51], v[152:155], v[168:171], v[48:51]
	v_mfma_f32_16x16x32_bf16 v[44:47], v[144:147], v[176:179], v[44:47]
	v_mfma_f32_16x16x32_bf16 v[40:43], v[152:155], v[176:179], v[40:43]
	v_mfma_f32_16x16x32_bf16 v[36:39], v[144:147], v[184:187], v[36:39]
	v_mfma_f32_16x16x32_bf16 v[32:35], v[152:155], v[184:187], v[32:35]
	s_barrier
	s_add_i32 m0, s68, 0x14000
	s_add_u32 s98, s56, s46
	s_addc_u32 s99, s57, s47
	global_load_lds_dwordx4 v128, s[98:99]
	s_add_i32 m0, s68, 0x16000
	s_nop 0
	global_load_lds_dwordx4 v130, s[98:99]
	s_waitcnt vmcnt(6)
	s_barrier
	v_mfma_f32_16x16x32_bf16 v[28:31], v[188:191], v[156:159], v[28:31]
	v_mfma_f32_16x16x32_bf16 v[24:27], v[202:205], v[156:159], v[24:27]
	v_mfma_f32_16x16x32_bf16 v[20:23], v[188:191], v[164:167], v[20:23]
	v_mfma_f32_16x16x32_bf16 v[16:19], v[202:205], v[164:167], v[16:19]
	v_mfma_f32_16x16x32_bf16 v[12:15], v[188:191], v[172:175], v[12:15]
	v_mfma_f32_16x16x32_bf16 v[8:11], v[202:205], v[172:175], v[8:11]
	v_mfma_f32_16x16x32_bf16 v[4:7], v[188:191], v[180:183], v[4:7]
	v_mfma_f32_16x16x32_bf16 v[0:3], v[202:205], v[180:183], v[0:3]
	v_mfma_f32_16x16x32_bf16 v[28:31], v[192:195], v[160:163], v[28:31]
	v_mfma_f32_16x16x32_bf16 v[24:27], v[206:209], v[160:163], v[24:27]
	v_mfma_f32_16x16x32_bf16 v[20:23], v[192:195], v[168:171], v[20:23]
	v_mfma_f32_16x16x32_bf16 v[16:19], v[206:209], v[168:171], v[16:19]
	v_mfma_f32_16x16x32_bf16 v[12:15], v[192:195], v[176:179], v[12:15]
	v_mfma_f32_16x16x32_bf16 v[8:11], v[206:209], v[176:179], v[8:11]
	v_mfma_f32_16x16x32_bf16 v[4:7], v[192:195], v[184:187], v[4:7]
	v_mfma_f32_16x16x32_bf16 v[0:3], v[206:209], v[184:187], v[0:3]
	s_barrier
	ds_read_b128 v[140:143], v138
	ds_read_b128 v[144:147], v138 offset:1024
	ds_read_b128 v[148:151], v138 offset:2048
	ds_read_b128 v[152:155], v138 offset:3072
	ds_read_b128 v[156:159], v136 offset:32768
	ds_read_b128 v[160:163], v136 offset:33792
	ds_read_b128 v[164:167], v135 offset:32768
	ds_read_b128 v[168:171], v135 offset:33792
	ds_read_b128 v[172:175], v134 offset:32768
	ds_read_b128 v[176:179], v134 offset:33792
	ds_read_b128 v[180:183], v133 offset:32768
	ds_read_b128 v[184:187], v133 offset:33792
	s_add_i32 m0, s68, 0x4000
	s_add_u32 s98, s28, s46
	s_addc_u32 s99, s29, s47
	global_load_lds_dwordx4 v128, s[98:99]
	s_add_i32 m0, s68, 0x6000
	s_nop 0
	global_load_lds_dwordx4 v130, s[98:99]
	s_waitcnt lgkmcnt(8)
	s_barrier
	s_waitcnt lgkmcnt(0)
	s_waitcnt lgkmcnt(0)
	v_mfma_f32_16x16x32_bf16 v[124:127], v[140:143], v[156:159], v[124:127]
	v_mfma_f32_16x16x32_bf16 v[120:123], v[148:151], v[156:159], v[120:123]
	v_mfma_f32_16x16x32_bf16 v[116:119], v[140:143], v[164:167], v[116:119]
	v_mfma_f32_16x16x32_bf16 v[112:115], v[148:151], v[164:167], v[112:115]
	v_mfma_f32_16x16x32_bf16 v[108:111], v[140:143], v[172:175], v[108:111]
	v_mfma_f32_16x16x32_bf16 v[104:107], v[148:151], v[172:175], v[104:107]
	v_mfma_f32_16x16x32_bf16 v[100:103], v[140:143], v[180:183], v[100:103]
	v_mfma_f32_16x16x32_bf16 v[96:99], v[148:151], v[180:183], v[96:99]
	v_mfma_f32_16x16x32_bf16 v[124:127], v[144:147], v[160:163], v[124:127]
	v_mfma_f32_16x16x32_bf16 v[120:123], v[152:155], v[160:163], v[120:123]
	v_mfma_f32_16x16x32_bf16 v[116:119], v[144:147], v[168:171], v[116:119]
	v_mfma_f32_16x16x32_bf16 v[112:115], v[152:155], v[168:171], v[112:115]
	v_mfma_f32_16x16x32_bf16 v[108:111], v[144:147], v[176:179], v[108:111]
	v_mfma_f32_16x16x32_bf16 v[104:107], v[152:155], v[176:179], v[104:107]
	v_mfma_f32_16x16x32_bf16 v[100:103], v[144:147], v[184:187], v[100:103]
	v_mfma_f32_16x16x32_bf16 v[96:99], v[152:155], v[184:187], v[96:99]
	s_barrier
	ds_read_b128 v[188:191], v137
	ds_read_b128 v[192:195], v137 offset:1024
	ds_read_b128 v[202:205], v137 offset:2048
	ds_read_b128 v[206:209], v137 offset:3072
	s_mov_b32 m0, s69
	s_add_u32 s98, s56, s30
	s_addc_u32 s99, s57, s31
	global_load_lds_dwordx4 v128, s[98:99]
	s_mov_b32 m0, s70
	s_nop 0
	global_load_lds_dwordx4 v130, s[98:99]
	s_barrier
	s_waitcnt lgkmcnt(0)
	s_waitcnt lgkmcnt(0)
	v_mfma_f32_16x16x32_bf16 v[92:95], v[188:191], v[156:159], v[92:95]
	v_mfma_f32_16x16x32_bf16 v[88:91], v[202:205], v[156:159], v[88:91]
	v_mfma_f32_16x16x32_bf16 v[84:87], v[188:191], v[164:167], v[84:87]
	v_mfma_f32_16x16x32_bf16 v[80:83], v[202:205], v[164:167], v[80:83]
	v_mfma_f32_16x16x32_bf16 v[76:79], v[188:191], v[172:175], v[76:79]
	v_mfma_f32_16x16x32_bf16 v[72:75], v[202:205], v[172:175], v[72:75]
	v_mfma_f32_16x16x32_bf16 v[68:71], v[188:191], v[180:183], v[68:71]
	v_mfma_f32_16x16x32_bf16 v[64:67], v[202:205], v[180:183], v[64:67]
	v_mfma_f32_16x16x32_bf16 v[92:95], v[192:195], v[160:163], v[92:95]
	v_mfma_f32_16x16x32_bf16 v[88:91], v[206:209], v[160:163], v[88:91]
	v_mfma_f32_16x16x32_bf16 v[84:87], v[192:195], v[168:171], v[84:87]
	v_mfma_f32_16x16x32_bf16 v[80:83], v[206:209], v[168:171], v[80:83]
	v_mfma_f32_16x16x32_bf16 v[76:79], v[192:195], v[176:179], v[76:79]
	v_mfma_f32_16x16x32_bf16 v[72:75], v[206:209], v[176:179], v[72:75]
	v_mfma_f32_16x16x32_bf16 v[68:71], v[192:195], v[184:187], v[68:71]
	v_mfma_f32_16x16x32_bf16 v[64:67], v[206:209], v[184:187], v[64:67]
	v_mov_b32_e32 v210, v130
	s_barrier
	ds_read_b128 v[156:159], v136 offset:49152
	ds_read_b128 v[160:163], v136 offset:50176
	ds_read_b128 v[164:167], v135 offset:49152
	ds_read_b128 v[168:171], v135 offset:50176
	ds_read_b128 v[172:175], v134 offset:49152
	ds_read_b128 v[176:179], v134 offset:50176
	ds_read_b128 v[180:183], v133 offset:49152
	ds_read_b128 v[184:187], v133 offset:50176
	v_mov_b32_e32 v211, v197
	s_mov_b32 m0, s71
	s_add_u32 s98, s28, s30
	s_addc_u32 s99, s29, s31
	global_load_lds_dwordx4 v128, s[98:99]
	s_mov_b32 m0, s33
	s_nop 0
	global_load_lds_dwordx4 v130, s[98:99]
	s_barrier
	s_waitcnt lgkmcnt(0)
	s_waitcnt lgkmcnt(0)
	v_mfma_f32_16x16x32_bf16 v[60:63], v[140:143], v[156:159], v[60:63]
	v_mfma_f32_16x16x32_bf16 v[56:59], v[148:151], v[156:159], v[56:59]
	v_mfma_f32_16x16x32_bf16 v[52:55], v[140:143], v[164:167], v[52:55]
	v_mfma_f32_16x16x32_bf16 v[48:51], v[148:151], v[164:167], v[48:51]
	v_mfma_f32_16x16x32_bf16 v[44:47], v[140:143], v[172:175], v[44:47]
	v_mfma_f32_16x16x32_bf16 v[40:43], v[148:151], v[172:175], v[40:43]
	v_mfma_f32_16x16x32_bf16 v[36:39], v[140:143], v[180:183], v[36:39]
	v_mfma_f32_16x16x32_bf16 v[32:35], v[148:151], v[180:183], v[32:35]
	v_mfma_f32_16x16x32_bf16 v[60:63], v[144:147], v[160:163], v[60:63]
	v_mfma_f32_16x16x32_bf16 v[56:59], v[152:155], v[160:163], v[56:59]
	v_mfma_f32_16x16x32_bf16 v[52:55], v[144:147], v[168:171], v[52:55]
	v_mfma_f32_16x16x32_bf16 v[48:51], v[152:155], v[168:171], v[48:51]
	v_mfma_f32_16x16x32_bf16 v[44:47], v[144:147], v[176:179], v[44:47]
	v_mfma_f32_16x16x32_bf16 v[40:43], v[152:155], v[176:179], v[40:43]
	v_mfma_f32_16x16x32_bf16 v[36:39], v[144:147], v[184:187], v[36:39]
	v_mfma_f32_16x16x32_bf16 v[32:35], v[152:155], v[184:187], v[32:35]
	s_barrier
	v_mov_b32_e32 v196, v128
	s_mov_b32 m0, s72
	s_add_u32 s98, s56, s48
	s_addc_u32 s99, s57, s49
	global_load_lds_dwordx4 v128, s[98:99]
	s_mov_b32 m0, s36
	s_nop 0
	global_load_lds_dwordx4 v130, s[98:99]
	s_waitcnt vmcnt(6)
	s_barrier
	v_mfma_f32_16x16x32_bf16 v[28:31], v[188:191], v[156:159], v[28:31]
	v_mfma_f32_16x16x32_bf16 v[24:27], v[202:205], v[156:159], v[24:27]
	v_mfma_f32_16x16x32_bf16 v[20:23], v[188:191], v[164:167], v[20:23]
	v_mfma_f32_16x16x32_bf16 v[16:19], v[202:205], v[164:167], v[16:19]
	v_mfma_f32_16x16x32_bf16 v[12:15], v[188:191], v[172:175], v[12:15]
	v_mfma_f32_16x16x32_bf16 v[8:11], v[202:205], v[172:175], v[8:11]
	v_mfma_f32_16x16x32_bf16 v[4:7], v[188:191], v[180:183], v[4:7]
	v_mfma_f32_16x16x32_bf16 v[0:3], v[202:205], v[180:183], v[0:3]
	v_mfma_f32_16x16x32_bf16 v[28:31], v[192:195], v[160:163], v[28:31]
	v_mfma_f32_16x16x32_bf16 v[24:27], v[206:209], v[160:163], v[24:27]
	v_mfma_f32_16x16x32_bf16 v[20:23], v[192:195], v[168:171], v[20:23]
	v_mfma_f32_16x16x32_bf16 v[16:19], v[206:209], v[168:171], v[16:19]
	v_mfma_f32_16x16x32_bf16 v[12:15], v[192:195], v[176:179], v[12:15]
	v_mfma_f32_16x16x32_bf16 v[8:11], v[206:209], v[176:179], v[8:11]
	v_mfma_f32_16x16x32_bf16 v[4:7], v[192:195], v[184:187], v[4:7]
	v_mfma_f32_16x16x32_bf16 v[0:3], v[206:209], v[184:187], v[0:3]
	s_add_i32 s37, s37, 2
	s_add_u32 s10, s10, 0x100
	s_addc_u32 s11, s11, 0
	s_cmp_lt_u32 s37, 28
	s_barrier
	s_cbranch_scc1 .LBB0_568
	s_lshl_b64 s[4:5], s[4:5], 12
	s_add_u32 s4, s67, s4
	s_addc_u32 s5, s53, s5
	ds_read_b128 v[140:143], v129
	ds_read_b128 v[144:147], v129 offset:1024
	ds_read_b128 v[148:151], v129 offset:2048
	ds_read_b128 v[152:155], v129 offset:3072
	ds_read_b128 v[156:159], v136
	ds_read_b128 v[160:163], v136 offset:1024
	ds_read_b128 v[164:167], v135
	ds_read_b128 v[168:171], v135 offset:1024
	ds_read_b128 v[172:175], v134
	ds_read_b128 v[176:179], v134 offset:1024
	ds_read_b128 v[180:183], v133
	ds_read_b128 v[184:187], v133 offset:1024
	v_mov_b32_e32 v129, v197
	v_lshl_add_u64 v[128:129], s[4:5], 0, v[128:129]
	s_mov_b64 s[6:7], 0xf80
	s_mov_b32 m0, s39
	v_lshl_add_u64 v[128:129], v[128:129], 0, s[6:7]
	v_mov_b32_e32 v131, v197
	global_load_lds_dwordx4 v[128:129], off
	v_lshl_add_u64 v[128:129], s[4:5], 0, v[130:131]
	v_lshl_add_u64 v[128:129], v[128:129], 0, s[6:7]
	s_mov_b32 m0, s38
	s_nop 0
	global_load_lds_dwordx4 v[128:129], off
	s_barrier
	s_waitcnt lgkmcnt(0)
	s_waitcnt lgkmcnt(0)
	v_mfma_f32_16x16x32_bf16 v[124:127], v[140:143], v[156:159], v[124:127]
	v_mfma_f32_16x16x32_bf16 v[120:123], v[148:151], v[156:159], v[120:123]
	v_mfma_f32_16x16x32_bf16 v[116:119], v[140:143], v[164:167], v[116:119]
	v_mfma_f32_16x16x32_bf16 v[112:115], v[148:151], v[164:167], v[112:115]
	v_mfma_f32_16x16x32_bf16 v[100:103], v[140:143], v[180:183], v[100:103]
	v_mfma_f32_16x16x32_bf16 v[96:99], v[148:151], v[180:183], v[96:99]
	v_mfma_f32_16x16x32_bf16 v[124:127], v[144:147], v[160:163], v[124:127]
	v_mfma_f32_16x16x32_bf16 v[120:123], v[152:155], v[160:163], v[120:123]
	v_mfma_f32_16x16x32_bf16 v[116:119], v[144:147], v[168:171], v[116:119]
	v_mfma_f32_16x16x32_bf16 v[112:115], v[152:155], v[168:171], v[112:115]
	v_mfma_f32_16x16x32_bf16 v[108:111], v[140:143], v[172:175], v[108:111]
	v_mfma_f32_16x16x32_bf16 v[104:107], v[148:151], v[172:175], v[104:107]
	v_mfma_f32_16x16x32_bf16 v[100:103], v[144:147], v[184:187], v[100:103]
	v_mfma_f32_16x16x32_bf16 v[96:99], v[152:155], v[184:187], v[96:99]
	v_mfma_f32_16x16x32_bf16 v[128:131], v[144:147], v[176:179], v[108:111]
	v_mfma_f32_16x16x32_bf16 v[188:191], v[152:155], v[176:179], v[104:107]
	s_barrier
	s_nop 1
	ds_read_b128 v[104:107], v139
	ds_read_b128 v[108:111], v139 offset:1024
	ds_read_b128 v[192:195], v139 offset:2048
	ds_read_b128 v[202:205], v139 offset:3072
	s_barrier
	s_waitcnt lgkmcnt(0)
	s_waitcnt lgkmcnt(0)
	v_mfma_f32_16x16x32_bf16 v[84:87], v[104:107], v[164:167], v[84:87]
	v_mfma_f32_16x16x32_bf16 v[80:83], v[192:195], v[164:167], v[80:83]
	v_mfma_f32_16x16x32_bf16 v[68:71], v[104:107], v[180:183], v[68:71]
	v_mfma_f32_16x16x32_bf16 v[64:67], v[192:195], v[180:183], v[64:67]
	v_mfma_f32_16x16x32_bf16 v[92:95], v[104:107], v[156:159], v[92:95]
	v_mfma_f32_16x16x32_bf16 v[88:91], v[192:195], v[156:159], v[88:91]
	v_mfma_f32_16x16x32_bf16 v[84:87], v[108:111], v[168:171], v[84:87]
	v_mfma_f32_16x16x32_bf16 v[80:83], v[202:205], v[168:171], v[80:83]
	v_mfma_f32_16x16x32_bf16 v[76:79], v[104:107], v[172:175], v[76:79]
	v_mfma_f32_16x16x32_bf16 v[72:75], v[192:195], v[172:175], v[72:75]
	v_mfma_f32_16x16x32_bf16 v[68:71], v[108:111], v[184:187], v[68:71]
	v_mfma_f32_16x16x32_bf16 v[64:67], v[202:205], v[184:187], v[64:67]
	v_mfma_f32_16x16x32_bf16 v[206:209], v[108:111], v[160:163], v[92:95]
	v_mfma_f32_16x16x32_bf16 v[156:159], v[202:205], v[160:163], v[88:91]
	v_mfma_f32_16x16x32_bf16 v[160:163], v[108:111], v[176:179], v[76:79]
	v_mfma_f32_16x16x32_bf16 v[164:167], v[202:205], v[176:179], v[72:75]
	s_barrier
	s_nop 0
	ds_read_b128 v[72:75], v136 offset:16384
	ds_read_b128 v[76:79], v136 offset:17408
	ds_read_b128 v[88:91], v135 offset:16384
	ds_read_b128 v[92:95], v135 offset:17408
	ds_read_b128 v[168:171], v134 offset:16384
	ds_read_b128 v[172:175], v134 offset:17408
	ds_read_b128 v[176:179], v133 offset:16384
	ds_read_b128 v[180:183], v133 offset:17408
	s_waitcnt vmcnt(4)
	s_barrier
	s_waitcnt lgkmcnt(0)
	s_waitcnt lgkmcnt(0)
	v_mfma_f32_16x16x32_bf16 v[60:63], v[140:143], v[72:75], v[60:63]
	v_mfma_f32_16x16x32_bf16 v[56:59], v[148:151], v[72:75], v[56:59]
	v_mfma_f32_16x16x32_bf16 v[52:55], v[140:143], v[88:91], v[52:55]
	v_mfma_f32_16x16x32_bf16 v[48:51], v[148:151], v[88:91], v[48:51]
	v_mfma_f32_16x16x32_bf16 v[36:39], v[140:143], v[176:179], v[36:39]
	v_mfma_f32_16x16x32_bf16 v[32:35], v[148:151], v[176:179], v[32:35]
	v_mfma_f32_16x16x32_bf16 v[60:63], v[144:147], v[76:79], v[60:63]
	v_mfma_f32_16x16x32_bf16 v[56:59], v[152:155], v[76:79], v[56:59]
	v_mfma_f32_16x16x32_bf16 v[52:55], v[144:147], v[92:95], v[52:55]
	v_mfma_f32_16x16x32_bf16 v[48:51], v[152:155], v[92:95], v[48:51]
	v_mfma_f32_16x16x32_bf16 v[44:47], v[140:143], v[168:171], v[44:47]
	v_mfma_f32_16x16x32_bf16 v[40:43], v[148:151], v[168:171], v[40:43]
	v_mfma_f32_16x16x32_bf16 v[36:39], v[144:147], v[180:183], v[36:39]
	v_mfma_f32_16x16x32_bf16 v[32:35], v[152:155], v[180:183], v[32:35]
	v_mfma_f32_16x16x32_bf16 v[184:187], v[144:147], v[172:175], v[44:47]
	v_mfma_f32_16x16x32_bf16 v[210:213], v[152:155], v[172:175], v[40:43]
	v_mfma_f32_16x16x32_bf16 v[20:23], v[104:107], v[88:91], v[20:23]
	v_mfma_f32_16x16x32_bf16 v[16:19], v[192:195], v[88:91], v[16:19]
	v_mfma_f32_16x16x32_bf16 v[4:7], v[104:107], v[176:179], v[4:7]
	v_mfma_f32_16x16x32_bf16 v[0:3], v[192:195], v[176:179], v[0:3]
	v_mfma_f32_16x16x32_bf16 v[28:31], v[104:107], v[72:75], v[28:31]
	v_mfma_f32_16x16x32_bf16 v[24:27], v[192:195], v[72:75], v[24:27]
	v_mfma_f32_16x16x32_bf16 v[20:23], v[108:111], v[92:95], v[20:23]
	v_mfma_f32_16x16x32_bf16 v[16:19], v[202:205], v[92:95], v[16:19]
	v_mfma_f32_16x16x32_bf16 v[12:15], v[104:107], v[168:171], v[12:15]
	v_mfma_f32_16x16x32_bf16 v[8:11], v[192:195], v[168:171], v[8:11]
	v_mfma_f32_16x16x32_bf16 v[4:7], v[108:111], v[180:183], v[4:7]
	v_mfma_f32_16x16x32_bf16 v[0:3], v[202:205], v[180:183], v[0:3]
	v_mfma_f32_16x16x32_bf16 v[140:143], v[108:111], v[76:79], v[28:31]
	v_mfma_f32_16x16x32_bf16 v[144:147], v[202:205], v[76:79], v[24:27]
	v_mfma_f32_16x16x32_bf16 v[148:151], v[108:111], v[172:175], v[12:15]
	v_mfma_f32_16x16x32_bf16 v[152:155], v[202:205], v[172:175], v[8:11]
	s_barrier
	s_nop 0
	ds_read_b128 v[8:11], v138
	ds_read_b128 v[12:15], v138 offset:1024
	ds_read_b128 v[168:171], v138 offset:2048
	ds_read_b128 v[172:175], v138 offset:3072
	ds_read_b128 v[24:27], v136 offset:32768
	ds_read_b128 v[28:31], v136 offset:33792
	ds_read_b128 v[40:43], v135 offset:32768
	ds_read_b128 v[44:47], v135 offset:33792
	ds_read_b128 v[176:179], v134 offset:32768
	ds_read_b128 v[180:183], v134 offset:33792
	ds_read_b128 v[192:195], v133 offset:32768
	ds_read_b128 v[202:205], v133 offset:33792
	s_waitcnt vmcnt(2)
	s_barrier
	s_waitcnt lgkmcnt(0)
	s_waitcnt lgkmcnt(0)
	v_mfma_f32_16x16x32_bf16 v[72:75], v[8:11], v[24:27], v[124:127]
	v_mfma_f32_16x16x32_bf16 v[124:127], v[12:15], v[28:31], v[72:75]
	v_mfma_f32_16x16x32_bf16 v[72:75], v[168:171], v[24:27], v[120:123]
	v_mfma_f32_16x16x32_bf16 v[120:123], v[172:175], v[28:31], v[72:75]
	v_mfma_f32_16x16x32_bf16 v[72:75], v[8:11], v[40:43], v[116:119]
	v_mfma_f32_16x16x32_bf16 v[108:111], v[12:15], v[44:47], v[72:75]
	v_mfma_f32_16x16x32_bf16 v[72:75], v[168:171], v[40:43], v[112:115]
	v_mfma_f32_16x16x32_bf16 v[104:107], v[172:175], v[44:47], v[72:75]
	v_mfma_f32_16x16x32_bf16 v[72:75], v[8:11], v[176:179], v[128:131]
	v_mfma_f32_16x16x32_bf16 v[92:95], v[12:15], v[180:183], v[72:75]
	v_mfma_f32_16x16x32_bf16 v[72:75], v[168:171], v[176:179], v[188:191]
	v_mfma_f32_16x16x32_bf16 v[88:91], v[172:175], v[180:183], v[72:75]
	v_mfma_f32_16x16x32_bf16 v[72:75], v[8:11], v[192:195], v[100:103]
	v_mfma_f32_16x16x32_bf16 v[76:79], v[12:15], v[202:205], v[72:75]
	v_mfma_f32_16x16x32_bf16 v[72:75], v[168:171], v[192:195], v[96:99]
	v_mfma_f32_16x16x32_bf16 v[72:75], v[172:175], v[202:205], v[72:75]
	s_barrier
	ds_read_b128 v[128:131], v137
	ds_read_b128 v[188:191], v137 offset:1024
	ds_read_b128 v[214:217], v137 offset:2048
	ds_read_b128 v[218:221], v137 offset:3072
	s_waitcnt vmcnt(0)
	s_barrier
	s_waitcnt lgkmcnt(0)
	s_waitcnt lgkmcnt(0)
	v_mfma_f32_16x16x32_bf16 v[96:99], v[128:131], v[24:27], v[206:209]
	v_mfma_f32_16x16x32_bf16 v[24:27], v[214:217], v[24:27], v[156:159]
	v_mfma_f32_16x16x32_bf16 v[112:115], v[218:221], v[28:31], v[24:27]
	v_mfma_f32_16x16x32_bf16 v[24:27], v[128:131], v[40:43], v[84:87]
	v_mfma_f32_16x16x32_bf16 v[100:103], v[188:191], v[44:47], v[24:27]
	v_mfma_f32_16x16x32_bf16 v[24:27], v[214:217], v[40:43], v[80:83]
	v_mfma_f32_16x16x32_bf16 v[116:119], v[188:191], v[28:31], v[96:99]
	v_mfma_f32_16x16x32_bf16 v[96:99], v[218:221], v[44:47], v[24:27]
	v_mfma_f32_16x16x32_bf16 v[24:27], v[128:131], v[176:179], v[160:163]
	v_mfma_f32_16x16x32_bf16 v[84:87], v[188:191], v[180:183], v[24:27]
	v_mfma_f32_16x16x32_bf16 v[24:27], v[214:217], v[176:179], v[164:167]
	v_mfma_f32_16x16x32_bf16 v[80:83], v[218:221], v[180:183], v[24:27]
	v_mfma_f32_16x16x32_bf16 v[24:27], v[128:131], v[192:195], v[68:71]
	v_mfma_f32_16x16x32_bf16 v[68:71], v[188:191], v[202:205], v[24:27]
	v_mfma_f32_16x16x32_bf16 v[24:27], v[214:217], v[192:195], v[64:67]
	v_mfma_f32_16x16x32_bf16 v[64:67], v[218:221], v[202:205], v[24:27]
	s_barrier
	ds_read_b128 v[156:159], v136 offset:49152
	ds_read_b128 v[136:139], v136 offset:50176
	ds_read_b128 v[160:163], v135 offset:49152
	ds_read_b128 v[164:167], v135 offset:50176
	ds_read_b128 v[176:179], v134 offset:49152
	ds_read_b128 v[180:183], v134 offset:50176
	ds_read_b128 v[192:195], v133 offset:49152
	ds_read_b128 v[202:205], v133 offset:50176
	s_barrier
	s_waitcnt lgkmcnt(0)
	s_waitcnt lgkmcnt(0)
	v_mfma_f32_16x16x32_bf16 v[24:27], v[8:11], v[156:159], v[60:63]
	v_mfma_f32_16x16x32_bf16 v[60:63], v[12:15], v[136:139], v[24:27]
	v_mfma_f32_16x16x32_bf16 v[24:27], v[168:171], v[156:159], v[56:59]
	v_mfma_f32_16x16x32_bf16 v[56:59], v[172:175], v[136:139], v[24:27]
	v_mfma_f32_16x16x32_bf16 v[24:27], v[8:11], v[160:163], v[52:55]
	v_mfma_f32_16x16x32_bf16 v[44:47], v[12:15], v[164:167], v[24:27]
	v_mfma_f32_16x16x32_bf16 v[24:27], v[168:171], v[160:163], v[48:51]
	v_mfma_f32_16x16x32_bf16 v[40:43], v[172:175], v[164:167], v[24:27]
	v_mfma_f32_16x16x32_bf16 v[24:27], v[8:11], v[176:179], v[184:187]
	v_mfma_f32_16x16x32_bf16 v[8:11], v[8:11], v[192:195], v[36:39]
	v_mfma_f32_16x16x32_bf16 v[28:31], v[12:15], v[180:183], v[24:27]
	v_mfma_f32_16x16x32_bf16 v[24:27], v[168:171], v[176:179], v[210:213]
	v_mfma_f32_16x16x32_bf16 v[12:15], v[12:15], v[202:205], v[8:11]
	v_mfma_f32_16x16x32_bf16 v[8:11], v[168:171], v[192:195], v[32:35]
	v_mfma_f32_16x16x32_bf16 v[24:27], v[172:175], v[180:183], v[24:27]
	v_mfma_f32_16x16x32_bf16 v[8:11], v[172:175], v[202:205], v[8:11]
	v_mfma_f32_16x16x32_bf16 v[32:35], v[128:131], v[156:159], v[140:143]
	v_mfma_f32_16x16x32_bf16 v[52:55], v[188:191], v[136:139], v[32:35]
	v_mfma_f32_16x16x32_bf16 v[32:35], v[214:217], v[156:159], v[144:147]
	v_mfma_f32_16x16x32_bf16 v[16:19], v[214:217], v[160:163], v[16:19]
	v_mfma_f32_16x16x32_bf16 v[48:51], v[218:221], v[136:139], v[32:35]
	v_mfma_f32_16x16x32_bf16 v[20:23], v[128:131], v[160:163], v[20:23]
	v_mfma_f32_16x16x32_bf16 v[32:35], v[218:221], v[164:167], v[16:19]
	v_mfma_f32_16x16x32_bf16 v[16:19], v[128:131], v[176:179], v[148:151]
	v_mfma_f32_16x16x32_bf16 v[36:39], v[188:191], v[164:167], v[20:23]
	v_mfma_f32_16x16x32_bf16 v[20:23], v[188:191], v[180:183], v[16:19]
	v_mfma_f32_16x16x32_bf16 v[16:19], v[214:217], v[176:179], v[152:155]
	v_mfma_f32_16x16x32_bf16 v[4:7], v[128:131], v[192:195], v[4:7]
	v_mfma_f32_16x16x32_bf16 v[0:3], v[214:217], v[192:195], v[0:3]
	v_mfma_f32_16x16x32_bf16 v[16:19], v[218:221], v[180:183], v[16:19]
	v_mfma_f32_16x16x32_bf16 v[4:7], v[188:191], v[202:205], v[4:7]
	v_mfma_f32_16x16x32_bf16 v[0:3], v[218:221], v[202:205], v[0:3]
	s_movk_i32 s4, 0x100
	v_cmp_gt_u32_e32 vcc, s4, v132
	s_barrier
	s_and_saveexec_b64 s[4:5], vcc
	s_cbranch_execz .LBB0_571
	s_barrier
